# s_setprio 1 issued before the opening barrier of each MFMA block
# baseline (speedup 1.0000x reference)
.LBB0_92:
	s_add_u32 s8, s6, 0xfffc0080
	s_addc_u32 s9, s7, -1
	s_add_i32 s35, 0, 0x10000
	s_cmp_eq_u32 s59, 12
	s_cselect_b32 s11, s5, s9
	s_cselect_b32 s10, s24, s8
	v_add_u32_e32 v140, s35, v165
	s_cselect_b32 s9, s47, s58
	s_cselect_b32 s8, s51, s53
	s_add_i32 s74, 0, 0x14000
	ds_read_b128 v[142:145], v140
	ds_read_b128 v[146:149], v140 offset:1024
	ds_read_b128 v[150:153], v140 offset:2048
	ds_read_b128 v[154:157], v140 offset:3072
	v_add_u32_e32 v140, s74, v165
	ds_read_b128 v[158:161], v140
	ds_read_b128 v[168:171], v140 offset:1024
	ds_read_b128 v[172:175], v140 offset:2048
	ds_read_b128 v[176:179], v140 offset:3072
	v_lshl_add_u64 v[162:163], s[6:7], 0, v[136:137]
	s_add_i32 m0, s27, 0xc000
	ds_read_b128 v[180:183], v166
	ds_read_b128 v[184:187], v166 offset:1024
	ds_read_b128 v[188:191], v166 offset:2048
	ds_read_b128 v[192:195], v166 offset:3072
	ds_read_b128 v[200:203], v166 offset:4096
	ds_read_b128 v[206:209], v166 offset:5120
	ds_read_b128 v[210:213], v166 offset:6144
	ds_read_b128 v[214:217], v166 offset:7168
	global_load_lds_dwordx4 v[162:163], off
	v_lshl_add_u64 v[162:163], s[6:7], 0, v[138:139]
	s_add_i32 m0, s27, 0xe000
	s_nop 0
	global_load_lds_dwordx4 v[162:163], off
	s_waitcnt vmcnt(8)
	s_waitcnt lgkmcnt(0)
	s_setprio 1
	s_barrier
	v_mfma_f32_16x16x32_bf16 v[124:127], v[142:145], v[180:183], v[124:127]
	v_mfma_f32_16x16x32_bf16 v[120:123], v[150:153], v[180:183], v[120:123]
	v_mfma_f32_16x16x32_bf16 v[108:111], v[142:145], v[188:191], v[108:111]
	v_mfma_f32_16x16x32_bf16 v[104:107], v[150:153], v[188:191], v[104:107]
	v_mfma_f32_16x16x32_bf16 v[92:95], v[142:145], v[200:203], v[92:95]
	v_mfma_f32_16x16x32_bf16 v[88:91], v[150:153], v[200:203], v[88:91]
	v_mfma_f32_16x16x32_bf16 v[76:79], v[142:145], v[210:213], v[76:79]
	v_mfma_f32_16x16x32_bf16 v[72:75], v[150:153], v[210:213], v[72:75]
	v_mfma_f32_16x16x32_bf16 v[124:127], v[146:149], v[184:187], v[124:127]
	v_mfma_f32_16x16x32_bf16 v[120:123], v[154:157], v[184:187], v[120:123]
	v_mfma_f32_16x16x32_bf16 v[108:111], v[146:149], v[192:195], v[108:111]
	v_mfma_f32_16x16x32_bf16 v[104:107], v[154:157], v[192:195], v[104:107]
	v_mfma_f32_16x16x32_bf16 v[92:95], v[146:149], v[206:209], v[92:95]
	v_mfma_f32_16x16x32_bf16 v[88:91], v[154:157], v[206:209], v[88:91]
	v_mfma_f32_16x16x32_bf16 v[76:79], v[146:149], v[214:217], v[76:79]
	v_mfma_f32_16x16x32_bf16 v[72:75], v[154:157], v[214:217], v[72:75]
	v_mfma_f32_16x16x32_bf16 v[116:119], v[158:161], v[180:183], v[116:119]
	v_mfma_f32_16x16x32_bf16 v[112:115], v[172:175], v[180:183], v[112:115]
	v_mfma_f32_16x16x32_bf16 v[100:103], v[158:161], v[188:191], v[100:103]
	v_mfma_f32_16x16x32_bf16 v[96:99], v[172:175], v[188:191], v[96:99]
	v_mfma_f32_16x16x32_bf16 v[84:87], v[158:161], v[200:203], v[84:87]
	v_mfma_f32_16x16x32_bf16 v[80:83], v[172:175], v[200:203], v[80:83]
	v_mfma_f32_16x16x32_bf16 v[68:71], v[158:161], v[210:213], v[68:71]
	v_mfma_f32_16x16x32_bf16 v[64:67], v[172:175], v[210:213], v[64:67]
	v_mfma_f32_16x16x32_bf16 v[116:119], v[168:171], v[184:187], v[116:119]
	v_mfma_f32_16x16x32_bf16 v[112:115], v[176:179], v[184:187], v[112:115]
	v_mfma_f32_16x16x32_bf16 v[100:103], v[168:171], v[192:195], v[100:103]
	v_mfma_f32_16x16x32_bf16 v[96:99], v[176:179], v[192:195], v[96:99]
	v_mfma_f32_16x16x32_bf16 v[84:87], v[168:171], v[206:209], v[84:87]
	v_mfma_f32_16x16x32_bf16 v[80:83], v[176:179], v[206:209], v[80:83]
	v_mfma_f32_16x16x32_bf16 v[68:71], v[168:171], v[214:217], v[68:71]
	v_mfma_f32_16x16x32_bf16 v[64:67], v[176:179], v[214:217], v[64:67]
	s_barrier
	s_setprio 0
	s_add_i32 s35, s35, s13
	v_lshl_add_u64 v[162:163], s[8:9], 0, v[132:133]
	s_mov_b32 m0, s35
	ds_read_b128 v[180:183], v166 offset:16384
	ds_read_b128 v[184:187], v166 offset:17408
	ds_read_b128 v[188:191], v166 offset:18432
	ds_read_b128 v[192:195], v166 offset:19456
	ds_read_b128 v[200:203], v166 offset:20480
	ds_read_b128 v[206:209], v166 offset:21504
	ds_read_b128 v[210:213], v166 offset:22528
	ds_read_b128 v[214:217], v166 offset:23552
	global_load_lds_dwordx4 v[162:163], off
	s_add_i32 m0, s35, 0x2000
	s_add_u32 s60, s8, 0x40000
	v_lshl_add_u64 v[196:197], s[8:9], 0, v[128:129]
	s_addc_u32 s61, s9, 0
	s_add_i32 s35, s74, s13
	global_load_lds_dwordx4 v[196:197], off
	v_lshl_add_u64 v[198:199], s[60:61], 0, v[132:133]
	s_mov_b32 m0, s35
	v_lshl_add_u64 v[204:205], s[10:11], 0, v[130:131]
	global_load_lds_dwordx4 v[198:199], off
	v_lshl_add_u64 v[198:199], s[60:61], 0, v[128:129]
	s_add_i32 m0, s35, 0x2000
	s_nop 0
	global_load_lds_dwordx4 v[198:199], off
	v_lshl_add_u64 v[198:199], s[10:11], 0, v[134:135]
	s_mov_b32 m0, s27
	s_nop 0
	global_load_lds_dwordx4 v[198:199], off
	s_mov_b32 m0, s28
	s_nop 0
	global_load_lds_dwordx4 v[204:205], off
	s_waitcnt vmcnt(8)
	s_waitcnt lgkmcnt(0)
	s_setprio 1
	s_barrier
	v_mfma_f32_16x16x32_bf16 v[60:63], v[142:145], v[180:183], v[60:63]
	v_mfma_f32_16x16x32_bf16 v[56:59], v[150:153], v[180:183], v[56:59]
	v_mfma_f32_16x16x32_bf16 v[44:47], v[142:145], v[188:191], v[44:47]
	v_mfma_f32_16x16x32_bf16 v[40:43], v[150:153], v[188:191], v[40:43]
	v_mfma_f32_16x16x32_bf16 v[28:31], v[142:145], v[200:203], v[28:31]
	v_mfma_f32_16x16x32_bf16 v[24:27], v[150:153], v[200:203], v[24:27]
	v_mfma_f32_16x16x32_bf16 v[12:15], v[142:145], v[210:213], v[12:15]
	v_mfma_f32_16x16x32_bf16 v[8:11], v[150:153], v[210:213], v[8:11]
	v_mfma_f32_16x16x32_bf16 v[60:63], v[146:149], v[184:187], v[60:63]
	v_mfma_f32_16x16x32_bf16 v[56:59], v[154:157], v[184:187], v[56:59]
	v_mfma_f32_16x16x32_bf16 v[44:47], v[146:149], v[192:195], v[44:47]
	v_mfma_f32_16x16x32_bf16 v[40:43], v[154:157], v[192:195], v[40:43]
	v_mfma_f32_16x16x32_bf16 v[28:31], v[146:149], v[206:209], v[28:31]
	v_mfma_f32_16x16x32_bf16 v[24:27], v[154:157], v[206:209], v[24:27]
	v_mfma_f32_16x16x32_bf16 v[12:15], v[146:149], v[214:217], v[12:15]
	v_mfma_f32_16x16x32_bf16 v[8:11], v[154:157], v[214:217], v[8:11]
	v_mfma_f32_16x16x32_bf16 v[52:55], v[158:161], v[180:183], v[52:55]
	v_mfma_f32_16x16x32_bf16 v[48:51], v[172:175], v[180:183], v[48:51]
	v_mfma_f32_16x16x32_bf16 v[36:39], v[158:161], v[188:191], v[36:39]
	v_mfma_f32_16x16x32_bf16 v[32:35], v[172:175], v[188:191], v[32:35]
	v_mfma_f32_16x16x32_bf16 v[20:23], v[158:161], v[200:203], v[20:23]
	v_mfma_f32_16x16x32_bf16 v[16:19], v[172:175], v[200:203], v[16:19]
	v_mfma_f32_16x16x32_bf16 v[4:7], v[158:161], v[210:213], v[4:7]
	v_mfma_f32_16x16x32_bf16 v[0:3], v[172:175], v[210:213], v[0:3]
	v_mfma_f32_16x16x32_bf16 v[52:55], v[168:171], v[184:187], v[52:55]
	v_mfma_f32_16x16x32_bf16 v[48:51], v[176:179], v[184:187], v[48:51]
	v_mfma_f32_16x16x32_bf16 v[36:39], v[168:171], v[192:195], v[36:39]
	v_mfma_f32_16x16x32_bf16 v[32:35], v[176:179], v[192:195], v[32:35]
	v_mfma_f32_16x16x32_bf16 v[20:23], v[168:171], v[206:209], v[20:23]
	v_mfma_f32_16x16x32_bf16 v[16:19], v[176:179], v[206:209], v[16:19]
	v_mfma_f32_16x16x32_bf16 v[4:7], v[168:171], v[214:217], v[4:7]
	v_mfma_f32_16x16x32_bf16 v[0:3], v[176:179], v[214:217], v[0:3]
	s_barrier
	s_setprio 0
	s_add_i32 s35, 0, 0x18000
	v_add_u32_e32 v140, s35, v165
	s_add_i32 s60, 0, 0x1c000
	ds_read_b128 v[142:145], v140
	ds_read_b128 v[146:149], v140 offset:1024
	ds_read_b128 v[150:153], v140 offset:2048
	ds_read_b128 v[154:157], v140 offset:3072
	v_add_u32_e32 v140, s60, v165
	ds_read_b128 v[158:161], v140
	ds_read_b128 v[168:171], v140 offset:1024
	ds_read_b128 v[172:175], v140 offset:2048
	ds_read_b128 v[176:179], v140 offset:3072
	s_add_u32 s10, s10, 0x40000
	s_addc_u32 s11, s11, 0
	s_mov_b32 m0, s29
	v_lshl_add_u64 v[218:219], s[10:11], 0, v[134:135]
	ds_read_b128 v[180:183], v166 offset:32768
	ds_read_b128 v[184:187], v166 offset:33792
	ds_read_b128 v[188:191], v166 offset:34816
	ds_read_b128 v[192:195], v166 offset:35840
	ds_read_b128 v[200:203], v166 offset:36864
	ds_read_b128 v[206:209], v166 offset:37888
	ds_read_b128 v[210:213], v166 offset:38912
	ds_read_b128 v[214:217], v166 offset:39936
	global_load_lds_dwordx4 v[218:219], off
	v_lshl_add_u64 v[218:219], s[10:11], 0, v[130:131]
	s_mov_b32 m0, s38
	s_nop 0
	global_load_lds_dwordx4 v[218:219], off
	s_waitcnt vmcnt(8)
	s_waitcnt lgkmcnt(0)
	s_setprio 1
	s_barrier
	v_mfma_f32_16x16x32_bf16 v[124:127], v[142:145], v[180:183], v[124:127]
	v_mfma_f32_16x16x32_bf16 v[120:123], v[150:153], v[180:183], v[120:123]
	v_mfma_f32_16x16x32_bf16 v[108:111], v[142:145], v[188:191], v[108:111]
	v_mfma_f32_16x16x32_bf16 v[104:107], v[150:153], v[188:191], v[104:107]
	v_mfma_f32_16x16x32_bf16 v[92:95], v[142:145], v[200:203], v[92:95]
	v_mfma_f32_16x16x32_bf16 v[88:91], v[150:153], v[200:203], v[88:91]
	v_mfma_f32_16x16x32_bf16 v[76:79], v[142:145], v[210:213], v[76:79]
	v_mfma_f32_16x16x32_bf16 v[72:75], v[150:153], v[210:213], v[72:75]
	v_mfma_f32_16x16x32_bf16 v[124:127], v[146:149], v[184:187], v[124:127]
	v_mfma_f32_16x16x32_bf16 v[120:123], v[154:157], v[184:187], v[120:123]
	v_mfma_f32_16x16x32_bf16 v[108:111], v[146:149], v[192:195], v[108:111]
	v_mfma_f32_16x16x32_bf16 v[104:107], v[154:157], v[192:195], v[104:107]
	v_mfma_f32_16x16x32_bf16 v[92:95], v[146:149], v[206:209], v[92:95]
	v_mfma_f32_16x16x32_bf16 v[88:91], v[154:157], v[206:209], v[88:91]
	v_mfma_f32_16x16x32_bf16 v[76:79], v[146:149], v[214:217], v[76:79]
	v_mfma_f32_16x16x32_bf16 v[72:75], v[154:157], v[214:217], v[72:75]
	v_mfma_f32_16x16x32_bf16 v[116:119], v[158:161], v[180:183], v[116:119]
	v_mfma_f32_16x16x32_bf16 v[112:115], v[172:175], v[180:183], v[112:115]
	v_mfma_f32_16x16x32_bf16 v[100:103], v[158:161], v[188:191], v[100:103]
	v_mfma_f32_16x16x32_bf16 v[96:99], v[172:175], v[188:191], v[96:99]
	v_mfma_f32_16x16x32_bf16 v[84:87], v[158:161], v[200:203], v[84:87]
	v_mfma_f32_16x16x32_bf16 v[80:83], v[172:175], v[200:203], v[80:83]
	v_mfma_f32_16x16x32_bf16 v[68:71], v[158:161], v[210:213], v[68:71]
	v_mfma_f32_16x16x32_bf16 v[64:67], v[172:175], v[210:213], v[64:67]
	v_mfma_f32_16x16x32_bf16 v[116:119], v[168:171], v[184:187], v[116:119]
	v_mfma_f32_16x16x32_bf16 v[112:115], v[176:179], v[184:187], v[112:115]
	v_mfma_f32_16x16x32_bf16 v[100:103], v[168:171], v[192:195], v[100:103]
	v_mfma_f32_16x16x32_bf16 v[96:99], v[176:179], v[192:195], v[96:99]
	v_mfma_f32_16x16x32_bf16 v[84:87], v[168:171], v[206:209], v[84:87]
	v_mfma_f32_16x16x32_bf16 v[80:83], v[176:179], v[206:209], v[80:83]
	v_mfma_f32_16x16x32_bf16 v[68:71], v[168:171], v[214:217], v[68:71]
	v_mfma_f32_16x16x32_bf16 v[64:67], v[176:179], v[214:217], v[64:67]
	s_barrier
	s_setprio 0
	s_add_i32 s10, s35, s13
	v_lshl_add_u64 v[162:163], v[162:163], 0, s[36:37]
	s_mov_b32 m0, s10
	ds_read_b128 v[180:183], v166 offset:49152
	ds_read_b128 v[184:187], v166 offset:50176
	ds_read_b128 v[188:191], v166 offset:51200
	ds_read_b128 v[192:195], v166 offset:52224
	ds_read_b128 v[200:203], v166 offset:53248
	ds_read_b128 v[206:209], v166 offset:54272
	ds_read_b128 v[210:213], v166 offset:55296
	ds_read_b128 v[214:217], v166 offset:56320
	global_load_lds_dwordx4 v[162:163], off
	s_add_i32 m0, s10, 0x2000
	s_add_u32 s8, s8, 0x40080
	v_lshl_add_u64 v[162:163], v[196:197], 0, s[36:37]
	s_addc_u32 s9, s9, 0
	s_add_i32 s10, s60, s13
	global_load_lds_dwordx4 v[162:163], off
	v_lshl_add_u64 v[162:163], s[8:9], 0, v[132:133]
	s_mov_b32 m0, s10
	s_nop 0
	global_load_lds_dwordx4 v[162:163], off
	v_lshl_add_u64 v[162:163], s[8:9], 0, v[128:129]
	s_add_i32 m0, s10, 0x2000
	s_nop 0
	global_load_lds_dwordx4 v[162:163], off
	v_lshl_add_u64 v[162:163], v[198:199], 0, s[36:37]
	s_mov_b32 m0, s42
	s_nop 0
	global_load_lds_dwordx4 v[162:163], off
	v_lshl_add_u64 v[162:163], v[204:205], 0, s[36:37]
	s_mov_b32 m0, s43
	s_nop 0
	global_load_lds_dwordx4 v[162:163], off
	s_waitcnt vmcnt(8)
	s_waitcnt lgkmcnt(0)
	s_setprio 1
	s_barrier
	v_mfma_f32_16x16x32_bf16 v[60:63], v[142:145], v[180:183], v[60:63]
	v_mfma_f32_16x16x32_bf16 v[56:59], v[150:153], v[180:183], v[56:59]
	v_mfma_f32_16x16x32_bf16 v[44:47], v[142:145], v[188:191], v[44:47]
	v_mfma_f32_16x16x32_bf16 v[40:43], v[150:153], v[188:191], v[40:43]
	v_mfma_f32_16x16x32_bf16 v[28:31], v[142:145], v[200:203], v[28:31]
	v_mfma_f32_16x16x32_bf16 v[24:27], v[150:153], v[200:203], v[24:27]
	v_mfma_f32_16x16x32_bf16 v[12:15], v[142:145], v[210:213], v[12:15]
	v_mfma_f32_16x16x32_bf16 v[8:11], v[150:153], v[210:213], v[8:11]
	v_mfma_f32_16x16x32_bf16 v[60:63], v[146:149], v[184:187], v[60:63]
	v_mfma_f32_16x16x32_bf16 v[56:59], v[154:157], v[184:187], v[56:59]
	v_mfma_f32_16x16x32_bf16 v[44:47], v[146:149], v[192:195], v[44:47]
	v_mfma_f32_16x16x32_bf16 v[40:43], v[154:157], v[192:195], v[40:43]
	v_mfma_f32_16x16x32_bf16 v[28:31], v[146:149], v[206:209], v[28:31]
	v_mfma_f32_16x16x32_bf16 v[24:27], v[154:157], v[206:209], v[24:27]
	v_mfma_f32_16x16x32_bf16 v[12:15], v[146:149], v[214:217], v[12:15]
	v_mfma_f32_16x16x32_bf16 v[8:11], v[154:157], v[214:217], v[8:11]
	v_mfma_f32_16x16x32_bf16 v[52:55], v[158:161], v[180:183], v[52:55]
	v_mfma_f32_16x16x32_bf16 v[48:51], v[172:175], v[180:183], v[48:51]
	v_mfma_f32_16x16x32_bf16 v[36:39], v[158:161], v[188:191], v[36:39]
	v_mfma_f32_16x16x32_bf16 v[32:35], v[172:175], v[188:191], v[32:35]
	v_mfma_f32_16x16x32_bf16 v[20:23], v[158:161], v[200:203], v[20:23]
	v_mfma_f32_16x16x32_bf16 v[16:19], v[172:175], v[200:203], v[16:19]
	v_mfma_f32_16x16x32_bf16 v[4:7], v[158:161], v[210:213], v[4:7]
	v_mfma_f32_16x16x32_bf16 v[0:3], v[172:175], v[210:213], v[0:3]
	v_mfma_f32_16x16x32_bf16 v[52:55], v[168:171], v[184:187], v[52:55]
	v_mfma_f32_16x16x32_bf16 v[48:51], v[176:179], v[184:187], v[48:51]
	v_mfma_f32_16x16x32_bf16 v[36:39], v[168:171], v[192:195], v[36:39]
	v_mfma_f32_16x16x32_bf16 v[32:35], v[176:179], v[192:195], v[32:35]
	v_mfma_f32_16x16x32_bf16 v[20:23], v[168:171], v[206:209], v[20:23]
	v_mfma_f32_16x16x32_bf16 v[16:19], v[176:179], v[206:209], v[16:19]
	v_mfma_f32_16x16x32_bf16 v[4:7], v[168:171], v[214:217], v[4:7]
	v_mfma_f32_16x16x32_bf16 v[0:3], v[176:179], v[214:217], v[0:3]
	s_barrier
	s_setprio 0
	s_add_i32 s59, s59, 2
	s_add_u32 s6, s6, 0x100
	s_addc_u32 s7, s7, 0
	s_add_u32 s53, s53, 0x100
	s_addc_u32 s58, s58, 0
	s_cmp_gt_u32 s59, 13
	s_cbranch_scc0 .LBB0_92
	s_and_b64 vcc, exec, s[48:49]
	s_cbranch_vccz .LBB0_95
	s_barrier

.LBB0_147:
	s_add_u32 s8, s6, 0xfffc0080
	s_addc_u32 s9, s7, -1
	s_add_i32 s35, 0, 0x10000
	s_cmp_eq_u32 s74, 12
	s_cselect_b32 s11, s24, s9
	s_cselect_b32 s10, s38, s8
	s_cselect_b32 s9, s53, s61
	s_cselect_b32 s8, s55, s60
	s_add_i32 s75, 0, 0x14000
	v_add_u32_e32 v142, s35, v178
	v_add_u32_e32 v168, s75, v178
	ds_read_b128 v[128:131], v142
	ds_read_b128 v[132:135], v142 offset:1024
	ds_read_b128 v[136:139], v142 offset:2048
	ds_read_b128 v[142:145], v142 offset:3072
	ds_read_b128 v[146:149], v168
	ds_read_b128 v[150:153], v168 offset:1024
	ds_read_b128 v[154:157], v168 offset:2048
	ds_read_b128 v[168:171], v168 offset:3072
	v_lshl_add_u64 v[176:177], s[6:7], 0, v[164:165]
	s_add_i32 m0, s15, 0xc000
	ds_read_b128 v[172:175], v179
	ds_read_b128 v[180:183], v179 offset:1024
	ds_read_b128 v[184:187], v179 offset:2048
	ds_read_b128 v[188:191], v179 offset:3072
	ds_read_b128 v[192:195], v179 offset:4096
	ds_read_b128 v[200:203], v179 offset:5120
	ds_read_b128 v[206:209], v179 offset:6144
	ds_read_b128 v[210:213], v179 offset:7168
	global_load_lds_dwordx4 v[176:177], off
	v_lshl_add_u64 v[176:177], s[6:7], 0, v[166:167]
	s_add_i32 m0, s15, 0xe000
	s_nop 0
	global_load_lds_dwordx4 v[176:177], off
	s_waitcnt vmcnt(8)
	s_waitcnt lgkmcnt(0)
	s_setprio 1
	s_barrier
	v_mfma_f32_16x16x32_bf16 v[124:127], v[128:131], v[172:175], v[124:127]
	v_mfma_f32_16x16x32_bf16 v[120:123], v[136:139], v[172:175], v[120:123]
	v_mfma_f32_16x16x32_bf16 v[108:111], v[128:131], v[184:187], v[108:111]
	v_mfma_f32_16x16x32_bf16 v[104:107], v[136:139], v[184:187], v[104:107]
	v_mfma_f32_16x16x32_bf16 v[92:95], v[128:131], v[192:195], v[92:95]
	v_mfma_f32_16x16x32_bf16 v[88:91], v[136:139], v[192:195], v[88:91]
	v_mfma_f32_16x16x32_bf16 v[76:79], v[128:131], v[206:209], v[76:79]
	v_mfma_f32_16x16x32_bf16 v[72:75], v[136:139], v[206:209], v[72:75]
	v_mfma_f32_16x16x32_bf16 v[124:127], v[132:135], v[180:183], v[124:127]
	v_mfma_f32_16x16x32_bf16 v[120:123], v[142:145], v[180:183], v[120:123]
	v_mfma_f32_16x16x32_bf16 v[108:111], v[132:135], v[188:191], v[108:111]
	v_mfma_f32_16x16x32_bf16 v[104:107], v[142:145], v[188:191], v[104:107]
	v_mfma_f32_16x16x32_bf16 v[92:95], v[132:135], v[200:203], v[92:95]
	v_mfma_f32_16x16x32_bf16 v[88:91], v[142:145], v[200:203], v[88:91]
	v_mfma_f32_16x16x32_bf16 v[76:79], v[132:135], v[210:213], v[76:79]
	v_mfma_f32_16x16x32_bf16 v[72:75], v[142:145], v[210:213], v[72:75]
	v_mfma_f32_16x16x32_bf16 v[116:119], v[146:149], v[172:175], v[116:119]
	v_mfma_f32_16x16x32_bf16 v[112:115], v[154:157], v[172:175], v[112:115]
	v_mfma_f32_16x16x32_bf16 v[100:103], v[146:149], v[184:187], v[100:103]
	v_mfma_f32_16x16x32_bf16 v[96:99], v[154:157], v[184:187], v[96:99]
	v_mfma_f32_16x16x32_bf16 v[84:87], v[146:149], v[192:195], v[84:87]
	v_mfma_f32_16x16x32_bf16 v[80:83], v[154:157], v[192:195], v[80:83]
	v_mfma_f32_16x16x32_bf16 v[68:71], v[146:149], v[206:209], v[68:71]
	v_mfma_f32_16x16x32_bf16 v[64:67], v[154:157], v[206:209], v[64:67]
	v_mfma_f32_16x16x32_bf16 v[116:119], v[150:153], v[180:183], v[116:119]
	v_mfma_f32_16x16x32_bf16 v[112:115], v[168:171], v[180:183], v[112:115]
	v_mfma_f32_16x16x32_bf16 v[100:103], v[150:153], v[188:191], v[100:103]
	v_mfma_f32_16x16x32_bf16 v[96:99], v[168:171], v[188:191], v[96:99]
	v_mfma_f32_16x16x32_bf16 v[84:87], v[150:153], v[200:203], v[84:87]
	v_mfma_f32_16x16x32_bf16 v[80:83], v[168:171], v[200:203], v[80:83]
	v_mfma_f32_16x16x32_bf16 v[68:71], v[150:153], v[210:213], v[68:71]
	v_mfma_f32_16x16x32_bf16 v[64:67], v[168:171], v[210:213], v[64:67]
	s_barrier
	s_setprio 0
	s_add_i32 s35, s35, s13
	v_lshl_add_u64 v[176:177], s[8:9], 0, v[140:141]
	s_mov_b32 m0, s35
	ds_read_b128 v[172:175], v179 offset:16384
	ds_read_b128 v[180:183], v179 offset:17408
	ds_read_b128 v[184:187], v179 offset:18432
	ds_read_b128 v[188:191], v179 offset:19456
	ds_read_b128 v[192:195], v179 offset:20480
	ds_read_b128 v[200:203], v179 offset:21504
	ds_read_b128 v[206:209], v179 offset:22528
	ds_read_b128 v[210:213], v179 offset:23552
	global_load_lds_dwordx4 v[176:177], off
	s_add_i32 m0, s35, 0x2000
	s_add_u32 s84, s8, 0x40000
	v_lshl_add_u64 v[196:197], s[8:9], 0, v[158:159]
	s_addc_u32 s85, s9, 0
	s_add_i32 s35, s75, s13
	global_load_lds_dwordx4 v[196:197], off
	v_lshl_add_u64 v[198:199], s[84:85], 0, v[140:141]
	s_mov_b32 m0, s35
	v_lshl_add_u64 v[204:205], s[10:11], 0, v[160:161]
	global_load_lds_dwordx4 v[198:199], off
	v_lshl_add_u64 v[198:199], s[84:85], 0, v[158:159]
	s_add_i32 m0, s35, 0x2000
	s_nop 0
	global_load_lds_dwordx4 v[198:199], off
	v_lshl_add_u64 v[198:199], s[10:11], 0, v[162:163]
	s_mov_b32 m0, s15
	s_nop 0
	global_load_lds_dwordx4 v[198:199], off
	s_mov_b32 m0, s26
	s_nop 0
	global_load_lds_dwordx4 v[204:205], off
	s_waitcnt vmcnt(8)
	s_waitcnt lgkmcnt(0)
	s_setprio 1
	s_barrier
	v_mfma_f32_16x16x32_bf16 v[60:63], v[128:131], v[172:175], v[60:63]
	v_mfma_f32_16x16x32_bf16 v[56:59], v[136:139], v[172:175], v[56:59]
	v_mfma_f32_16x16x32_bf16 v[44:47], v[128:131], v[184:187], v[44:47]
	v_mfma_f32_16x16x32_bf16 v[40:43], v[136:139], v[184:187], v[40:43]
	v_mfma_f32_16x16x32_bf16 v[28:31], v[128:131], v[192:195], v[28:31]
	v_mfma_f32_16x16x32_bf16 v[24:27], v[136:139], v[192:195], v[24:27]
	v_mfma_f32_16x16x32_bf16 v[12:15], v[128:131], v[206:209], v[12:15]
	v_mfma_f32_16x16x32_bf16 v[8:11], v[136:139], v[206:209], v[8:11]
	v_mfma_f32_16x16x32_bf16 v[60:63], v[132:135], v[180:183], v[60:63]
	v_mfma_f32_16x16x32_bf16 v[56:59], v[142:145], v[180:183], v[56:59]
	v_mfma_f32_16x16x32_bf16 v[44:47], v[132:135], v[188:191], v[44:47]
	v_mfma_f32_16x16x32_bf16 v[40:43], v[142:145], v[188:191], v[40:43]
	v_mfma_f32_16x16x32_bf16 v[28:31], v[132:135], v[200:203], v[28:31]
	v_mfma_f32_16x16x32_bf16 v[24:27], v[142:145], v[200:203], v[24:27]
	v_mfma_f32_16x16x32_bf16 v[12:15], v[132:135], v[210:213], v[12:15]
	v_mfma_f32_16x16x32_bf16 v[8:11], v[142:145], v[210:213], v[8:11]
	v_mfma_f32_16x16x32_bf16 v[52:55], v[146:149], v[172:175], v[52:55]
	v_mfma_f32_16x16x32_bf16 v[48:51], v[154:157], v[172:175], v[48:51]
	v_mfma_f32_16x16x32_bf16 v[36:39], v[146:149], v[184:187], v[36:39]
	v_mfma_f32_16x16x32_bf16 v[32:35], v[154:157], v[184:187], v[32:35]
	v_mfma_f32_16x16x32_bf16 v[20:23], v[146:149], v[192:195], v[20:23]
	v_mfma_f32_16x16x32_bf16 v[16:19], v[154:157], v[192:195], v[16:19]
	v_mfma_f32_16x16x32_bf16 v[4:7], v[146:149], v[206:209], v[4:7]
	v_mfma_f32_16x16x32_bf16 v[0:3], v[154:157], v[206:209], v[0:3]
	v_mfma_f32_16x16x32_bf16 v[52:55], v[150:153], v[180:183], v[52:55]
	v_mfma_f32_16x16x32_bf16 v[48:51], v[168:171], v[180:183], v[48:51]
	v_mfma_f32_16x16x32_bf16 v[36:39], v[150:153], v[188:191], v[36:39]
	v_mfma_f32_16x16x32_bf16 v[32:35], v[168:171], v[188:191], v[32:35]
	v_mfma_f32_16x16x32_bf16 v[20:23], v[150:153], v[200:203], v[20:23]
	v_mfma_f32_16x16x32_bf16 v[16:19], v[168:171], v[200:203], v[16:19]
	v_mfma_f32_16x16x32_bf16 v[4:7], v[150:153], v[210:213], v[4:7]
	v_mfma_f32_16x16x32_bf16 v[0:3], v[168:171], v[210:213], v[0:3]
	s_barrier
	s_setprio 0
	s_add_i32 s35, 0, 0x18000
	s_add_i32 s75, 0, 0x1c000
	v_add_u32_e32 v142, s35, v178
	v_add_u32_e32 v168, s75, v178
	ds_read_b128 v[128:131], v142
	ds_read_b128 v[132:135], v142 offset:1024
	ds_read_b128 v[136:139], v142 offset:2048
	ds_read_b128 v[142:145], v142 offset:3072
	ds_read_b128 v[146:149], v168
	ds_read_b128 v[150:153], v168 offset:1024
	ds_read_b128 v[154:157], v168 offset:2048
	ds_read_b128 v[168:171], v168 offset:3072
	s_add_u32 s10, s10, 0x40000
	s_addc_u32 s11, s11, 0
	s_mov_b32 m0, s27
	v_lshl_add_u64 v[214:215], s[10:11], 0, v[162:163]
	ds_read_b128 v[172:175], v179 offset:32768
	ds_read_b128 v[180:183], v179 offset:33792
	ds_read_b128 v[184:187], v179 offset:34816
	ds_read_b128 v[188:191], v179 offset:35840
	ds_read_b128 v[192:195], v179 offset:36864
	ds_read_b128 v[200:203], v179 offset:37888
	ds_read_b128 v[206:209], v179 offset:38912
	ds_read_b128 v[210:213], v179 offset:39936
	global_load_lds_dwordx4 v[214:215], off
	v_lshl_add_u64 v[214:215], s[10:11], 0, v[160:161]
	s_mov_b32 m0, s28
	s_nop 0
	global_load_lds_dwordx4 v[214:215], off
	s_waitcnt vmcnt(8)
	s_waitcnt lgkmcnt(0)
	s_setprio 1
	s_barrier
	v_mfma_f32_16x16x32_bf16 v[124:127], v[128:131], v[172:175], v[124:127]
	v_mfma_f32_16x16x32_bf16 v[120:123], v[136:139], v[172:175], v[120:123]
	v_mfma_f32_16x16x32_bf16 v[108:111], v[128:131], v[184:187], v[108:111]
	v_mfma_f32_16x16x32_bf16 v[104:107], v[136:139], v[184:187], v[104:107]
	v_mfma_f32_16x16x32_bf16 v[92:95], v[128:131], v[192:195], v[92:95]
	v_mfma_f32_16x16x32_bf16 v[88:91], v[136:139], v[192:195], v[88:91]
	v_mfma_f32_16x16x32_bf16 v[76:79], v[128:131], v[206:209], v[76:79]
	v_mfma_f32_16x16x32_bf16 v[72:75], v[136:139], v[206:209], v[72:75]
	v_mfma_f32_16x16x32_bf16 v[124:127], v[132:135], v[180:183], v[124:127]
	v_mfma_f32_16x16x32_bf16 v[120:123], v[142:145], v[180:183], v[120:123]
	v_mfma_f32_16x16x32_bf16 v[108:111], v[132:135], v[188:191], v[108:111]
	v_mfma_f32_16x16x32_bf16 v[104:107], v[142:145], v[188:191], v[104:107]
	v_mfma_f32_16x16x32_bf16 v[92:95], v[132:135], v[200:203], v[92:95]
	v_mfma_f32_16x16x32_bf16 v[88:91], v[142:145], v[200:203], v[88:91]
	v_mfma_f32_16x16x32_bf16 v[76:79], v[132:135], v[210:213], v[76:79]
	v_mfma_f32_16x16x32_bf16 v[72:75], v[142:145], v[210:213], v[72:75]
	v_mfma_f32_16x16x32_bf16 v[116:119], v[146:149], v[172:175], v[116:119]
	v_mfma_f32_16x16x32_bf16 v[112:115], v[154:157], v[172:175], v[112:115]
	v_mfma_f32_16x16x32_bf16 v[100:103], v[146:149], v[184:187], v[100:103]
	v_mfma_f32_16x16x32_bf16 v[96:99], v[154:157], v[184:187], v[96:99]
	v_mfma_f32_16x16x32_bf16 v[84:87], v[146:149], v[192:195], v[84:87]
	v_mfma_f32_16x16x32_bf16 v[80:83], v[154:157], v[192:195], v[80:83]
	v_mfma_f32_16x16x32_bf16 v[68:71], v[146:149], v[206:209], v[68:71]
	v_mfma_f32_16x16x32_bf16 v[64:67], v[154:157], v[206:209], v[64:67]
	v_mfma_f32_16x16x32_bf16 v[116:119], v[150:153], v[180:183], v[116:119]
	v_mfma_f32_16x16x32_bf16 v[112:115], v[168:171], v[180:183], v[112:115]
	v_mfma_f32_16x16x32_bf16 v[100:103], v[150:153], v[188:191], v[100:103]
	v_mfma_f32_16x16x32_bf16 v[96:99], v[168:171], v[188:191], v[96:99]
	v_mfma_f32_16x16x32_bf16 v[84:87], v[150:153], v[200:203], v[84:87]
	v_mfma_f32_16x16x32_bf16 v[80:83], v[168:171], v[200:203], v[80:83]
	v_mfma_f32_16x16x32_bf16 v[68:71], v[150:153], v[210:213], v[68:71]
	v_mfma_f32_16x16x32_bf16 v[64:67], v[168:171], v[210:213], v[64:67]
	s_barrier
	s_setprio 0
	s_add_i32 s10, s35, s13
	v_lshl_add_u64 v[176:177], v[176:177], 0, s[36:37]
	s_mov_b32 m0, s10
	ds_read_b128 v[172:175], v179 offset:49152
	ds_read_b128 v[180:183], v179 offset:50176
	ds_read_b128 v[184:187], v179 offset:51200
	ds_read_b128 v[188:191], v179 offset:52224
	ds_read_b128 v[192:195], v179 offset:53248
	ds_read_b128 v[200:203], v179 offset:54272
	ds_read_b128 v[206:209], v179 offset:55296
	ds_read_b128 v[210:213], v179 offset:56320
	global_load_lds_dwordx4 v[176:177], off
	s_add_i32 m0, s10, 0x2000
	s_add_u32 s8, s8, 0x40080
	v_lshl_add_u64 v[176:177], v[196:197], 0, s[36:37]
	s_addc_u32 s9, s9, 0
	s_add_i32 s10, s75, s13
	global_load_lds_dwordx4 v[176:177], off
	v_lshl_add_u64 v[176:177], s[8:9], 0, v[140:141]
	s_mov_b32 m0, s10
	s_nop 0
	global_load_lds_dwordx4 v[176:177], off
	v_lshl_add_u64 v[176:177], s[8:9], 0, v[158:159]
	s_add_i32 m0, s10, 0x2000
	s_nop 0
	global_load_lds_dwordx4 v[176:177], off
	v_lshl_add_u64 v[176:177], v[198:199], 0, s[36:37]
	s_mov_b32 m0, s29
	s_nop 0
	global_load_lds_dwordx4 v[176:177], off
	v_lshl_add_u64 v[176:177], v[204:205], 0, s[36:37]
	s_mov_b32 m0, s42
	s_nop 0
	global_load_lds_dwordx4 v[176:177], off
	s_waitcnt vmcnt(8)
	s_waitcnt lgkmcnt(0)
	s_setprio 1
	s_barrier
	v_mfma_f32_16x16x32_bf16 v[60:63], v[128:131], v[172:175], v[60:63]
	v_mfma_f32_16x16x32_bf16 v[56:59], v[136:139], v[172:175], v[56:59]
	v_mfma_f32_16x16x32_bf16 v[44:47], v[128:131], v[184:187], v[44:47]
	v_mfma_f32_16x16x32_bf16 v[40:43], v[136:139], v[184:187], v[40:43]
	v_mfma_f32_16x16x32_bf16 v[28:31], v[128:131], v[192:195], v[28:31]
	v_mfma_f32_16x16x32_bf16 v[24:27], v[136:139], v[192:195], v[24:27]
	v_mfma_f32_16x16x32_bf16 v[12:15], v[128:131], v[206:209], v[12:15]
	v_mfma_f32_16x16x32_bf16 v[8:11], v[136:139], v[206:209], v[8:11]
	v_mfma_f32_16x16x32_bf16 v[60:63], v[132:135], v[180:183], v[60:63]
	v_mfma_f32_16x16x32_bf16 v[56:59], v[142:145], v[180:183], v[56:59]
	v_mfma_f32_16x16x32_bf16 v[44:47], v[132:135], v[188:191], v[44:47]
	v_mfma_f32_16x16x32_bf16 v[40:43], v[142:145], v[188:191], v[40:43]
	v_mfma_f32_16x16x32_bf16 v[28:31], v[132:135], v[200:203], v[28:31]
	v_mfma_f32_16x16x32_bf16 v[24:27], v[142:145], v[200:203], v[24:27]
	v_mfma_f32_16x16x32_bf16 v[12:15], v[132:135], v[210:213], v[12:15]
	v_mfma_f32_16x16x32_bf16 v[8:11], v[142:145], v[210:213], v[8:11]
	v_mfma_f32_16x16x32_bf16 v[52:55], v[146:149], v[172:175], v[52:55]
	v_mfma_f32_16x16x32_bf16 v[48:51], v[154:157], v[172:175], v[48:51]
	v_mfma_f32_16x16x32_bf16 v[36:39], v[146:149], v[184:187], v[36:39]
	v_mfma_f32_16x16x32_bf16 v[32:35], v[154:157], v[184:187], v[32:35]
	v_mfma_f32_16x16x32_bf16 v[20:23], v[146:149], v[192:195], v[20:23]
	v_mfma_f32_16x16x32_bf16 v[16:19], v[154:157], v[192:195], v[16:19]
	v_mfma_f32_16x16x32_bf16 v[4:7], v[146:149], v[206:209], v[4:7]
	v_mfma_f32_16x16x32_bf16 v[0:3], v[154:157], v[206:209], v[0:3]
	v_mfma_f32_16x16x32_bf16 v[52:55], v[150:153], v[180:183], v[52:55]
	v_mfma_f32_16x16x32_bf16 v[48:51], v[168:171], v[180:183], v[48:51]
	v_mfma_f32_16x16x32_bf16 v[36:39], v[150:153], v[188:191], v[36:39]
	v_mfma_f32_16x16x32_bf16 v[32:35], v[168:171], v[188:191], v[32:35]
	v_mfma_f32_16x16x32_bf16 v[20:23], v[150:153], v[200:203], v[20:23]
	v_mfma_f32_16x16x32_bf16 v[16:19], v[168:171], v[200:203], v[16:19]
	v_mfma_f32_16x16x32_bf16 v[4:7], v[150:153], v[210:213], v[4:7]
	v_mfma_f32_16x16x32_bf16 v[0:3], v[168:171], v[210:213], v[0:3]
	s_barrier
	s_setprio 0
	s_add_i32 s74, s74, 2
	s_add_u32 s6, s6, 0x100
	s_addc_u32 s7, s7, 0
	s_add_u32 s60, s60, 0x100
	s_addc_u32 s61, s61, 0
	s_cmp_gt_u32 s74, 13
	s_cbranch_scc0 .LBB0_147
	s_and_b64 vcc, exec, s[50:51]
	s_cbranch_vccz .LBB0_150
	s_barrier

.LBB0_234:
	s_add_u32 s8, s6, 0xfffc0080
	s_addc_u32 s9, s7, -1
	s_add_i32 s35, 0, 0x10000
	s_cmp_eq_u32 s53, 12
	s_cselect_b32 s11, s4, s9
	s_cselect_b32 s10, s5, s8
	v_add_u32_e32 v140, s35, v206
	s_cselect_b32 s9, s24, s51
	s_cselect_b32 s8, s42, s43
	s_add_i32 s76, 0, 0x14000
	ds_read_b128 v[142:145], v140
	ds_read_b128 v[146:149], v140 offset:1024
	ds_read_b128 v[150:153], v140 offset:2048
	ds_read_b128 v[154:157], v140 offset:3072
	v_add_u32_e32 v140, s76, v206
	ds_read_b128 v[158:161], v140
	ds_read_b128 v[162:165], v140 offset:1024
	ds_read_b128 v[166:169], v140 offset:2048
	ds_read_b128 v[170:173], v140 offset:3072
	v_lshl_add_u64 v[198:199], s[6:7], 0, v[136:137]
	s_add_i32 m0, s15, 0xc000
	ds_read_b128 v[174:177], v207
	ds_read_b128 v[178:181], v207 offset:1024
	ds_read_b128 v[182:185], v207 offset:2048
	ds_read_b128 v[186:189], v207 offset:3072
	ds_read_b128 v[190:193], v207 offset:4096
	ds_read_b128 v[194:197], v207 offset:5120
	ds_read_b128 v[200:203], v207 offset:6144
	ds_read_b128 v[208:211], v207 offset:7168
	global_load_lds_dwordx4 v[198:199], off
	v_lshl_add_u64 v[198:199], s[6:7], 0, v[138:139]
	s_add_i32 m0, s15, 0xe000
	s_nop 0
	global_load_lds_dwordx4 v[198:199], off
	s_waitcnt vmcnt(8)
	s_waitcnt lgkmcnt(0)
	s_setprio 1
	s_barrier
	v_mfma_f32_16x16x32_bf16 v[124:127], v[142:145], v[174:177], v[124:127]
	v_mfma_f32_16x16x32_bf16 v[120:123], v[150:153], v[174:177], v[120:123]
	v_mfma_f32_16x16x32_bf16 v[108:111], v[142:145], v[182:185], v[108:111]
	v_mfma_f32_16x16x32_bf16 v[104:107], v[150:153], v[182:185], v[104:107]
	v_mfma_f32_16x16x32_bf16 v[92:95], v[142:145], v[190:193], v[92:95]
	v_mfma_f32_16x16x32_bf16 v[88:91], v[150:153], v[190:193], v[88:91]
	v_mfma_f32_16x16x32_bf16 v[76:79], v[142:145], v[200:203], v[76:79]
	v_mfma_f32_16x16x32_bf16 v[72:75], v[150:153], v[200:203], v[72:75]
	v_mfma_f32_16x16x32_bf16 v[124:127], v[146:149], v[178:181], v[124:127]
	v_mfma_f32_16x16x32_bf16 v[120:123], v[154:157], v[178:181], v[120:123]
	v_mfma_f32_16x16x32_bf16 v[108:111], v[146:149], v[186:189], v[108:111]
	v_mfma_f32_16x16x32_bf16 v[104:107], v[154:157], v[186:189], v[104:107]
	v_mfma_f32_16x16x32_bf16 v[92:95], v[146:149], v[194:197], v[92:95]
	v_mfma_f32_16x16x32_bf16 v[88:91], v[154:157], v[194:197], v[88:91]
	v_mfma_f32_16x16x32_bf16 v[76:79], v[146:149], v[208:211], v[76:79]
	v_mfma_f32_16x16x32_bf16 v[72:75], v[154:157], v[208:211], v[72:75]
	v_mfma_f32_16x16x32_bf16 v[116:119], v[158:161], v[174:177], v[116:119]
	v_mfma_f32_16x16x32_bf16 v[112:115], v[166:169], v[174:177], v[112:115]
	v_mfma_f32_16x16x32_bf16 v[100:103], v[158:161], v[182:185], v[100:103]
	v_mfma_f32_16x16x32_bf16 v[96:99], v[166:169], v[182:185], v[96:99]
	v_mfma_f32_16x16x32_bf16 v[84:87], v[158:161], v[190:193], v[84:87]
	v_mfma_f32_16x16x32_bf16 v[80:83], v[166:169], v[190:193], v[80:83]
	v_mfma_f32_16x16x32_bf16 v[68:71], v[158:161], v[200:203], v[68:71]
	v_mfma_f32_16x16x32_bf16 v[64:67], v[166:169], v[200:203], v[64:67]
	v_mfma_f32_16x16x32_bf16 v[116:119], v[162:165], v[178:181], v[116:119]
	v_mfma_f32_16x16x32_bf16 v[112:115], v[170:173], v[178:181], v[112:115]
	v_mfma_f32_16x16x32_bf16 v[100:103], v[162:165], v[186:189], v[100:103]
	v_mfma_f32_16x16x32_bf16 v[96:99], v[170:173], v[186:189], v[96:99]
	v_mfma_f32_16x16x32_bf16 v[84:87], v[162:165], v[194:197], v[84:87]
	v_mfma_f32_16x16x32_bf16 v[80:83], v[170:173], v[194:197], v[80:83]
	v_mfma_f32_16x16x32_bf16 v[68:71], v[162:165], v[208:211], v[68:71]
	v_mfma_f32_16x16x32_bf16 v[64:67], v[170:173], v[208:211], v[64:67]
	s_barrier
	s_setprio 0
	s_add_i32 s35, s35, s13
	v_lshl_add_u64 v[198:199], s[8:9], 0, v[132:133]
	s_mov_b32 m0, s35
	ds_read_b128 v[174:177], v207 offset:16384
	ds_read_b128 v[178:181], v207 offset:17408
	ds_read_b128 v[182:185], v207 offset:18432
	ds_read_b128 v[186:189], v207 offset:19456
	ds_read_b128 v[190:193], v207 offset:20480
	ds_read_b128 v[194:197], v207 offset:21504
	ds_read_b128 v[200:203], v207 offset:22528
	ds_read_b128 v[208:211], v207 offset:23552
	global_load_lds_dwordx4 v[198:199], off
	s_add_i32 m0, s35, 0x2000
	s_add_u32 s60, s8, 0x40000
	v_lshl_add_u64 v[204:205], s[8:9], 0, v[128:129]
	s_addc_u32 s61, s9, 0
	s_add_i32 s35, s76, s13
	global_load_lds_dwordx4 v[204:205], off
	v_lshl_add_u64 v[212:213], s[60:61], 0, v[132:133]
	s_mov_b32 m0, s35
	v_lshl_add_u64 v[214:215], s[10:11], 0, v[130:131]
	global_load_lds_dwordx4 v[212:213], off
	v_lshl_add_u64 v[212:213], s[60:61], 0, v[128:129]
	s_add_i32 m0, s35, 0x2000
	s_nop 0
	global_load_lds_dwordx4 v[212:213], off
	v_lshl_add_u64 v[212:213], s[10:11], 0, v[134:135]
	s_mov_b32 m0, s15
	s_nop 0
	global_load_lds_dwordx4 v[212:213], off
	s_mov_b32 m0, s26
	s_nop 0
	global_load_lds_dwordx4 v[214:215], off
	s_waitcnt vmcnt(8)
	s_waitcnt lgkmcnt(0)
	s_setprio 1
	s_barrier
	v_mfma_f32_16x16x32_bf16 v[60:63], v[142:145], v[174:177], v[60:63]
	v_mfma_f32_16x16x32_bf16 v[56:59], v[150:153], v[174:177], v[56:59]
	v_mfma_f32_16x16x32_bf16 v[44:47], v[142:145], v[182:185], v[44:47]
	v_mfma_f32_16x16x32_bf16 v[40:43], v[150:153], v[182:185], v[40:43]
	v_mfma_f32_16x16x32_bf16 v[28:31], v[142:145], v[190:193], v[28:31]
	v_mfma_f32_16x16x32_bf16 v[24:27], v[150:153], v[190:193], v[24:27]
	v_mfma_f32_16x16x32_bf16 v[12:15], v[142:145], v[200:203], v[12:15]
	v_mfma_f32_16x16x32_bf16 v[8:11], v[150:153], v[200:203], v[8:11]
	v_mfma_f32_16x16x32_bf16 v[60:63], v[146:149], v[178:181], v[60:63]
	v_mfma_f32_16x16x32_bf16 v[56:59], v[154:157], v[178:181], v[56:59]
	v_mfma_f32_16x16x32_bf16 v[44:47], v[146:149], v[186:189], v[44:47]
	v_mfma_f32_16x16x32_bf16 v[40:43], v[154:157], v[186:189], v[40:43]
	v_mfma_f32_16x16x32_bf16 v[28:31], v[146:149], v[194:197], v[28:31]
	v_mfma_f32_16x16x32_bf16 v[24:27], v[154:157], v[194:197], v[24:27]
	v_mfma_f32_16x16x32_bf16 v[12:15], v[146:149], v[208:211], v[12:15]
	v_mfma_f32_16x16x32_bf16 v[8:11], v[154:157], v[208:211], v[8:11]
	v_mfma_f32_16x16x32_bf16 v[52:55], v[158:161], v[174:177], v[52:55]
	v_mfma_f32_16x16x32_bf16 v[48:51], v[166:169], v[174:177], v[48:51]
	v_mfma_f32_16x16x32_bf16 v[36:39], v[158:161], v[182:185], v[36:39]
	v_mfma_f32_16x16x32_bf16 v[32:35], v[166:169], v[182:185], v[32:35]
	v_mfma_f32_16x16x32_bf16 v[20:23], v[158:161], v[190:193], v[20:23]
	v_mfma_f32_16x16x32_bf16 v[16:19], v[166:169], v[190:193], v[16:19]
	v_mfma_f32_16x16x32_bf16 v[4:7], v[158:161], v[200:203], v[4:7]
	v_mfma_f32_16x16x32_bf16 v[0:3], v[166:169], v[200:203], v[0:3]
	v_mfma_f32_16x16x32_bf16 v[52:55], v[162:165], v[178:181], v[52:55]
	v_mfma_f32_16x16x32_bf16 v[48:51], v[170:173], v[178:181], v[48:51]
	v_mfma_f32_16x16x32_bf16 v[36:39], v[162:165], v[186:189], v[36:39]
	v_mfma_f32_16x16x32_bf16 v[32:35], v[170:173], v[186:189], v[32:35]
	v_mfma_f32_16x16x32_bf16 v[20:23], v[162:165], v[194:197], v[20:23]
	v_mfma_f32_16x16x32_bf16 v[16:19], v[170:173], v[194:197], v[16:19]
	v_mfma_f32_16x16x32_bf16 v[4:7], v[162:165], v[208:211], v[4:7]
	v_mfma_f32_16x16x32_bf16 v[0:3], v[170:173], v[208:211], v[0:3]
	s_barrier
	s_setprio 0
	s_add_i32 s35, 0, 0x18000
	v_add_u32_e32 v140, s35, v206
	s_add_i32 s60, 0, 0x1c000
	ds_read_b128 v[142:145], v140
	ds_read_b128 v[146:149], v140 offset:1024
	ds_read_b128 v[150:153], v140 offset:2048
	ds_read_b128 v[154:157], v140 offset:3072
	v_add_u32_e32 v140, s60, v206
	ds_read_b128 v[158:161], v140
	ds_read_b128 v[162:165], v140 offset:1024
	ds_read_b128 v[166:169], v140 offset:2048
	ds_read_b128 v[170:173], v140 offset:3072
	s_add_u32 s10, s10, 0x40000
	s_addc_u32 s11, s11, 0
	s_mov_b32 m0, s27
	v_lshl_add_u64 v[216:217], s[10:11], 0, v[134:135]
	ds_read_b128 v[174:177], v207 offset:32768
	ds_read_b128 v[178:181], v207 offset:33792
	ds_read_b128 v[182:185], v207 offset:34816
	ds_read_b128 v[186:189], v207 offset:35840
	ds_read_b128 v[190:193], v207 offset:36864
	ds_read_b128 v[194:197], v207 offset:37888
	ds_read_b128 v[200:203], v207 offset:38912
	ds_read_b128 v[208:211], v207 offset:39936
	global_load_lds_dwordx4 v[216:217], off
	v_lshl_add_u64 v[216:217], s[10:11], 0, v[130:131]
	s_mov_b32 m0, s28
	s_nop 0
	global_load_lds_dwordx4 v[216:217], off
	s_waitcnt vmcnt(8)
	s_waitcnt lgkmcnt(0)
	s_setprio 1
	s_barrier
	v_mfma_f32_16x16x32_bf16 v[124:127], v[142:145], v[174:177], v[124:127]
	v_mfma_f32_16x16x32_bf16 v[120:123], v[150:153], v[174:177], v[120:123]
	v_mfma_f32_16x16x32_bf16 v[108:111], v[142:145], v[182:185], v[108:111]
	v_mfma_f32_16x16x32_bf16 v[104:107], v[150:153], v[182:185], v[104:107]
	v_mfma_f32_16x16x32_bf16 v[92:95], v[142:145], v[190:193], v[92:95]
	v_mfma_f32_16x16x32_bf16 v[88:91], v[150:153], v[190:193], v[88:91]
	v_mfma_f32_16x16x32_bf16 v[76:79], v[142:145], v[200:203], v[76:79]
	v_mfma_f32_16x16x32_bf16 v[72:75], v[150:153], v[200:203], v[72:75]
	v_mfma_f32_16x16x32_bf16 v[124:127], v[146:149], v[178:181], v[124:127]
	v_mfma_f32_16x16x32_bf16 v[120:123], v[154:157], v[178:181], v[120:123]
	v_mfma_f32_16x16x32_bf16 v[108:111], v[146:149], v[186:189], v[108:111]
	v_mfma_f32_16x16x32_bf16 v[104:107], v[154:157], v[186:189], v[104:107]
	v_mfma_f32_16x16x32_bf16 v[92:95], v[146:149], v[194:197], v[92:95]
	v_mfma_f32_16x16x32_bf16 v[88:91], v[154:157], v[194:197], v[88:91]
	v_mfma_f32_16x16x32_bf16 v[76:79], v[146:149], v[208:211], v[76:79]
	v_mfma_f32_16x16x32_bf16 v[72:75], v[154:157], v[208:211], v[72:75]
	v_mfma_f32_16x16x32_bf16 v[116:119], v[158:161], v[174:177], v[116:119]
	v_mfma_f32_16x16x32_bf16 v[112:115], v[166:169], v[174:177], v[112:115]
	v_mfma_f32_16x16x32_bf16 v[100:103], v[158:161], v[182:185], v[100:103]
	v_mfma_f32_16x16x32_bf16 v[96:99], v[166:169], v[182:185], v[96:99]
	v_mfma_f32_16x16x32_bf16 v[84:87], v[158:161], v[190:193], v[84:87]
	v_mfma_f32_16x16x32_bf16 v[80:83], v[166:169], v[190:193], v[80:83]
	v_mfma_f32_16x16x32_bf16 v[68:71], v[158:161], v[200:203], v[68:71]
	v_mfma_f32_16x16x32_bf16 v[64:67], v[166:169], v[200:203], v[64:67]
	v_mfma_f32_16x16x32_bf16 v[116:119], v[162:165], v[178:181], v[116:119]
	v_mfma_f32_16x16x32_bf16 v[112:115], v[170:173], v[178:181], v[112:115]
	v_mfma_f32_16x16x32_bf16 v[100:103], v[162:165], v[186:189], v[100:103]
	v_mfma_f32_16x16x32_bf16 v[96:99], v[170:173], v[186:189], v[96:99]
	v_mfma_f32_16x16x32_bf16 v[84:87], v[162:165], v[194:197], v[84:87]
	v_mfma_f32_16x16x32_bf16 v[80:83], v[170:173], v[194:197], v[80:83]
	v_mfma_f32_16x16x32_bf16 v[68:71], v[162:165], v[208:211], v[68:71]
	v_mfma_f32_16x16x32_bf16 v[64:67], v[170:173], v[208:211], v[64:67]
	s_barrier
	s_setprio 0
	s_add_i32 s10, s35, s13
	v_lshl_add_u64 v[198:199], v[198:199], 0, s[36:37]
	s_mov_b32 m0, s10
	ds_read_b128 v[174:177], v207 offset:49152
	ds_read_b128 v[178:181], v207 offset:50176
	ds_read_b128 v[182:185], v207 offset:51200
	ds_read_b128 v[186:189], v207 offset:52224
	ds_read_b128 v[190:193], v207 offset:53248
	ds_read_b128 v[194:197], v207 offset:54272
	ds_read_b128 v[200:203], v207 offset:55296
	ds_read_b128 v[208:211], v207 offset:56320
	global_load_lds_dwordx4 v[198:199], off
	s_add_i32 m0, s10, 0x2000
	s_add_u32 s8, s8, 0x40080
	v_lshl_add_u64 v[198:199], v[204:205], 0, s[36:37]
	s_addc_u32 s9, s9, 0
	s_add_i32 s10, s60, s13
	global_load_lds_dwordx4 v[198:199], off
	v_lshl_add_u64 v[198:199], s[8:9], 0, v[132:133]
	s_mov_b32 m0, s10
	s_nop 0
	global_load_lds_dwordx4 v[198:199], off
	v_lshl_add_u64 v[198:199], s[8:9], 0, v[128:129]
	s_add_i32 m0, s10, 0x2000
	s_nop 0
	global_load_lds_dwordx4 v[198:199], off
	v_lshl_add_u64 v[198:199], v[212:213], 0, s[36:37]
	s_mov_b32 m0, s29
	s_nop 0
	global_load_lds_dwordx4 v[198:199], off
	v_lshl_add_u64 v[198:199], v[214:215], 0, s[36:37]
	s_mov_b32 m0, s38
	s_nop 0
	global_load_lds_dwordx4 v[198:199], off
	s_waitcnt vmcnt(8)
	s_waitcnt lgkmcnt(0)
	s_setprio 1
	s_barrier
	v_mfma_f32_16x16x32_bf16 v[60:63], v[142:145], v[174:177], v[60:63]
	v_mfma_f32_16x16x32_bf16 v[56:59], v[150:153], v[174:177], v[56:59]
	v_mfma_f32_16x16x32_bf16 v[44:47], v[142:145], v[182:185], v[44:47]
	v_mfma_f32_16x16x32_bf16 v[40:43], v[150:153], v[182:185], v[40:43]
	v_mfma_f32_16x16x32_bf16 v[28:31], v[142:145], v[190:193], v[28:31]
	v_mfma_f32_16x16x32_bf16 v[24:27], v[150:153], v[190:193], v[24:27]
	v_mfma_f32_16x16x32_bf16 v[12:15], v[142:145], v[200:203], v[12:15]
	v_mfma_f32_16x16x32_bf16 v[8:11], v[150:153], v[200:203], v[8:11]
	v_mfma_f32_16x16x32_bf16 v[60:63], v[146:149], v[178:181], v[60:63]
	v_mfma_f32_16x16x32_bf16 v[56:59], v[154:157], v[178:181], v[56:59]
	v_mfma_f32_16x16x32_bf16 v[44:47], v[146:149], v[186:189], v[44:47]
	v_mfma_f32_16x16x32_bf16 v[40:43], v[154:157], v[186:189], v[40:43]
	v_mfma_f32_16x16x32_bf16 v[28:31], v[146:149], v[194:197], v[28:31]
	v_mfma_f32_16x16x32_bf16 v[24:27], v[154:157], v[194:197], v[24:27]
	v_mfma_f32_16x16x32_bf16 v[12:15], v[146:149], v[208:211], v[12:15]
	v_mfma_f32_16x16x32_bf16 v[8:11], v[154:157], v[208:211], v[8:11]
	v_mfma_f32_16x16x32_bf16 v[52:55], v[158:161], v[174:177], v[52:55]
	v_mfma_f32_16x16x32_bf16 v[48:51], v[166:169], v[174:177], v[48:51]
	v_mfma_f32_16x16x32_bf16 v[36:39], v[158:161], v[182:185], v[36:39]
	v_mfma_f32_16x16x32_bf16 v[32:35], v[166:169], v[182:185], v[32:35]
	v_mfma_f32_16x16x32_bf16 v[20:23], v[158:161], v[190:193], v[20:23]
	v_mfma_f32_16x16x32_bf16 v[16:19], v[166:169], v[190:193], v[16:19]
	v_mfma_f32_16x16x32_bf16 v[4:7], v[158:161], v[200:203], v[4:7]
	v_mfma_f32_16x16x32_bf16 v[0:3], v[166:169], v[200:203], v[0:3]
	v_mfma_f32_16x16x32_bf16 v[52:55], v[162:165], v[178:181], v[52:55]
	v_mfma_f32_16x16x32_bf16 v[48:51], v[170:173], v[178:181], v[48:51]
	v_mfma_f32_16x16x32_bf16 v[36:39], v[162:165], v[186:189], v[36:39]
	v_mfma_f32_16x16x32_bf16 v[32:35], v[170:173], v[186:189], v[32:35]
	v_mfma_f32_16x16x32_bf16 v[20:23], v[162:165], v[194:197], v[20:23]
	v_mfma_f32_16x16x32_bf16 v[16:19], v[170:173], v[194:197], v[16:19]
	v_mfma_f32_16x16x32_bf16 v[4:7], v[162:165], v[208:211], v[4:7]
	v_mfma_f32_16x16x32_bf16 v[0:3], v[170:173], v[208:211], v[0:3]
	s_barrier
	s_setprio 0
	s_add_i32 s53, s53, 2
	s_add_u32 s6, s6, 0x100
	s_addc_u32 s7, s7, 0
	s_add_u32 s43, s43, 0x100
	s_addc_u32 s51, s51, 0
	s_cmp_gt_u32 s53, 13
	s_cbranch_scc0 .LBB0_234
	s_and_b64 vcc, exec, s[48:49]
	s_cbranch_vccz .LBB0_237
	s_barrier

.LBB0_333:
	s_add_i32 s56, s8, 2
	s_add_u32 s9, s6, 0x8000
	s_addc_u32 s10, s7, 0
	s_cmp_eq_u32 s94, s8
	s_cselect_b32 s11, s43, s10
	s_cselect_b32 s10, s42, s9
	s_cselect_b32 s60, s54, s24
	s_cselect_b32 s61, s55, s38
	s_add_u32 s8, s10, 0x8000
	s_addc_u32 s9, s11, 0
	s_add_i32 s35, 0, 0x10000
	s_add_i32 s57, 0, 0x14000
	v_add_u32_e32 v142, s35, v178
	v_add_u32_e32 v168, s57, v178
	ds_read_b128 v[128:131], v142
	ds_read_b128 v[132:135], v142 offset:1024
	ds_read_b128 v[136:139], v142 offset:2048
	ds_read_b128 v[142:145], v142 offset:3072
	ds_read_b128 v[146:149], v168
	ds_read_b128 v[150:153], v168 offset:1024
	ds_read_b128 v[154:157], v168 offset:2048
	ds_read_b128 v[168:171], v168 offset:3072
	v_lshl_add_u64 v[176:177], s[6:7], 0, v[164:165]
	s_add_i32 m0, s75, 0xc000
	ds_read_b128 v[172:175], v179
	ds_read_b128 v[180:183], v179 offset:1024
	ds_read_b128 v[184:187], v179 offset:2048
	ds_read_b128 v[188:191], v179 offset:3072
	ds_read_b128 v[192:195], v179 offset:4096
	ds_read_b128 v[200:203], v179 offset:5120
	ds_read_b128 v[206:209], v179 offset:6144
	ds_read_b128 v[210:213], v179 offset:7168
	global_load_lds_dwordx4 v[176:177], off
	v_lshl_add_u64 v[176:177], s[6:7], 0, v[166:167]
	s_add_i32 m0, s75, 0xe000
	s_nop 0
	global_load_lds_dwordx4 v[176:177], off
	s_waitcnt vmcnt(8)
	s_waitcnt lgkmcnt(0)
	s_setprio 1
	s_barrier
	v_mfma_f32_16x16x32_bf16 v[124:127], v[128:131], v[172:175], v[124:127]
	v_mfma_f32_16x16x32_bf16 v[120:123], v[136:139], v[172:175], v[120:123]
	v_mfma_f32_16x16x32_bf16 v[108:111], v[128:131], v[184:187], v[108:111]
	v_mfma_f32_16x16x32_bf16 v[104:107], v[136:139], v[184:187], v[104:107]
	v_mfma_f32_16x16x32_bf16 v[92:95], v[128:131], v[192:195], v[92:95]
	v_mfma_f32_16x16x32_bf16 v[88:91], v[136:139], v[192:195], v[88:91]
	v_mfma_f32_16x16x32_bf16 v[76:79], v[128:131], v[206:209], v[76:79]
	v_mfma_f32_16x16x32_bf16 v[72:75], v[136:139], v[206:209], v[72:75]
	v_mfma_f32_16x16x32_bf16 v[124:127], v[132:135], v[180:183], v[124:127]
	v_mfma_f32_16x16x32_bf16 v[120:123], v[142:145], v[180:183], v[120:123]
	v_mfma_f32_16x16x32_bf16 v[108:111], v[132:135], v[188:191], v[108:111]
	v_mfma_f32_16x16x32_bf16 v[104:107], v[142:145], v[188:191], v[104:107]
	v_mfma_f32_16x16x32_bf16 v[92:95], v[132:135], v[200:203], v[92:95]
	v_mfma_f32_16x16x32_bf16 v[88:91], v[142:145], v[200:203], v[88:91]
	v_mfma_f32_16x16x32_bf16 v[76:79], v[132:135], v[210:213], v[76:79]
	v_mfma_f32_16x16x32_bf16 v[72:75], v[142:145], v[210:213], v[72:75]
	v_mfma_f32_16x16x32_bf16 v[116:119], v[146:149], v[172:175], v[116:119]
	v_mfma_f32_16x16x32_bf16 v[112:115], v[154:157], v[172:175], v[112:115]
	v_mfma_f32_16x16x32_bf16 v[100:103], v[146:149], v[184:187], v[100:103]
	v_mfma_f32_16x16x32_bf16 v[96:99], v[154:157], v[184:187], v[96:99]
	v_mfma_f32_16x16x32_bf16 v[84:87], v[146:149], v[192:195], v[84:87]
	v_mfma_f32_16x16x32_bf16 v[80:83], v[154:157], v[192:195], v[80:83]
	v_mfma_f32_16x16x32_bf16 v[68:71], v[146:149], v[206:209], v[68:71]
	v_mfma_f32_16x16x32_bf16 v[64:67], v[154:157], v[206:209], v[64:67]
	v_mfma_f32_16x16x32_bf16 v[116:119], v[150:153], v[180:183], v[116:119]
	v_mfma_f32_16x16x32_bf16 v[112:115], v[168:171], v[180:183], v[112:115]
	v_mfma_f32_16x16x32_bf16 v[100:103], v[150:153], v[188:191], v[100:103]
	v_mfma_f32_16x16x32_bf16 v[96:99], v[168:171], v[188:191], v[96:99]
	v_mfma_f32_16x16x32_bf16 v[84:87], v[150:153], v[200:203], v[84:87]
	v_mfma_f32_16x16x32_bf16 v[80:83], v[168:171], v[200:203], v[80:83]
	v_mfma_f32_16x16x32_bf16 v[68:71], v[150:153], v[210:213], v[68:71]
	v_mfma_f32_16x16x32_bf16 v[64:67], v[168:171], v[210:213], v[64:67]
	s_barrier
	s_setprio 0
	s_add_i32 s35, s35, s74
	v_lshl_add_u64 v[176:177], s[60:61], 0, v[140:141]
	s_mov_b32 m0, s35
	ds_read_b128 v[172:175], v179 offset:16384
	ds_read_b128 v[180:183], v179 offset:17408
	ds_read_b128 v[184:187], v179 offset:18432
	ds_read_b128 v[188:191], v179 offset:19456
	ds_read_b128 v[192:195], v179 offset:20480
	ds_read_b128 v[200:203], v179 offset:21504
	ds_read_b128 v[206:209], v179 offset:22528
	ds_read_b128 v[210:213], v179 offset:23552
	global_load_lds_dwordx4 v[176:177], off
	s_add_i32 m0, s35, 0x2000
	v_lshl_add_u64 v[196:197], s[60:61], 0, v[158:159]
	s_add_u32 s60, s60, s13
	s_addc_u32 s61, s61, 0
	s_add_i32 s35, s57, s74
	global_load_lds_dwordx4 v[196:197], off
	v_lshl_add_u64 v[198:199], s[60:61], 0, v[140:141]
	s_mov_b32 m0, s35
	v_lshl_add_u64 v[204:205], s[60:61], 0, v[158:159]
	global_load_lds_dwordx4 v[198:199], off
	s_add_i32 m0, s35, 0x2000
	v_lshl_add_u64 v[214:215], s[10:11], 0, v[162:163]
	global_load_lds_dwordx4 v[204:205], off
	s_mov_b32 m0, s75
	s_nop 0
	global_load_lds_dwordx4 v[214:215], off
	v_lshl_add_u64 v[214:215], s[10:11], 0, v[160:161]
	s_mov_b32 m0, s26
	s_nop 0
	global_load_lds_dwordx4 v[214:215], off
	s_waitcnt vmcnt(8)
	s_waitcnt lgkmcnt(0)
	s_setprio 1
	s_barrier
	v_mfma_f32_16x16x32_bf16 v[60:63], v[128:131], v[172:175], v[60:63]
	v_mfma_f32_16x16x32_bf16 v[56:59], v[136:139], v[172:175], v[56:59]
	v_mfma_f32_16x16x32_bf16 v[44:47], v[128:131], v[184:187], v[44:47]
	v_mfma_f32_16x16x32_bf16 v[40:43], v[136:139], v[184:187], v[40:43]
	v_mfma_f32_16x16x32_bf16 v[28:31], v[128:131], v[192:195], v[28:31]
	v_mfma_f32_16x16x32_bf16 v[24:27], v[136:139], v[192:195], v[24:27]
	v_mfma_f32_16x16x32_bf16 v[12:15], v[128:131], v[206:209], v[12:15]
	v_mfma_f32_16x16x32_bf16 v[8:11], v[136:139], v[206:209], v[8:11]
	v_mfma_f32_16x16x32_bf16 v[60:63], v[132:135], v[180:183], v[60:63]
	v_mfma_f32_16x16x32_bf16 v[56:59], v[142:145], v[180:183], v[56:59]
	v_mfma_f32_16x16x32_bf16 v[44:47], v[132:135], v[188:191], v[44:47]
	v_mfma_f32_16x16x32_bf16 v[40:43], v[142:145], v[188:191], v[40:43]
	v_mfma_f32_16x16x32_bf16 v[28:31], v[132:135], v[200:203], v[28:31]
	v_mfma_f32_16x16x32_bf16 v[24:27], v[142:145], v[200:203], v[24:27]
	v_mfma_f32_16x16x32_bf16 v[12:15], v[132:135], v[210:213], v[12:15]
	v_mfma_f32_16x16x32_bf16 v[8:11], v[142:145], v[210:213], v[8:11]
	v_mfma_f32_16x16x32_bf16 v[52:55], v[146:149], v[172:175], v[52:55]
	v_mfma_f32_16x16x32_bf16 v[48:51], v[154:157], v[172:175], v[48:51]
	v_mfma_f32_16x16x32_bf16 v[36:39], v[146:149], v[184:187], v[36:39]
	v_mfma_f32_16x16x32_bf16 v[32:35], v[154:157], v[184:187], v[32:35]
	v_mfma_f32_16x16x32_bf16 v[20:23], v[146:149], v[192:195], v[20:23]
	v_mfma_f32_16x16x32_bf16 v[16:19], v[154:157], v[192:195], v[16:19]
	v_mfma_f32_16x16x32_bf16 v[4:7], v[146:149], v[206:209], v[4:7]
	v_mfma_f32_16x16x32_bf16 v[0:3], v[154:157], v[206:209], v[0:3]
	v_mfma_f32_16x16x32_bf16 v[52:55], v[150:153], v[180:183], v[52:55]
	v_mfma_f32_16x16x32_bf16 v[48:51], v[168:171], v[180:183], v[48:51]
	v_mfma_f32_16x16x32_bf16 v[36:39], v[150:153], v[188:191], v[36:39]
	v_mfma_f32_16x16x32_bf16 v[32:35], v[168:171], v[188:191], v[32:35]
	v_mfma_f32_16x16x32_bf16 v[20:23], v[150:153], v[200:203], v[20:23]
	v_mfma_f32_16x16x32_bf16 v[16:19], v[168:171], v[200:203], v[16:19]
	v_mfma_f32_16x16x32_bf16 v[4:7], v[150:153], v[210:213], v[4:7]
	v_mfma_f32_16x16x32_bf16 v[0:3], v[168:171], v[210:213], v[0:3]
	s_barrier
	s_setprio 0
	s_add_i32 s35, 0, 0x18000
	s_add_i32 s57, 0, 0x1c000
	v_add_u32_e32 v142, s35, v178
	v_add_u32_e32 v168, s57, v178
	ds_read_b128 v[128:131], v142
	ds_read_b128 v[132:135], v142 offset:1024
	ds_read_b128 v[136:139], v142 offset:2048
	ds_read_b128 v[142:145], v142 offset:3072
	ds_read_b128 v[146:149], v168
	ds_read_b128 v[150:153], v168 offset:1024
	ds_read_b128 v[154:157], v168 offset:2048
	ds_read_b128 v[168:171], v168 offset:3072
	s_add_u32 s10, s10, s48
	s_addc_u32 s11, s11, 0
	s_mov_b32 m0, s27
	v_lshl_add_u64 v[214:215], s[10:11], 0, v[162:163]
	ds_read_b128 v[172:175], v179 offset:32768
	ds_read_b128 v[180:183], v179 offset:33792
	ds_read_b128 v[184:187], v179 offset:34816
	ds_read_b128 v[188:191], v179 offset:35840
	ds_read_b128 v[192:195], v179 offset:36864
	ds_read_b128 v[200:203], v179 offset:37888
	ds_read_b128 v[206:209], v179 offset:38912
	ds_read_b128 v[210:213], v179 offset:39936
	global_load_lds_dwordx4 v[214:215], off
	v_lshl_add_u64 v[214:215], s[10:11], 0, v[160:161]
	s_mov_b32 m0, s15
	s_nop 0
	global_load_lds_dwordx4 v[214:215], off
	s_waitcnt vmcnt(8)
	s_waitcnt lgkmcnt(0)
	s_setprio 1
	s_barrier
	v_mfma_f32_16x16x32_bf16 v[124:127], v[128:131], v[172:175], v[124:127]
	v_mfma_f32_16x16x32_bf16 v[120:123], v[136:139], v[172:175], v[120:123]
	v_mfma_f32_16x16x32_bf16 v[108:111], v[128:131], v[184:187], v[108:111]
	v_mfma_f32_16x16x32_bf16 v[104:107], v[136:139], v[184:187], v[104:107]
	v_mfma_f32_16x16x32_bf16 v[92:95], v[128:131], v[192:195], v[92:95]
	v_mfma_f32_16x16x32_bf16 v[88:91], v[136:139], v[192:195], v[88:91]
	v_mfma_f32_16x16x32_bf16 v[76:79], v[128:131], v[206:209], v[76:79]
	v_mfma_f32_16x16x32_bf16 v[72:75], v[136:139], v[206:209], v[72:75]
	v_mfma_f32_16x16x32_bf16 v[124:127], v[132:135], v[180:183], v[124:127]
	v_mfma_f32_16x16x32_bf16 v[120:123], v[142:145], v[180:183], v[120:123]
	v_mfma_f32_16x16x32_bf16 v[108:111], v[132:135], v[188:191], v[108:111]
	v_mfma_f32_16x16x32_bf16 v[104:107], v[142:145], v[188:191], v[104:107]
	v_mfma_f32_16x16x32_bf16 v[92:95], v[132:135], v[200:203], v[92:95]
	v_mfma_f32_16x16x32_bf16 v[88:91], v[142:145], v[200:203], v[88:91]
	v_mfma_f32_16x16x32_bf16 v[76:79], v[132:135], v[210:213], v[76:79]
	v_mfma_f32_16x16x32_bf16 v[72:75], v[142:145], v[210:213], v[72:75]
	v_mfma_f32_16x16x32_bf16 v[116:119], v[146:149], v[172:175], v[116:119]
	v_mfma_f32_16x16x32_bf16 v[112:115], v[154:157], v[172:175], v[112:115]
	v_mfma_f32_16x16x32_bf16 v[100:103], v[146:149], v[184:187], v[100:103]
	v_mfma_f32_16x16x32_bf16 v[96:99], v[154:157], v[184:187], v[96:99]
	v_mfma_f32_16x16x32_bf16 v[84:87], v[146:149], v[192:195], v[84:87]
	v_mfma_f32_16x16x32_bf16 v[80:83], v[154:157], v[192:195], v[80:83]
	v_mfma_f32_16x16x32_bf16 v[68:71], v[146:149], v[206:209], v[68:71]
	v_mfma_f32_16x16x32_bf16 v[64:67], v[154:157], v[206:209], v[64:67]
	v_mfma_f32_16x16x32_bf16 v[116:119], v[150:153], v[180:183], v[116:119]
	v_mfma_f32_16x16x32_bf16 v[112:115], v[168:171], v[180:183], v[112:115]
	v_mfma_f32_16x16x32_bf16 v[100:103], v[150:153], v[188:191], v[100:103]
	v_mfma_f32_16x16x32_bf16 v[96:99], v[168:171], v[188:191], v[96:99]
	v_mfma_f32_16x16x32_bf16 v[84:87], v[150:153], v[200:203], v[84:87]
	v_mfma_f32_16x16x32_bf16 v[80:83], v[168:171], v[200:203], v[80:83]
	v_mfma_f32_16x16x32_bf16 v[68:71], v[150:153], v[210:213], v[68:71]
	v_mfma_f32_16x16x32_bf16 v[64:67], v[168:171], v[210:213], v[64:67]
	s_barrier
	s_setprio 0
	s_add_i32 s10, s35, s74
	v_lshl_add_u64 v[176:177], v[176:177], 0, s[36:37]
	s_mov_b32 m0, s10
	ds_read_b128 v[172:175], v179 offset:49152
	ds_read_b128 v[180:183], v179 offset:50176
	ds_read_b128 v[184:187], v179 offset:51200
	ds_read_b128 v[188:191], v179 offset:52224
	ds_read_b128 v[192:195], v179 offset:53248
	ds_read_b128 v[200:203], v179 offset:54272
	ds_read_b128 v[206:209], v179 offset:55296
	ds_read_b128 v[210:213], v179 offset:56320
	global_load_lds_dwordx4 v[176:177], off
	v_lshl_add_u64 v[176:177], v[196:197], 0, s[36:37]
	s_add_i32 m0, s10, 0x2000
	s_add_i32 s10, s57, s74
	global_load_lds_dwordx4 v[176:177], off
	v_lshl_add_u64 v[176:177], v[198:199], 0, s[36:37]
	s_mov_b32 m0, s10
	s_nop 0
	global_load_lds_dwordx4 v[176:177], off
	v_lshl_add_u64 v[176:177], v[204:205], 0, s[36:37]
	s_add_i32 m0, s10, 0x2000
	s_nop 0
	global_load_lds_dwordx4 v[176:177], off
	v_lshl_add_u64 v[176:177], s[8:9], 0, v[162:163]
	s_mov_b32 m0, s28
	s_nop 0
	global_load_lds_dwordx4 v[176:177], off
	v_lshl_add_u64 v[176:177], s[8:9], 0, v[160:161]
	s_mov_b32 m0, s29
	s_nop 0
	global_load_lds_dwordx4 v[176:177], off
	s_waitcnt vmcnt(8)
	s_waitcnt lgkmcnt(0)
	s_setprio 1
	s_barrier
	v_mfma_f32_16x16x32_bf16 v[60:63], v[128:131], v[172:175], v[60:63]
	v_mfma_f32_16x16x32_bf16 v[56:59], v[136:139], v[172:175], v[56:59]
	v_mfma_f32_16x16x32_bf16 v[44:47], v[128:131], v[184:187], v[44:47]
	v_mfma_f32_16x16x32_bf16 v[40:43], v[136:139], v[184:187], v[40:43]
	v_mfma_f32_16x16x32_bf16 v[28:31], v[128:131], v[192:195], v[28:31]
	v_mfma_f32_16x16x32_bf16 v[24:27], v[136:139], v[192:195], v[24:27]
	v_mfma_f32_16x16x32_bf16 v[12:15], v[128:131], v[206:209], v[12:15]
	v_mfma_f32_16x16x32_bf16 v[8:11], v[136:139], v[206:209], v[8:11]
	v_mfma_f32_16x16x32_bf16 v[60:63], v[132:135], v[180:183], v[60:63]
	v_mfma_f32_16x16x32_bf16 v[56:59], v[142:145], v[180:183], v[56:59]
	v_mfma_f32_16x16x32_bf16 v[44:47], v[132:135], v[188:191], v[44:47]
	v_mfma_f32_16x16x32_bf16 v[40:43], v[142:145], v[188:191], v[40:43]
	v_mfma_f32_16x16x32_bf16 v[28:31], v[132:135], v[200:203], v[28:31]
	v_mfma_f32_16x16x32_bf16 v[24:27], v[142:145], v[200:203], v[24:27]
	v_mfma_f32_16x16x32_bf16 v[12:15], v[132:135], v[210:213], v[12:15]
	v_mfma_f32_16x16x32_bf16 v[8:11], v[142:145], v[210:213], v[8:11]
	v_mfma_f32_16x16x32_bf16 v[52:55], v[146:149], v[172:175], v[52:55]
	v_mfma_f32_16x16x32_bf16 v[48:51], v[154:157], v[172:175], v[48:51]
	v_mfma_f32_16x16x32_bf16 v[36:39], v[146:149], v[184:187], v[36:39]
	v_mfma_f32_16x16x32_bf16 v[32:35], v[154:157], v[184:187], v[32:35]
	v_mfma_f32_16x16x32_bf16 v[20:23], v[146:149], v[192:195], v[20:23]
	v_mfma_f32_16x16x32_bf16 v[16:19], v[154:157], v[192:195], v[16:19]
	v_mfma_f32_16x16x32_bf16 v[4:7], v[146:149], v[206:209], v[4:7]
	v_mfma_f32_16x16x32_bf16 v[0:3], v[154:157], v[206:209], v[0:3]
	v_mfma_f32_16x16x32_bf16 v[52:55], v[150:153], v[180:183], v[52:55]
	v_mfma_f32_16x16x32_bf16 v[48:51], v[168:171], v[180:183], v[48:51]
	v_mfma_f32_16x16x32_bf16 v[36:39], v[150:153], v[188:191], v[36:39]
	v_mfma_f32_16x16x32_bf16 v[32:35], v[168:171], v[188:191], v[32:35]
	v_mfma_f32_16x16x32_bf16 v[20:23], v[150:153], v[200:203], v[20:23]
	v_mfma_f32_16x16x32_bf16 v[16:19], v[168:171], v[200:203], v[16:19]
	v_mfma_f32_16x16x32_bf16 v[4:7], v[150:153], v[210:213], v[4:7]
	v_mfma_f32_16x16x32_bf16 v[0:3], v[168:171], v[210:213], v[0:3]
	s_barrier
	s_setprio 0
	s_add_u32 s24, s24, 0x100
	s_addc_u32 s38, s38, 0
	s_add_u32 s6, s6, 0x10000
	s_addc_u32 s7, s7, 0
	s_cmp_ge_u32 s56, s12
	s_mov_b32 s8, s56
	s_cbranch_scc0 .LBB0_333
	s_and_b64 vcc, exec, s[52:53]
	s_cbranch_vccz .LBB0_336
	s_barrier

.LBB0_375:
	s_add_i32 s24, s8, 2
	s_add_u32 s35, s6, 0x80
	s_addc_u32 s9, s7, 0
	s_add_i32 s38, 0, 0x10000
	s_cmp_eq_u32 s94, s8
	s_cselect_b32 s9, s43, s9
	s_cselect_b32 s8, s42, s35
	s_cselect_b32 s57, s55, s11
	s_cselect_b32 s56, s54, s10
	s_add_i32 s35, 0, 0x14000
	v_add_u32_e32 v142, s38, v178
	v_add_u32_e32 v168, s35, v178
	ds_read_b128 v[128:131], v142
	ds_read_b128 v[132:135], v142 offset:1024
	ds_read_b128 v[136:139], v142 offset:2048
	ds_read_b128 v[142:145], v142 offset:3072
	ds_read_b128 v[146:149], v168
	ds_read_b128 v[150:153], v168 offset:1024
	ds_read_b128 v[154:157], v168 offset:2048
	ds_read_b128 v[168:171], v168 offset:3072
	v_lshl_add_u64 v[176:177], s[6:7], 0, v[164:165]
	s_add_i32 m0, s15, 0xc000
	ds_read_b128 v[172:175], v179
	ds_read_b128 v[180:183], v179 offset:1024
	ds_read_b128 v[184:187], v179 offset:2048
	ds_read_b128 v[188:191], v179 offset:3072
	ds_read_b128 v[192:195], v179 offset:4096
	ds_read_b128 v[200:203], v179 offset:5120
	ds_read_b128 v[206:209], v179 offset:6144
	ds_read_b128 v[210:213], v179 offset:7168
	global_load_lds_dwordx4 v[176:177], off
	v_lshl_add_u64 v[176:177], s[6:7], 0, v[166:167]
	s_add_i32 m0, s15, 0xe000
	s_nop 0
	global_load_lds_dwordx4 v[176:177], off
	s_waitcnt vmcnt(8)
	s_waitcnt lgkmcnt(0)
	s_setprio 1
	s_barrier
	v_mfma_f32_16x16x32_bf16 v[124:127], v[128:131], v[172:175], v[124:127]
	v_mfma_f32_16x16x32_bf16 v[120:123], v[136:139], v[172:175], v[120:123]
	v_mfma_f32_16x16x32_bf16 v[108:111], v[128:131], v[184:187], v[108:111]
	v_mfma_f32_16x16x32_bf16 v[104:107], v[136:139], v[184:187], v[104:107]
	v_mfma_f32_16x16x32_bf16 v[92:95], v[128:131], v[192:195], v[92:95]
	v_mfma_f32_16x16x32_bf16 v[88:91], v[136:139], v[192:195], v[88:91]
	v_mfma_f32_16x16x32_bf16 v[76:79], v[128:131], v[206:209], v[76:79]
	v_mfma_f32_16x16x32_bf16 v[72:75], v[136:139], v[206:209], v[72:75]
	v_mfma_f32_16x16x32_bf16 v[124:127], v[132:135], v[180:183], v[124:127]
	v_mfma_f32_16x16x32_bf16 v[120:123], v[142:145], v[180:183], v[120:123]
	v_mfma_f32_16x16x32_bf16 v[108:111], v[132:135], v[188:191], v[108:111]
	v_mfma_f32_16x16x32_bf16 v[104:107], v[142:145], v[188:191], v[104:107]
	v_mfma_f32_16x16x32_bf16 v[92:95], v[132:135], v[200:203], v[92:95]
	v_mfma_f32_16x16x32_bf16 v[88:91], v[142:145], v[200:203], v[88:91]
	v_mfma_f32_16x16x32_bf16 v[76:79], v[132:135], v[210:213], v[76:79]
	v_mfma_f32_16x16x32_bf16 v[72:75], v[142:145], v[210:213], v[72:75]
	v_mfma_f32_16x16x32_bf16 v[116:119], v[146:149], v[172:175], v[116:119]
	v_mfma_f32_16x16x32_bf16 v[112:115], v[154:157], v[172:175], v[112:115]
	v_mfma_f32_16x16x32_bf16 v[100:103], v[146:149], v[184:187], v[100:103]
	v_mfma_f32_16x16x32_bf16 v[96:99], v[154:157], v[184:187], v[96:99]
	v_mfma_f32_16x16x32_bf16 v[84:87], v[146:149], v[192:195], v[84:87]
	v_mfma_f32_16x16x32_bf16 v[80:83], v[154:157], v[192:195], v[80:83]
	v_mfma_f32_16x16x32_bf16 v[68:71], v[146:149], v[206:209], v[68:71]
	v_mfma_f32_16x16x32_bf16 v[64:67], v[154:157], v[206:209], v[64:67]
	v_mfma_f32_16x16x32_bf16 v[116:119], v[150:153], v[180:183], v[116:119]
	v_mfma_f32_16x16x32_bf16 v[112:115], v[168:171], v[180:183], v[112:115]
	v_mfma_f32_16x16x32_bf16 v[100:103], v[150:153], v[188:191], v[100:103]
	v_mfma_f32_16x16x32_bf16 v[96:99], v[168:171], v[188:191], v[96:99]
	v_mfma_f32_16x16x32_bf16 v[84:87], v[150:153], v[200:203], v[84:87]
	v_mfma_f32_16x16x32_bf16 v[80:83], v[168:171], v[200:203], v[80:83]
	v_mfma_f32_16x16x32_bf16 v[68:71], v[150:153], v[210:213], v[68:71]
	v_mfma_f32_16x16x32_bf16 v[64:67], v[168:171], v[210:213], v[64:67]
	s_barrier
	s_setprio 0
	s_add_i32 s38, s38, s75
	v_lshl_add_u64 v[176:177], s[56:57], 0, v[140:141]
	s_mov_b32 m0, s38
	ds_read_b128 v[172:175], v179 offset:16384
	ds_read_b128 v[180:183], v179 offset:17408
	ds_read_b128 v[184:187], v179 offset:18432
	ds_read_b128 v[188:191], v179 offset:19456
	ds_read_b128 v[192:195], v179 offset:20480
	ds_read_b128 v[200:203], v179 offset:21504
	ds_read_b128 v[206:209], v179 offset:22528
	ds_read_b128 v[210:213], v179 offset:23552
	global_load_lds_dwordx4 v[176:177], off
	s_add_i32 m0, s38, 0x2000
	v_lshl_add_u64 v[196:197], s[56:57], 0, v[158:159]
	s_add_u32 s56, s56, s13
	s_addc_u32 s57, s57, 0
	s_add_i32 s35, s35, s75
	global_load_lds_dwordx4 v[196:197], off
	v_lshl_add_u64 v[198:199], s[56:57], 0, v[140:141]
	s_mov_b32 m0, s35
	v_lshl_add_u64 v[204:205], s[56:57], 0, v[158:159]
	global_load_lds_dwordx4 v[198:199], off
	s_add_i32 m0, s35, 0x2000
	v_lshl_add_u64 v[214:215], s[8:9], 0, v[162:163]
	global_load_lds_dwordx4 v[204:205], off
	s_mov_b32 m0, s15
	v_lshl_add_u64 v[216:217], s[8:9], 0, v[160:161]
	global_load_lds_dwordx4 v[214:215], off
	s_mov_b32 m0, s26
	s_nop 0
	global_load_lds_dwordx4 v[216:217], off
	s_waitcnt vmcnt(8)
	s_waitcnt lgkmcnt(0)
	s_setprio 1
	s_barrier
	v_mfma_f32_16x16x32_bf16 v[60:63], v[128:131], v[172:175], v[60:63]
	v_mfma_f32_16x16x32_bf16 v[56:59], v[136:139], v[172:175], v[56:59]
	v_mfma_f32_16x16x32_bf16 v[44:47], v[128:131], v[184:187], v[44:47]
	v_mfma_f32_16x16x32_bf16 v[40:43], v[136:139], v[184:187], v[40:43]
	v_mfma_f32_16x16x32_bf16 v[28:31], v[128:131], v[192:195], v[28:31]
	v_mfma_f32_16x16x32_bf16 v[24:27], v[136:139], v[192:195], v[24:27]
	v_mfma_f32_16x16x32_bf16 v[12:15], v[128:131], v[206:209], v[12:15]
	v_mfma_f32_16x16x32_bf16 v[8:11], v[136:139], v[206:209], v[8:11]
	v_mfma_f32_16x16x32_bf16 v[60:63], v[132:135], v[180:183], v[60:63]
	v_mfma_f32_16x16x32_bf16 v[56:59], v[142:145], v[180:183], v[56:59]
	v_mfma_f32_16x16x32_bf16 v[44:47], v[132:135], v[188:191], v[44:47]
	v_mfma_f32_16x16x32_bf16 v[40:43], v[142:145], v[188:191], v[40:43]
	v_mfma_f32_16x16x32_bf16 v[28:31], v[132:135], v[200:203], v[28:31]
	v_mfma_f32_16x16x32_bf16 v[24:27], v[142:145], v[200:203], v[24:27]
	v_mfma_f32_16x16x32_bf16 v[12:15], v[132:135], v[210:213], v[12:15]
	v_mfma_f32_16x16x32_bf16 v[8:11], v[142:145], v[210:213], v[8:11]
	v_mfma_f32_16x16x32_bf16 v[52:55], v[146:149], v[172:175], v[52:55]
	v_mfma_f32_16x16x32_bf16 v[48:51], v[154:157], v[172:175], v[48:51]
	v_mfma_f32_16x16x32_bf16 v[36:39], v[146:149], v[184:187], v[36:39]
	v_mfma_f32_16x16x32_bf16 v[32:35], v[154:157], v[184:187], v[32:35]
	v_mfma_f32_16x16x32_bf16 v[20:23], v[146:149], v[192:195], v[20:23]
	v_mfma_f32_16x16x32_bf16 v[16:19], v[154:157], v[192:195], v[16:19]
	v_mfma_f32_16x16x32_bf16 v[4:7], v[146:149], v[206:209], v[4:7]
	v_mfma_f32_16x16x32_bf16 v[0:3], v[154:157], v[206:209], v[0:3]
	v_mfma_f32_16x16x32_bf16 v[52:55], v[150:153], v[180:183], v[52:55]
	v_mfma_f32_16x16x32_bf16 v[48:51], v[168:171], v[180:183], v[48:51]
	v_mfma_f32_16x16x32_bf16 v[36:39], v[150:153], v[188:191], v[36:39]
	v_mfma_f32_16x16x32_bf16 v[32:35], v[168:171], v[188:191], v[32:35]
	v_mfma_f32_16x16x32_bf16 v[20:23], v[150:153], v[200:203], v[20:23]
	v_mfma_f32_16x16x32_bf16 v[16:19], v[168:171], v[200:203], v[16:19]
	v_mfma_f32_16x16x32_bf16 v[4:7], v[150:153], v[210:213], v[4:7]
	v_mfma_f32_16x16x32_bf16 v[0:3], v[168:171], v[210:213], v[0:3]
	s_barrier
	s_setprio 0
	s_add_i32 s35, 0, 0x18000
	s_add_i32 s38, 0, 0x1c000
	v_add_u32_e32 v142, s35, v178
	v_add_u32_e32 v168, s38, v178
	ds_read_b128 v[128:131], v142
	ds_read_b128 v[132:135], v142 offset:1024
	ds_read_b128 v[136:139], v142 offset:2048
	ds_read_b128 v[142:145], v142 offset:3072
	ds_read_b128 v[146:149], v168
	ds_read_b128 v[150:153], v168 offset:1024
	ds_read_b128 v[154:157], v168 offset:2048
	ds_read_b128 v[168:171], v168 offset:3072
	s_add_u32 s8, s8, s48
	s_addc_u32 s9, s9, 0
	s_mov_b32 m0, s27
	v_lshl_add_u64 v[218:219], s[8:9], 0, v[162:163]
	ds_read_b128 v[172:175], v179 offset:32768
	ds_read_b128 v[180:183], v179 offset:33792
	ds_read_b128 v[184:187], v179 offset:34816
	ds_read_b128 v[188:191], v179 offset:35840
	ds_read_b128 v[192:195], v179 offset:36864
	ds_read_b128 v[200:203], v179 offset:37888
	ds_read_b128 v[206:209], v179 offset:38912
	ds_read_b128 v[210:213], v179 offset:39936
	global_load_lds_dwordx4 v[218:219], off
	v_lshl_add_u64 v[218:219], s[8:9], 0, v[160:161]
	s_mov_b32 m0, s28
	s_nop 0
	global_load_lds_dwordx4 v[218:219], off
	s_waitcnt vmcnt(8)
	s_waitcnt lgkmcnt(0)
	s_setprio 1
	s_barrier
	v_mfma_f32_16x16x32_bf16 v[124:127], v[128:131], v[172:175], v[124:127]
	v_mfma_f32_16x16x32_bf16 v[120:123], v[136:139], v[172:175], v[120:123]
	v_mfma_f32_16x16x32_bf16 v[108:111], v[128:131], v[184:187], v[108:111]
	v_mfma_f32_16x16x32_bf16 v[104:107], v[136:139], v[184:187], v[104:107]
	v_mfma_f32_16x16x32_bf16 v[92:95], v[128:131], v[192:195], v[92:95]
	v_mfma_f32_16x16x32_bf16 v[88:91], v[136:139], v[192:195], v[88:91]
	v_mfma_f32_16x16x32_bf16 v[76:79], v[128:131], v[206:209], v[76:79]
	v_mfma_f32_16x16x32_bf16 v[72:75], v[136:139], v[206:209], v[72:75]
	v_mfma_f32_16x16x32_bf16 v[124:127], v[132:135], v[180:183], v[124:127]
	v_mfma_f32_16x16x32_bf16 v[120:123], v[142:145], v[180:183], v[120:123]
	v_mfma_f32_16x16x32_bf16 v[108:111], v[132:135], v[188:191], v[108:111]
	v_mfma_f32_16x16x32_bf16 v[104:107], v[142:145], v[188:191], v[104:107]
	v_mfma_f32_16x16x32_bf16 v[92:95], v[132:135], v[200:203], v[92:95]
	v_mfma_f32_16x16x32_bf16 v[88:91], v[142:145], v[200:203], v[88:91]
	v_mfma_f32_16x16x32_bf16 v[76:79], v[132:135], v[210:213], v[76:79]
	v_mfma_f32_16x16x32_bf16 v[72:75], v[142:145], v[210:213], v[72:75]
	v_mfma_f32_16x16x32_bf16 v[116:119], v[146:149], v[172:175], v[116:119]
	v_mfma_f32_16x16x32_bf16 v[112:115], v[154:157], v[172:175], v[112:115]
	v_mfma_f32_16x16x32_bf16 v[100:103], v[146:149], v[184:187], v[100:103]
	v_mfma_f32_16x16x32_bf16 v[96:99], v[154:157], v[184:187], v[96:99]
	v_mfma_f32_16x16x32_bf16 v[84:87], v[146:149], v[192:195], v[84:87]
	v_mfma_f32_16x16x32_bf16 v[80:83], v[154:157], v[192:195], v[80:83]
	v_mfma_f32_16x16x32_bf16 v[68:71], v[146:149], v[206:209], v[68:71]
	v_mfma_f32_16x16x32_bf16 v[64:67], v[154:157], v[206:209], v[64:67]
	v_mfma_f32_16x16x32_bf16 v[116:119], v[150:153], v[180:183], v[116:119]
	v_mfma_f32_16x16x32_bf16 v[112:115], v[168:171], v[180:183], v[112:115]
	v_mfma_f32_16x16x32_bf16 v[100:103], v[150:153], v[188:191], v[100:103]
	v_mfma_f32_16x16x32_bf16 v[96:99], v[168:171], v[188:191], v[96:99]
	v_mfma_f32_16x16x32_bf16 v[84:87], v[150:153], v[200:203], v[84:87]
	v_mfma_f32_16x16x32_bf16 v[80:83], v[168:171], v[200:203], v[80:83]
	v_mfma_f32_16x16x32_bf16 v[68:71], v[150:153], v[210:213], v[68:71]
	v_mfma_f32_16x16x32_bf16 v[64:67], v[168:171], v[210:213], v[64:67]
	s_barrier
	s_setprio 0
	s_add_i32 s8, s35, s75
	v_lshl_add_u64 v[176:177], v[176:177], 0, s[36:37]
	s_mov_b32 m0, s8
	ds_read_b128 v[172:175], v179 offset:49152
	ds_read_b128 v[180:183], v179 offset:50176
	ds_read_b128 v[184:187], v179 offset:51200
	ds_read_b128 v[188:191], v179 offset:52224
	ds_read_b128 v[192:195], v179 offset:53248
	ds_read_b128 v[200:203], v179 offset:54272
	ds_read_b128 v[206:209], v179 offset:55296
	ds_read_b128 v[210:213], v179 offset:56320
	global_load_lds_dwordx4 v[176:177], off
	v_lshl_add_u64 v[176:177], v[196:197], 0, s[36:37]
	s_add_i32 m0, s8, 0x2000
	s_add_i32 s8, s38, s75
	global_load_lds_dwordx4 v[176:177], off
	v_lshl_add_u64 v[176:177], v[198:199], 0, s[36:37]
	s_mov_b32 m0, s8
	s_nop 0
	global_load_lds_dwordx4 v[176:177], off
	v_lshl_add_u64 v[176:177], v[204:205], 0, s[36:37]
	s_add_i32 m0, s8, 0x2000
	s_nop 0
	global_load_lds_dwordx4 v[176:177], off
	v_lshl_add_u64 v[176:177], v[214:215], 0, s[36:37]
	s_mov_b32 m0, s29
	s_nop 0
	global_load_lds_dwordx4 v[176:177], off
	v_lshl_add_u64 v[176:177], v[216:217], 0, s[36:37]
	s_mov_b32 m0, s58
	s_nop 0
	global_load_lds_dwordx4 v[176:177], off
	s_waitcnt vmcnt(8)
	s_waitcnt lgkmcnt(0)
	s_setprio 1
	s_barrier
	v_mfma_f32_16x16x32_bf16 v[60:63], v[128:131], v[172:175], v[60:63]
	v_mfma_f32_16x16x32_bf16 v[56:59], v[136:139], v[172:175], v[56:59]
	v_mfma_f32_16x16x32_bf16 v[44:47], v[128:131], v[184:187], v[44:47]
	v_mfma_f32_16x16x32_bf16 v[40:43], v[136:139], v[184:187], v[40:43]
	v_mfma_f32_16x16x32_bf16 v[28:31], v[128:131], v[192:195], v[28:31]
	v_mfma_f32_16x16x32_bf16 v[24:27], v[136:139], v[192:195], v[24:27]
	v_mfma_f32_16x16x32_bf16 v[12:15], v[128:131], v[206:209], v[12:15]
	v_mfma_f32_16x16x32_bf16 v[8:11], v[136:139], v[206:209], v[8:11]
	v_mfma_f32_16x16x32_bf16 v[60:63], v[132:135], v[180:183], v[60:63]
	v_mfma_f32_16x16x32_bf16 v[56:59], v[142:145], v[180:183], v[56:59]
	v_mfma_f32_16x16x32_bf16 v[44:47], v[132:135], v[188:191], v[44:47]
	v_mfma_f32_16x16x32_bf16 v[40:43], v[142:145], v[188:191], v[40:43]
	v_mfma_f32_16x16x32_bf16 v[28:31], v[132:135], v[200:203], v[28:31]
	v_mfma_f32_16x16x32_bf16 v[24:27], v[142:145], v[200:203], v[24:27]
	v_mfma_f32_16x16x32_bf16 v[12:15], v[132:135], v[210:213], v[12:15]
	v_mfma_f32_16x16x32_bf16 v[8:11], v[142:145], v[210:213], v[8:11]
	v_mfma_f32_16x16x32_bf16 v[52:55], v[146:149], v[172:175], v[52:55]
	v_mfma_f32_16x16x32_bf16 v[48:51], v[154:157], v[172:175], v[48:51]
	v_mfma_f32_16x16x32_bf16 v[36:39], v[146:149], v[184:187], v[36:39]
	v_mfma_f32_16x16x32_bf16 v[32:35], v[154:157], v[184:187], v[32:35]
	v_mfma_f32_16x16x32_bf16 v[20:23], v[146:149], v[192:195], v[20:23]
	v_mfma_f32_16x16x32_bf16 v[16:19], v[154:157], v[192:195], v[16:19]
	v_mfma_f32_16x16x32_bf16 v[4:7], v[146:149], v[206:209], v[4:7]
	v_mfma_f32_16x16x32_bf16 v[0:3], v[154:157], v[206:209], v[0:3]
	v_mfma_f32_16x16x32_bf16 v[52:55], v[150:153], v[180:183], v[52:55]
	v_mfma_f32_16x16x32_bf16 v[48:51], v[168:171], v[180:183], v[48:51]
	v_mfma_f32_16x16x32_bf16 v[36:39], v[150:153], v[188:191], v[36:39]
	v_mfma_f32_16x16x32_bf16 v[32:35], v[168:171], v[188:191], v[32:35]
	v_mfma_f32_16x16x32_bf16 v[20:23], v[150:153], v[200:203], v[20:23]
	v_mfma_f32_16x16x32_bf16 v[16:19], v[168:171], v[200:203], v[16:19]
	v_mfma_f32_16x16x32_bf16 v[4:7], v[150:153], v[210:213], v[4:7]
	v_mfma_f32_16x16x32_bf16 v[0:3], v[168:171], v[210:213], v[0:3]
	s_barrier
	s_setprio 0
	s_add_u32 s6, s6, 0x100
	s_addc_u32 s7, s7, 0
	s_add_u32 s10, s10, 0x100
	s_addc_u32 s11, s11, 0
	s_cmp_ge_u32 s24, s12
	s_mov_b32 s8, s24
	s_cbranch_scc0 .LBB0_375
	s_and_b64 vcc, exec, s[52:53]
	s_cbranch_vccz .LBB0_378
	s_barrier

.LBB0_417:
	s_lshl_b64 s[10:11], s[52:53], 17
	s_add_u32 s56, s12, s10
	s_addc_u32 s57, s13, s11
	s_and_b64 s[10:11], s[40:41], exec
	s_cselect_b32 s11, s57, s9
	s_cselect_b32 s10, s56, s8
	s_add_i32 s55, 0, 0x10000
	s_add_i32 s38, 0, 0x14000
	v_add_u32_e32 v212, s55, v174
	v_add_u32_e32 v213, s38, v174
	ds_read_b128 v[0:3], v212
	ds_read_b128 v[4:7], v212 offset:1024
	ds_read_b128 v[8:11], v212 offset:2048
	ds_read_b128 v[12:15], v212 offset:3072
	ds_read_b128 v[16:19], v213
	ds_read_b128 v[20:23], v213 offset:1024
	ds_read_b128 v[24:27], v213 offset:2048
	ds_read_b128 v[28:31], v213 offset:3072
	s_add_u32 s60, s6, 0x40080
	s_addc_u32 s61, s7, 0
	s_add_i32 s59, s26, 0xc000
	v_lshl_add_u64 v[64:65], s[60:61], 0, v[162:163]
	s_mov_b32 m0, s59
	s_add_i32 s24, s26, 0xe000
	ds_read_b128 v[32:35], v175
	ds_read_b128 v[36:39], v175 offset:1024
	ds_read_b128 v[40:43], v175 offset:2048
	ds_read_b128 v[44:47], v175 offset:3072
	ds_read_b128 v[48:51], v175 offset:4096
	ds_read_b128 v[52:55], v175 offset:5120
	ds_read_b128 v[56:59], v175 offset:6144
	ds_read_b128 v[60:63], v175 offset:7168
	global_load_lds_dwordx4 v[64:65], off
	v_lshl_add_u64 v[64:65], s[60:61], 0, v[160:161]
	s_mov_b32 m0, s24
	s_nop 0
	global_load_lds_dwordx4 v[64:65], off
	s_waitcnt vmcnt(8)
	s_waitcnt lgkmcnt(0)
	s_setprio 1
	s_barrier
	v_mfma_f32_16x16x32_bf16 v[64:67], v[0:3], v[32:35], 0
	v_mfma_f32_16x16x32_bf16 v[68:71], v[8:11], v[32:35], 0
	v_mfma_f32_16x16x32_bf16 v[72:75], v[0:3], v[40:43], 0
	v_mfma_f32_16x16x32_bf16 v[76:79], v[8:11], v[40:43], 0
	v_mfma_f32_16x16x32_bf16 v[80:83], v[0:3], v[48:51], 0
	v_mfma_f32_16x16x32_bf16 v[84:87], v[8:11], v[48:51], 0
	v_mfma_f32_16x16x32_bf16 v[88:91], v[0:3], v[56:59], 0
	v_mfma_f32_16x16x32_bf16 v[92:95], v[8:11], v[56:59], 0
	v_mfma_f32_16x16x32_bf16 v[64:67], v[4:7], v[36:39], v[64:67]
	v_mfma_f32_16x16x32_bf16 v[68:71], v[12:15], v[36:39], v[68:71]
	v_mfma_f32_16x16x32_bf16 v[72:75], v[4:7], v[44:47], v[72:75]
	v_mfma_f32_16x16x32_bf16 v[76:79], v[12:15], v[44:47], v[76:79]
	v_mfma_f32_16x16x32_bf16 v[80:83], v[4:7], v[52:55], v[80:83]
	v_mfma_f32_16x16x32_bf16 v[84:87], v[12:15], v[52:55], v[84:87]
	v_mfma_f32_16x16x32_bf16 v[88:91], v[4:7], v[60:63], v[88:91]
	v_mfma_f32_16x16x32_bf16 v[92:95], v[12:15], v[60:63], v[92:95]
	v_mfma_f32_16x16x32_bf16 v[96:99], v[16:19], v[32:35], 0
	v_mfma_f32_16x16x32_bf16 v[32:35], v[24:27], v[32:35], 0
	v_mfma_f32_16x16x32_bf16 v[96:99], v[20:23], v[36:39], v[96:99]
	v_mfma_f32_16x16x32_bf16 v[32:35], v[28:31], v[36:39], v[32:35]
	v_mfma_f32_16x16x32_bf16 v[36:39], v[16:19], v[40:43], 0
	v_mfma_f32_16x16x32_bf16 v[40:43], v[24:27], v[40:43], 0
	v_mfma_f32_16x16x32_bf16 v[36:39], v[20:23], v[44:47], v[36:39]
	v_mfma_f32_16x16x32_bf16 v[40:43], v[28:31], v[44:47], v[40:43]
	v_mfma_f32_16x16x32_bf16 v[44:47], v[16:19], v[48:51], 0
	v_mfma_f32_16x16x32_bf16 v[48:51], v[24:27], v[48:51], 0
	v_mfma_f32_16x16x32_bf16 v[44:47], v[20:23], v[52:55], v[44:47]
	v_mfma_f32_16x16x32_bf16 v[48:51], v[28:31], v[52:55], v[48:51]
	v_mfma_f32_16x16x32_bf16 v[52:55], v[16:19], v[56:59], 0
	v_mfma_f32_16x16x32_bf16 v[56:59], v[24:27], v[56:59], 0
	v_mfma_f32_16x16x32_bf16 v[52:55], v[20:23], v[60:63], v[52:55]
	v_mfma_f32_16x16x32_bf16 v[56:59], v[28:31], v[60:63], v[56:59]
	s_barrier
	s_setprio 0
	s_add_i32 s55, s55, s15
	v_lshl_add_u64 v[172:173], s[8:9], 0, v[140:141]
	s_mov_b64 s[2:3], 0x100
	s_add_i32 s35, s55, 0x2000
	v_lshl_add_u64 v[128:129], v[172:173], 0, s[2:3]
	s_mov_b32 m0, s55
	v_lshl_add_u64 v[196:197], s[8:9], 0, v[158:159]
	s_add_u32 s60, s8, 0x10100
	ds_read_b128 v[60:63], v175 offset:16384
	ds_read_b128 v[100:103], v175 offset:17408
	ds_read_b128 v[104:107], v175 offset:18432
	ds_read_b128 v[108:111], v175 offset:19456
	ds_read_b128 v[112:115], v175 offset:20480
	ds_read_b128 v[116:119], v175 offset:21504
	ds_read_b128 v[120:123], v175 offset:22528
	ds_read_b128 v[124:127], v175 offset:23552
	global_load_lds_dwordx4 v[128:129], off
	v_lshl_add_u64 v[128:129], v[196:197], 0, s[2:3]
	s_mov_b32 m0, s35
	s_addc_u32 s61, s9, 0
	s_add_i32 s38, s38, s15
	global_load_lds_dwordx4 v[128:129], off
	v_lshl_add_u64 v[128:129], s[60:61], 0, v[140:141]
	s_mov_b32 m0, s38
	s_add_i32 s53, s38, 0x2000
	global_load_lds_dwordx4 v[128:129], off
	v_lshl_add_u64 v[128:129], s[60:61], 0, v[158:159]
	s_mov_b32 m0, s53
	v_lshl_add_u64 v[198:199], s[6:7], 0, v[162:163]
	global_load_lds_dwordx4 v[128:129], off
	v_lshl_add_u64 v[128:129], v[198:199], 0, s[2:3]
	s_mov_b32 m0, s26
	v_lshl_add_u64 v[204:205], s[6:7], 0, v[160:161]
	global_load_lds_dwordx4 v[128:129], off
	v_lshl_add_u64 v[128:129], v[204:205], 0, s[2:3]
	s_mov_b32 m0, s27
	s_nop 0
	global_load_lds_dwordx4 v[128:129], off
	s_waitcnt vmcnt(8)
	s_waitcnt lgkmcnt(0)
	s_setprio 1
	s_barrier
	v_mfma_f32_16x16x32_bf16 v[128:131], v[0:3], v[60:63], 0
	v_mfma_f32_16x16x32_bf16 v[136:139], v[0:3], v[104:107], 0
	v_mfma_f32_16x16x32_bf16 v[146:149], v[0:3], v[112:115], 0
	v_mfma_f32_16x16x32_bf16 v[0:3], v[0:3], v[120:123], 0
	v_mfma_f32_16x16x32_bf16 v[128:131], v[4:7], v[100:103], v[128:131]
	v_mfma_f32_16x16x32_bf16 v[132:135], v[8:11], v[60:63], 0
	v_mfma_f32_16x16x32_bf16 v[136:139], v[4:7], v[108:111], v[136:139]
	v_mfma_f32_16x16x32_bf16 v[146:149], v[4:7], v[116:119], v[146:149]
	v_mfma_f32_16x16x32_bf16 v[0:3], v[4:7], v[124:127], v[0:3]
	v_mfma_f32_16x16x32_bf16 v[4:7], v[8:11], v[120:123], 0
	v_mfma_f32_16x16x32_bf16 v[132:135], v[12:15], v[100:103], v[132:135]
	v_mfma_f32_16x16x32_bf16 v[142:145], v[8:11], v[104:107], 0
	v_mfma_f32_16x16x32_bf16 v[150:153], v[8:11], v[112:115], 0
	v_mfma_f32_16x16x32_bf16 v[4:7], v[12:15], v[124:127], v[4:7]
	v_mfma_f32_16x16x32_bf16 v[142:145], v[12:15], v[108:111], v[142:145]
	v_mfma_f32_16x16x32_bf16 v[150:153], v[12:15], v[116:119], v[150:153]
	v_mfma_f32_16x16x32_bf16 v[8:11], v[16:19], v[60:63], 0
	v_mfma_f32_16x16x32_bf16 v[12:15], v[24:27], v[60:63], 0
	v_mfma_f32_16x16x32_bf16 v[8:11], v[20:23], v[100:103], v[8:11]
	v_mfma_f32_16x16x32_bf16 v[12:15], v[28:31], v[100:103], v[12:15]
	v_mfma_f32_16x16x32_bf16 v[60:63], v[16:19], v[104:107], 0
	v_mfma_f32_16x16x32_bf16 v[100:103], v[24:27], v[104:107], 0
	v_mfma_f32_16x16x32_bf16 v[104:107], v[16:19], v[112:115], 0
	v_mfma_f32_16x16x32_bf16 v[16:19], v[16:19], v[120:123], 0
	v_mfma_f32_16x16x32_bf16 v[60:63], v[20:23], v[108:111], v[60:63]
	v_mfma_f32_16x16x32_bf16 v[100:103], v[28:31], v[108:111], v[100:103]
	v_mfma_f32_16x16x32_bf16 v[104:107], v[20:23], v[116:119], v[104:107]
	v_mfma_f32_16x16x32_bf16 v[108:111], v[24:27], v[112:115], 0
	v_mfma_f32_16x16x32_bf16 v[16:19], v[20:23], v[124:127], v[16:19]
	v_mfma_f32_16x16x32_bf16 v[20:23], v[24:27], v[120:123], 0
	v_mfma_f32_16x16x32_bf16 v[108:111], v[28:31], v[116:119], v[108:111]
	v_mfma_f32_16x16x32_bf16 v[20:23], v[28:31], v[124:127], v[20:23]
	s_barrier
	s_setprio 0
	s_add_i32 s58, 0, 0x18000
	s_add_i32 s76, 0, 0x1c000
	v_add_u32_e32 v222, s58, v174
	v_add_u32_e32 v223, s76, v174
	ds_read_b128 v[24:27], v222
	ds_read_b128 v[28:31], v222 offset:1024
	ds_read_b128 v[112:115], v222 offset:2048
	ds_read_b128 v[116:119], v222 offset:3072
	ds_read_b128 v[120:123], v223
	ds_read_b128 v[124:127], v223 offset:1024
	ds_read_b128 v[154:157], v223 offset:2048
	ds_read_b128 v[164:167], v223 offset:3072
	s_add_u32 s60, s6, 0x40100
	s_addc_u32 s61, s7, 0
	s_mov_b32 m0, s28
	v_lshl_add_u64 v[210:211], s[60:61], 0, v[162:163]
	ds_read_b128 v[168:171], v175 offset:32768
	ds_read_b128 v[176:179], v175 offset:33792
	ds_read_b128 v[180:183], v175 offset:34816
	ds_read_b128 v[184:187], v175 offset:35840
	ds_read_b128 v[188:191], v175 offset:36864
	ds_read_b128 v[192:195], v175 offset:37888
	ds_read_b128 v[200:203], v175 offset:38912
	ds_read_b128 v[206:209], v175 offset:39936
	global_load_lds_dwordx4 v[210:211], off
	v_lshl_add_u64 v[210:211], s[60:61], 0, v[160:161]
	s_mov_b32 m0, s29
	s_nop 0
	global_load_lds_dwordx4 v[210:211], off
	s_waitcnt vmcnt(8)
	s_waitcnt lgkmcnt(0)
	s_setprio 1
	s_barrier
	v_mfma_f32_16x16x32_bf16 v[64:67], v[24:27], v[168:171], v[64:67]
	v_mfma_f32_16x16x32_bf16 v[68:71], v[112:115], v[168:171], v[68:71]
	v_mfma_f32_16x16x32_bf16 v[72:75], v[24:27], v[180:183], v[72:75]
	v_mfma_f32_16x16x32_bf16 v[76:79], v[112:115], v[180:183], v[76:79]
	v_mfma_f32_16x16x32_bf16 v[80:83], v[24:27], v[188:191], v[80:83]
	v_mfma_f32_16x16x32_bf16 v[84:87], v[112:115], v[188:191], v[84:87]
	v_mfma_f32_16x16x32_bf16 v[88:91], v[24:27], v[200:203], v[88:91]
	v_mfma_f32_16x16x32_bf16 v[92:95], v[112:115], v[200:203], v[92:95]
	v_mfma_f32_16x16x32_bf16 v[64:67], v[28:31], v[176:179], v[64:67]
	v_mfma_f32_16x16x32_bf16 v[68:71], v[116:119], v[176:179], v[68:71]
	v_mfma_f32_16x16x32_bf16 v[72:75], v[28:31], v[184:187], v[72:75]
	v_mfma_f32_16x16x32_bf16 v[76:79], v[116:119], v[184:187], v[76:79]
	v_mfma_f32_16x16x32_bf16 v[80:83], v[28:31], v[192:195], v[80:83]
	v_mfma_f32_16x16x32_bf16 v[84:87], v[116:119], v[192:195], v[84:87]
	v_mfma_f32_16x16x32_bf16 v[88:91], v[28:31], v[206:209], v[88:91]
	v_mfma_f32_16x16x32_bf16 v[92:95], v[116:119], v[206:209], v[92:95]
	v_mfma_f32_16x16x32_bf16 v[96:99], v[120:123], v[168:171], v[96:99]
	v_mfma_f32_16x16x32_bf16 v[32:35], v[154:157], v[168:171], v[32:35]
	v_mfma_f32_16x16x32_bf16 v[36:39], v[120:123], v[180:183], v[36:39]
	v_mfma_f32_16x16x32_bf16 v[40:43], v[154:157], v[180:183], v[40:43]
	v_mfma_f32_16x16x32_bf16 v[44:47], v[120:123], v[188:191], v[44:47]
	v_mfma_f32_16x16x32_bf16 v[48:51], v[154:157], v[188:191], v[48:51]
	v_mfma_f32_16x16x32_bf16 v[52:55], v[120:123], v[200:203], v[52:55]
	v_mfma_f32_16x16x32_bf16 v[56:59], v[154:157], v[200:203], v[56:59]
	v_mfma_f32_16x16x32_bf16 v[96:99], v[124:127], v[176:179], v[96:99]
	v_mfma_f32_16x16x32_bf16 v[32:35], v[164:167], v[176:179], v[32:35]
	v_mfma_f32_16x16x32_bf16 v[36:39], v[124:127], v[184:187], v[36:39]
	v_mfma_f32_16x16x32_bf16 v[40:43], v[164:167], v[184:187], v[40:43]
	v_mfma_f32_16x16x32_bf16 v[44:47], v[124:127], v[192:195], v[44:47]
	v_mfma_f32_16x16x32_bf16 v[48:51], v[164:167], v[192:195], v[48:51]
	v_mfma_f32_16x16x32_bf16 v[52:55], v[124:127], v[206:209], v[52:55]
	v_mfma_f32_16x16x32_bf16 v[56:59], v[164:167], v[206:209], v[56:59]
	s_barrier
	s_setprio 0
	s_add_i32 s60, s58, s15
	s_mov_b64 s[2:3], 0x180
	s_add_i32 s58, s60, 0x2000
	v_lshl_add_u64 v[172:173], v[172:173], 0, s[2:3]
	s_mov_b32 m0, s60
	s_add_u32 s84, s8, 0x10180
	ds_read_b128 v[168:171], v175 offset:49152
	ds_read_b128 v[176:179], v175 offset:50176
	ds_read_b128 v[180:183], v175 offset:51200
	ds_read_b128 v[184:187], v175 offset:52224
	ds_read_b128 v[188:191], v175 offset:53248
	ds_read_b128 v[192:195], v175 offset:54272
	ds_read_b128 v[200:203], v175 offset:55296
	ds_read_b128 v[206:209], v175 offset:56320
	global_load_lds_dwordx4 v[172:173], off
	v_lshl_add_u64 v[172:173], v[196:197], 0, s[2:3]
	s_mov_b32 m0, s58
	s_addc_u32 s85, s9, 0
	s_add_i32 s8, s76, s15
	global_load_lds_dwordx4 v[172:173], off
	v_lshl_add_u64 v[172:173], s[84:85], 0, v[140:141]
	s_mov_b32 m0, s8
	s_add_i32 s9, s8, 0x2000
	global_load_lds_dwordx4 v[172:173], off
	v_lshl_add_u64 v[172:173], s[84:85], 0, v[158:159]
	s_mov_b32 m0, s9
	s_nop 0
	global_load_lds_dwordx4 v[172:173], off
	v_lshl_add_u64 v[172:173], v[198:199], 0, s[2:3]
	s_mov_b32 m0, s74
	s_nop 0
	global_load_lds_dwordx4 v[172:173], off
	v_lshl_add_u64 v[172:173], v[204:205], 0, s[2:3]
	s_mov_b32 m0, s75
	s_nop 0
	global_load_lds_dwordx4 v[172:173], off
	s_waitcnt vmcnt(8)
	s_waitcnt lgkmcnt(0)
	s_setprio 1
	s_barrier
	v_mfma_f32_16x16x32_bf16 v[132:135], v[112:115], v[168:171], v[132:135]
	v_mfma_f32_16x16x32_bf16 v[136:139], v[24:27], v[180:183], v[136:139]
	v_mfma_f32_16x16x32_bf16 v[0:3], v[24:27], v[200:203], v[0:3]
	v_mfma_f32_16x16x32_bf16 v[4:7], v[112:115], v[200:203], v[4:7]
	v_mfma_f32_16x16x32_bf16 v[128:131], v[24:27], v[168:171], v[128:131]
	v_mfma_f32_16x16x32_bf16 v[132:135], v[116:119], v[176:179], v[132:135]
	v_mfma_f32_16x16x32_bf16 v[136:139], v[28:31], v[184:187], v[136:139]
	v_mfma_f32_16x16x32_bf16 v[142:145], v[112:115], v[180:183], v[142:145]
	v_mfma_f32_16x16x32_bf16 v[146:149], v[24:27], v[188:191], v[146:149]
	v_mfma_f32_16x16x32_bf16 v[150:153], v[112:115], v[188:191], v[150:153]
	v_mfma_f32_16x16x32_bf16 v[0:3], v[28:31], v[206:209], v[0:3]
	v_mfma_f32_16x16x32_bf16 v[4:7], v[116:119], v[206:209], v[4:7]
	v_mfma_f32_16x16x32_bf16 v[128:131], v[28:31], v[176:179], v[128:131]
	v_mfma_f32_16x16x32_bf16 v[142:145], v[116:119], v[184:187], v[142:145]
	v_mfma_f32_16x16x32_bf16 v[146:149], v[28:31], v[192:195], v[146:149]
	v_mfma_f32_16x16x32_bf16 v[150:153], v[116:119], v[192:195], v[150:153]
	v_mfma_f32_16x16x32_bf16 v[8:11], v[120:123], v[168:171], v[8:11]
	v_mfma_f32_16x16x32_bf16 v[12:15], v[154:157], v[168:171], v[12:15]
	v_mfma_f32_16x16x32_bf16 v[24:27], v[120:123], v[180:183], v[60:63]
	v_mfma_f32_16x16x32_bf16 v[28:31], v[154:157], v[180:183], v[100:103]
	v_mfma_f32_16x16x32_bf16 v[60:63], v[120:123], v[188:191], v[104:107]
	v_mfma_f32_16x16x32_bf16 v[100:103], v[154:157], v[188:191], v[108:111]
	v_mfma_f32_16x16x32_bf16 v[16:19], v[120:123], v[200:203], v[16:19]
	v_mfma_f32_16x16x32_bf16 v[20:23], v[154:157], v[200:203], v[20:23]
	v_mfma_f32_16x16x32_bf16 v[8:11], v[124:127], v[176:179], v[8:11]
	v_mfma_f32_16x16x32_bf16 v[12:15], v[164:167], v[176:179], v[12:15]
	v_mfma_f32_16x16x32_bf16 v[24:27], v[124:127], v[184:187], v[24:27]
	v_mfma_f32_16x16x32_bf16 v[28:31], v[164:167], v[184:187], v[28:31]
	v_mfma_f32_16x16x32_bf16 v[60:63], v[124:127], v[192:195], v[60:63]
	v_mfma_f32_16x16x32_bf16 v[100:103], v[164:167], v[192:195], v[100:103]
	v_mfma_f32_16x16x32_bf16 v[16:19], v[124:127], v[206:209], v[16:19]
	v_mfma_f32_16x16x32_bf16 v[20:23], v[164:167], v[206:209], v[20:23]
	s_barrier
	s_setprio 0
	ds_read_b128 v[104:107], v212
	ds_read_b128 v[108:111], v212 offset:1024
	ds_read_b128 v[112:115], v212 offset:2048
	ds_read_b128 v[116:119], v212 offset:3072
	ds_read_b128 v[120:123], v213
	ds_read_b128 v[124:127], v213 offset:1024
	ds_read_b128 v[154:157], v213 offset:2048
	ds_read_b128 v[164:167], v213 offset:3072
	s_add_u32 s6, s6, 0x40180
	s_addc_u32 s7, s7, 0
	s_mov_b32 m0, s59
	v_lshl_add_u64 v[172:173], s[6:7], 0, v[162:163]
	ds_read_b128 v[168:171], v175
	ds_read_b128 v[176:179], v175 offset:1024
	ds_read_b128 v[180:183], v175 offset:2048
	ds_read_b128 v[184:187], v175 offset:3072
	ds_read_b128 v[188:191], v175 offset:4096
	ds_read_b128 v[192:195], v175 offset:5120
	ds_read_b128 v[200:203], v175 offset:6144
	ds_read_b128 v[206:209], v175 offset:7168
	global_load_lds_dwordx4 v[172:173], off
	v_lshl_add_u64 v[172:173], s[6:7], 0, v[160:161]
	s_mov_b32 m0, s24
	s_nop 0
	global_load_lds_dwordx4 v[172:173], off
	s_waitcnt vmcnt(8)
	s_waitcnt lgkmcnt(0)
	s_setprio 1
	s_barrier
	v_mfma_f32_16x16x32_bf16 v[64:67], v[104:107], v[168:171], v[64:67]
	v_mfma_f32_16x16x32_bf16 v[68:71], v[112:115], v[168:171], v[68:71]
	v_mfma_f32_16x16x32_bf16 v[72:75], v[104:107], v[180:183], v[72:75]
	v_mfma_f32_16x16x32_bf16 v[76:79], v[112:115], v[180:183], v[76:79]
	v_mfma_f32_16x16x32_bf16 v[80:83], v[104:107], v[188:191], v[80:83]
	v_mfma_f32_16x16x32_bf16 v[84:87], v[112:115], v[188:191], v[84:87]
	v_mfma_f32_16x16x32_bf16 v[88:91], v[104:107], v[200:203], v[88:91]
	v_mfma_f32_16x16x32_bf16 v[64:67], v[108:111], v[176:179], v[64:67]
	v_mfma_f32_16x16x32_bf16 v[68:71], v[116:119], v[176:179], v[68:71]
	v_mfma_f32_16x16x32_bf16 v[72:75], v[108:111], v[184:187], v[72:75]
	v_mfma_f32_16x16x32_bf16 v[76:79], v[116:119], v[184:187], v[76:79]
	v_mfma_f32_16x16x32_bf16 v[80:83], v[108:111], v[192:195], v[80:83]
	v_mfma_f32_16x16x32_bf16 v[84:87], v[116:119], v[192:195], v[84:87]
	v_mfma_f32_16x16x32_bf16 v[210:213], v[108:111], v[206:209], v[88:91]
	v_mfma_f32_16x16x32_bf16 v[88:91], v[112:115], v[200:203], v[92:95]
	v_mfma_f32_16x16x32_bf16 v[214:217], v[116:119], v[206:209], v[88:91]
	v_mfma_f32_16x16x32_bf16 v[88:91], v[120:123], v[168:171], v[96:99]
	v_mfma_f32_16x16x32_bf16 v[32:35], v[154:157], v[168:171], v[32:35]
	v_mfma_f32_16x16x32_bf16 v[36:39], v[120:123], v[180:183], v[36:39]
	v_mfma_f32_16x16x32_bf16 v[40:43], v[154:157], v[180:183], v[40:43]
	v_mfma_f32_16x16x32_bf16 v[44:47], v[120:123], v[188:191], v[44:47]
	v_mfma_f32_16x16x32_bf16 v[48:51], v[154:157], v[188:191], v[48:51]
	v_mfma_f32_16x16x32_bf16 v[52:55], v[120:123], v[200:203], v[52:55]
	v_mfma_f32_16x16x32_bf16 v[56:59], v[154:157], v[200:203], v[56:59]
	v_mfma_f32_16x16x32_bf16 v[96:99], v[124:127], v[176:179], v[88:91]
	v_mfma_f32_16x16x32_bf16 v[32:35], v[164:167], v[176:179], v[32:35]
	v_mfma_f32_16x16x32_bf16 v[36:39], v[124:127], v[184:187], v[36:39]
	v_mfma_f32_16x16x32_bf16 v[40:43], v[164:167], v[184:187], v[40:43]
	v_mfma_f32_16x16x32_bf16 v[44:47], v[124:127], v[192:195], v[44:47]
	v_mfma_f32_16x16x32_bf16 v[48:51], v[164:167], v[192:195], v[48:51]
	v_mfma_f32_16x16x32_bf16 v[52:55], v[124:127], v[206:209], v[52:55]
	v_mfma_f32_16x16x32_bf16 v[56:59], v[164:167], v[206:209], v[56:59]
	s_barrier
	s_setprio 0
	s_mov_b32 m0, s55
	v_lshl_add_u64 v[172:173], s[10:11], 0, v[140:141]
	s_add_u32 s6, s10, 0x10000
	ds_read_b128 v[88:91], v175 offset:16384
	ds_read_b128 v[92:95], v175 offset:17408
	ds_read_b128 v[168:171], v175 offset:18432
	ds_read_b128 v[176:179], v175 offset:19456
	ds_read_b128 v[180:183], v175 offset:20480
	ds_read_b128 v[184:187], v175 offset:21504
	ds_read_b128 v[188:191], v175 offset:22528
	ds_read_b128 v[192:195], v175 offset:23552
	global_load_lds_dwordx4 v[172:173], off
	v_lshl_add_u64 v[196:197], s[10:11], 0, v[158:159]
	s_mov_b32 m0, s35
	s_addc_u32 s7, s11, 0
	global_load_lds_dwordx4 v[196:197], off
	v_lshl_add_u64 v[198:199], s[6:7], 0, v[140:141]
	s_mov_b32 m0, s38
	v_lshl_add_u64 v[204:205], s[42:43], 0, v[160:161]
	global_load_lds_dwordx4 v[198:199], off
	v_lshl_add_u64 v[198:199], s[6:7], 0, v[158:159]
	s_mov_b32 m0, s53
	s_nop 0
	global_load_lds_dwordx4 v[198:199], off
	v_lshl_add_u64 v[198:199], s[42:43], 0, v[162:163]
	s_mov_b32 m0, s26
	s_nop 0
	global_load_lds_dwordx4 v[198:199], off
	s_mov_b32 m0, s27
	s_nop 0
	global_load_lds_dwordx4 v[204:205], off
	s_waitcnt vmcnt(8)
	s_waitcnt lgkmcnt(0)
	s_setprio 1
	s_barrier
	v_mfma_f32_16x16x32_bf16 v[132:135], v[112:115], v[88:91], v[132:135]
	v_mfma_f32_16x16x32_bf16 v[200:203], v[116:119], v[92:95], v[132:135]
	v_mfma_f32_16x16x32_bf16 v[132:135], v[104:107], v[168:171], v[136:139]
	v_mfma_f32_16x16x32_bf16 v[206:209], v[108:111], v[176:179], v[132:135]
	v_mfma_f32_16x16x32_bf16 v[132:135], v[112:115], v[168:171], v[142:145]
	v_mfma_f32_16x16x32_bf16 v[142:145], v[116:119], v[176:179], v[132:135]
	v_mfma_f32_16x16x32_bf16 v[132:135], v[104:107], v[180:183], v[146:149]
	v_mfma_f32_16x16x32_bf16 v[0:3], v[104:107], v[188:191], v[0:3]
	v_mfma_f32_16x16x32_bf16 v[4:7], v[112:115], v[188:191], v[4:7]
	v_mfma_f32_16x16x32_bf16 v[128:131], v[104:107], v[88:91], v[128:131]
	v_mfma_f32_16x16x32_bf16 v[146:149], v[108:111], v[184:187], v[132:135]
	v_mfma_f32_16x16x32_bf16 v[132:135], v[112:115], v[180:183], v[150:153]
	v_mfma_f32_16x16x32_bf16 v[0:3], v[108:111], v[192:195], v[0:3]
	v_mfma_f32_16x16x32_bf16 v[4:7], v[116:119], v[192:195], v[4:7]
	v_mfma_f32_16x16x32_bf16 v[128:131], v[108:111], v[92:95], v[128:131]
	v_mfma_f32_16x16x32_bf16 v[150:153], v[116:119], v[184:187], v[132:135]
	v_mfma_f32_16x16x32_bf16 v[8:11], v[120:123], v[88:91], v[8:11]
	v_mfma_f32_16x16x32_bf16 v[112:115], v[124:127], v[92:95], v[8:11]
	v_mfma_f32_16x16x32_bf16 v[8:11], v[154:157], v[88:91], v[12:15]
	v_mfma_f32_16x16x32_bf16 v[116:119], v[164:167], v[92:95], v[8:11]
	v_mfma_f32_16x16x32_bf16 v[8:11], v[120:123], v[168:171], v[24:27]
	v_mfma_f32_16x16x32_bf16 v[218:221], v[124:127], v[176:179], v[8:11]
	v_mfma_f32_16x16x32_bf16 v[8:11], v[154:157], v[168:171], v[28:31]
	v_mfma_f32_16x16x32_bf16 v[168:171], v[164:167], v[176:179], v[8:11]
	v_mfma_f32_16x16x32_bf16 v[8:11], v[120:123], v[180:183], v[60:63]
	v_mfma_f32_16x16x32_bf16 v[176:179], v[124:127], v[184:187], v[8:11]
	v_mfma_f32_16x16x32_bf16 v[8:11], v[154:157], v[180:183], v[100:103]
	v_mfma_f32_16x16x32_bf16 v[180:183], v[164:167], v[184:187], v[8:11]
	v_mfma_f32_16x16x32_bf16 v[8:11], v[120:123], v[188:191], v[16:19]
	v_mfma_f32_16x16x32_bf16 v[184:187], v[124:127], v[192:195], v[8:11]
	v_mfma_f32_16x16x32_bf16 v[8:11], v[154:157], v[188:191], v[20:23]
	v_mfma_f32_16x16x32_bf16 v[154:157], v[164:167], v[192:195], v[8:11]
	s_barrier
	s_setprio 0
	s_nop 4
	ds_read_b128 v[8:11], v222
	ds_read_b128 v[12:15], v222 offset:1024
	ds_read_b128 v[16:19], v222 offset:2048
	ds_read_b128 v[20:23], v222 offset:3072
	ds_read_b128 v[164:167], v223
	ds_read_b128 v[188:191], v223 offset:1024
	ds_read_b128 v[192:195], v223 offset:2048
	ds_read_b128 v[222:225], v223 offset:3072
	s_add_u32 s6, s42, 0x40000
	s_addc_u32 s7, s43, 0
	s_mov_b32 m0, s28
	v_lshl_add_u64 v[88:89], s[6:7], 0, v[162:163]
	ds_read_b128 v[24:27], v175 offset:32768
	ds_read_b128 v[28:31], v175 offset:33792
	ds_read_b128 v[60:63], v175 offset:34816
	ds_read_b128 v[226:229], v175 offset:35840
	ds_read_b128 v[230:233], v175 offset:36864
	ds_read_b128 v[234:237], v175 offset:37888
	ds_read_b128 v[238:241], v175 offset:38912
	ds_read_b128 v[242:245], v175 offset:39936
	global_load_lds_dwordx4 v[88:89], off
	v_lshl_add_u64 v[88:89], s[6:7], 0, v[160:161]
	s_mov_b32 m0, s29
	s_nop 0
	global_load_lds_dwordx4 v[88:89], off
	s_waitcnt vmcnt(8)
	s_waitcnt lgkmcnt(0)
	s_setprio 1
	s_barrier
	v_mfma_f32_16x16x32_bf16 v[64:67], v[8:11], v[24:27], v[64:67]
	v_mfma_f32_16x16x32_bf16 v[132:135], v[12:15], v[28:31], v[64:67]
	v_mfma_f32_16x16x32_bf16 v[64:67], v[16:19], v[24:27], v[68:71]
	v_mfma_f32_16x16x32_bf16 v[136:139], v[20:23], v[28:31], v[64:67]
	v_mfma_f32_16x16x32_bf16 v[64:67], v[8:11], v[60:63], v[72:75]
	v_mfma_f32_16x16x32_bf16 v[108:111], v[12:15], v[226:229], v[64:67]
	v_mfma_f32_16x16x32_bf16 v[64:67], v[16:19], v[60:63], v[76:79]
	v_mfma_f32_16x16x32_bf16 v[104:107], v[20:23], v[226:229], v[64:67]
	v_mfma_f32_16x16x32_bf16 v[64:67], v[8:11], v[230:233], v[80:83]
	v_mfma_f32_16x16x32_bf16 v[88:91], v[12:15], v[234:237], v[64:67]
	v_mfma_f32_16x16x32_bf16 v[64:67], v[16:19], v[230:233], v[84:87]
	v_mfma_f32_16x16x32_bf16 v[92:95], v[20:23], v[234:237], v[64:67]
	v_mfma_f32_16x16x32_bf16 v[64:67], v[8:11], v[238:241], v[210:213]
	v_mfma_f32_16x16x32_bf16 v[76:79], v[12:15], v[242:245], v[64:67]
	v_mfma_f32_16x16x32_bf16 v[64:67], v[16:19], v[238:241], v[214:217]
	v_mfma_f32_16x16x32_bf16 v[72:75], v[20:23], v[242:245], v[64:67]
	v_mfma_f32_16x16x32_bf16 v[64:67], v[164:167], v[24:27], v[96:99]
	v_mfma_f32_16x16x32_bf16 v[24:27], v[192:195], v[24:27], v[32:35]
	v_mfma_f32_16x16x32_bf16 v[120:123], v[222:225], v[28:31], v[24:27]
	v_mfma_f32_16x16x32_bf16 v[24:27], v[164:167], v[60:63], v[36:39]
	v_mfma_f32_16x16x32_bf16 v[100:103], v[188:191], v[226:229], v[24:27]
	v_mfma_f32_16x16x32_bf16 v[24:27], v[192:195], v[60:63], v[40:43]
	v_mfma_f32_16x16x32_bf16 v[96:99], v[222:225], v[226:229], v[24:27]
	v_mfma_f32_16x16x32_bf16 v[24:27], v[164:167], v[230:233], v[44:47]
	v_mfma_f32_16x16x32_bf16 v[84:87], v[188:191], v[234:237], v[24:27]
	v_mfma_f32_16x16x32_bf16 v[24:27], v[192:195], v[230:233], v[48:51]
	v_mfma_f32_16x16x32_bf16 v[80:83], v[222:225], v[234:237], v[24:27]
	v_mfma_f32_16x16x32_bf16 v[24:27], v[164:167], v[238:241], v[52:55]
	v_mfma_f32_16x16x32_bf16 v[68:71], v[188:191], v[242:245], v[24:27]
	v_mfma_f32_16x16x32_bf16 v[24:27], v[192:195], v[238:241], v[56:59]
	v_mfma_f32_16x16x32_bf16 v[124:127], v[188:191], v[28:31], v[64:67]
	v_mfma_f32_16x16x32_bf16 v[64:67], v[222:225], v[242:245], v[24:27]
	s_barrier
	s_setprio 0
	s_mov_b32 m0, s60
	s_nop 2
	v_lshl_add_u64 v[24:25], v[172:173], 0, s[36:37]
	s_add_u32 s6, s10, 0x10080
	ds_read_b128 v[32:35], v175 offset:49152
	ds_read_b128 v[36:39], v175 offset:50176
	ds_read_b128 v[210:213], v175 offset:51200
	ds_read_b128 v[214:217], v175 offset:52224
	ds_read_b128 v[226:229], v175 offset:53248
	ds_read_b128 v[230:233], v175 offset:54272
	ds_read_b128 v[234:237], v175 offset:55296
	ds_read_b128 v[238:241], v175 offset:56320
	global_load_lds_dwordx4 v[24:25], off
	v_lshl_add_u64 v[24:25], v[196:197], 0, s[36:37]
	s_mov_b32 m0, s58
	s_addc_u32 s7, s11, 0
	global_load_lds_dwordx4 v[24:25], off
	v_lshl_add_u64 v[24:25], s[6:7], 0, v[140:141]
	s_mov_b32 m0, s8
	s_nop 0
	global_load_lds_dwordx4 v[24:25], off
	v_lshl_add_u64 v[24:25], s[6:7], 0, v[158:159]
	s_mov_b32 m0, s9
	s_nop 0
	global_load_lds_dwordx4 v[24:25], off
	v_lshl_add_u64 v[24:25], v[198:199], 0, s[36:37]
	s_mov_b32 m0, s74
	s_nop 0
	global_load_lds_dwordx4 v[24:25], off
	v_lshl_add_u64 v[24:25], v[204:205], 0, s[36:37]
	s_mov_b32 m0, s75
	s_nop 0
	global_load_lds_dwordx4 v[24:25], off
	s_waitcnt vmcnt(8)
	s_waitcnt lgkmcnt(0)
	s_setprio 1
	s_barrier
	v_mfma_f32_16x16x32_bf16 v[24:27], v[8:11], v[32:35], v[128:131]
	v_mfma_f32_16x16x32_bf16 v[56:59], v[12:15], v[36:39], v[24:27]
	v_mfma_f32_16x16x32_bf16 v[24:27], v[16:19], v[32:35], v[200:203]
	v_mfma_f32_16x16x32_bf16 v[60:63], v[20:23], v[36:39], v[24:27]
	v_mfma_f32_16x16x32_bf16 v[24:27], v[8:11], v[210:213], v[206:209]
	v_mfma_f32_16x16x32_bf16 v[44:47], v[12:15], v[214:217], v[24:27]
	v_mfma_f32_16x16x32_bf16 v[24:27], v[16:19], v[210:213], v[142:145]
	v_mfma_f32_16x16x32_bf16 v[40:43], v[20:23], v[214:217], v[24:27]
	v_mfma_f32_16x16x32_bf16 v[24:27], v[8:11], v[226:229], v[146:149]
	v_mfma_f32_16x16x32_bf16 v[0:3], v[8:11], v[234:237], v[0:3]
	v_mfma_f32_16x16x32_bf16 v[24:27], v[12:15], v[230:233], v[24:27]
	v_mfma_f32_16x16x32_bf16 v[28:31], v[16:19], v[226:229], v[150:153]
	v_mfma_f32_16x16x32_bf16 v[12:15], v[12:15], v[238:241], v[0:3]
	v_mfma_f32_16x16x32_bf16 v[0:3], v[16:19], v[234:237], v[4:7]
	v_mfma_f32_16x16x32_bf16 v[28:31], v[20:23], v[230:233], v[28:31]
	v_mfma_f32_16x16x32_bf16 v[8:11], v[20:23], v[238:241], v[0:3]
	v_mfma_f32_16x16x32_bf16 v[0:3], v[164:167], v[32:35], v[112:115]
	v_mfma_f32_16x16x32_bf16 v[52:55], v[188:191], v[36:39], v[0:3]
	v_mfma_f32_16x16x32_bf16 v[0:3], v[192:195], v[32:35], v[116:119]
	v_mfma_f32_16x16x32_bf16 v[48:51], v[222:225], v[36:39], v[0:3]
	v_mfma_f32_16x16x32_bf16 v[0:3], v[164:167], v[210:213], v[218:221]
	v_mfma_f32_16x16x32_bf16 v[36:39], v[188:191], v[214:217], v[0:3]
	v_mfma_f32_16x16x32_bf16 v[0:3], v[192:195], v[210:213], v[168:171]
	v_mfma_f32_16x16x32_bf16 v[32:35], v[222:225], v[214:217], v[0:3]
	v_mfma_f32_16x16x32_bf16 v[0:3], v[164:167], v[226:229], v[176:179]
	v_mfma_f32_16x16x32_bf16 v[20:23], v[188:191], v[230:233], v[0:3]
	v_mfma_f32_16x16x32_bf16 v[0:3], v[192:195], v[226:229], v[180:183]
	v_mfma_f32_16x16x32_bf16 v[16:19], v[222:225], v[230:233], v[0:3]
	v_mfma_f32_16x16x32_bf16 v[0:3], v[164:167], v[234:237], v[184:187]
	v_mfma_f32_16x16x32_bf16 v[4:7], v[188:191], v[238:241], v[0:3]
	v_mfma_f32_16x16x32_bf16 v[0:3], v[192:195], v[234:237], v[154:157]
	v_mfma_f32_16x16x32_bf16 v[0:3], v[222:225], v[238:241], v[0:3]
	s_barrier
	s_setprio 0
	s_andn2_b64 vcc, exec, s[48:49]
	s_cbranch_vccnz .LBB0_419
	s_barrier

.LBB0_457:
	s_lshl_b64 s[10:11], s[52:53], 17
	s_add_u32 s56, s12, s10
	s_addc_u32 s57, s13, s11
	s_and_b64 s[10:11], s[40:41], exec
	s_cselect_b32 s11, s57, s9
	s_cselect_b32 s10, s56, s8
	s_add_i32 s55, 0, 0x10000
	s_add_i32 s38, 0, 0x14000
	v_add_u32_e32 v212, s55, v138
	v_add_u32_e32 v213, s38, v138
	ds_read_b128 v[0:3], v212
	ds_read_b128 v[4:7], v212 offset:1024
	ds_read_b128 v[8:11], v212 offset:2048
	ds_read_b128 v[12:15], v212 offset:3072
	ds_read_b128 v[16:19], v213
	ds_read_b128 v[20:23], v213 offset:1024
	ds_read_b128 v[24:27], v213 offset:2048
	ds_read_b128 v[28:31], v213 offset:3072
	s_add_u32 s74, s6, 0x40080
	s_addc_u32 s75, s7, 0
	s_add_i32 s61, s26, 0xc000
	v_lshl_add_u64 v[64:65], s[74:75], 0, v[132:133]
	s_mov_b32 m0, s61
	s_add_i32 s24, s26, 0xe000
	ds_read_b128 v[32:35], v139
	ds_read_b128 v[36:39], v139 offset:1024
	ds_read_b128 v[40:43], v139 offset:2048
	ds_read_b128 v[44:47], v139 offset:3072
	ds_read_b128 v[48:51], v139 offset:4096
	ds_read_b128 v[52:55], v139 offset:5120
	ds_read_b128 v[56:59], v139 offset:6144
	ds_read_b128 v[60:63], v139 offset:7168
	global_load_lds_dwordx4 v[64:65], off
	v_lshl_add_u64 v[64:65], s[74:75], 0, v[130:131]
	s_mov_b32 m0, s24
	s_nop 0
	global_load_lds_dwordx4 v[64:65], off
	s_waitcnt vmcnt(8)
	s_waitcnt lgkmcnt(0)
	s_setprio 1
	s_barrier
	v_mfma_f32_16x16x32_bf16 v[64:67], v[0:3], v[32:35], 0
	v_mfma_f32_16x16x32_bf16 v[68:71], v[8:11], v[32:35], 0
	v_mfma_f32_16x16x32_bf16 v[72:75], v[0:3], v[40:43], 0
	v_mfma_f32_16x16x32_bf16 v[76:79], v[8:11], v[40:43], 0
	v_mfma_f32_16x16x32_bf16 v[80:83], v[0:3], v[48:51], 0
	v_mfma_f32_16x16x32_bf16 v[84:87], v[8:11], v[48:51], 0
	v_mfma_f32_16x16x32_bf16 v[88:91], v[0:3], v[56:59], 0
	v_mfma_f32_16x16x32_bf16 v[92:95], v[8:11], v[56:59], 0
	v_mfma_f32_16x16x32_bf16 v[64:67], v[4:7], v[36:39], v[64:67]
	v_mfma_f32_16x16x32_bf16 v[68:71], v[12:15], v[36:39], v[68:71]
	v_mfma_f32_16x16x32_bf16 v[72:75], v[4:7], v[44:47], v[72:75]
	v_mfma_f32_16x16x32_bf16 v[76:79], v[12:15], v[44:47], v[76:79]
	v_mfma_f32_16x16x32_bf16 v[80:83], v[4:7], v[52:55], v[80:83]
	v_mfma_f32_16x16x32_bf16 v[84:87], v[12:15], v[52:55], v[84:87]
	v_mfma_f32_16x16x32_bf16 v[88:91], v[4:7], v[60:63], v[88:91]
	v_mfma_f32_16x16x32_bf16 v[92:95], v[12:15], v[60:63], v[92:95]
	v_mfma_f32_16x16x32_bf16 v[96:99], v[16:19], v[32:35], 0
	v_mfma_f32_16x16x32_bf16 v[32:35], v[24:27], v[32:35], 0
	v_mfma_f32_16x16x32_bf16 v[96:99], v[20:23], v[36:39], v[96:99]
	v_mfma_f32_16x16x32_bf16 v[32:35], v[28:31], v[36:39], v[32:35]
	v_mfma_f32_16x16x32_bf16 v[36:39], v[16:19], v[40:43], 0
	v_mfma_f32_16x16x32_bf16 v[40:43], v[24:27], v[40:43], 0
	v_mfma_f32_16x16x32_bf16 v[36:39], v[20:23], v[44:47], v[36:39]
	v_mfma_f32_16x16x32_bf16 v[40:43], v[28:31], v[44:47], v[40:43]
	v_mfma_f32_16x16x32_bf16 v[44:47], v[16:19], v[48:51], 0
	v_mfma_f32_16x16x32_bf16 v[48:51], v[24:27], v[48:51], 0
	v_mfma_f32_16x16x32_bf16 v[44:47], v[20:23], v[52:55], v[44:47]
	v_mfma_f32_16x16x32_bf16 v[48:51], v[28:31], v[52:55], v[48:51]
	v_mfma_f32_16x16x32_bf16 v[52:55], v[16:19], v[56:59], 0
	v_mfma_f32_16x16x32_bf16 v[56:59], v[24:27], v[56:59], 0
	v_mfma_f32_16x16x32_bf16 v[52:55], v[20:23], v[60:63], v[52:55]
	v_mfma_f32_16x16x32_bf16 v[56:59], v[28:31], v[60:63], v[56:59]
	s_barrier
	s_setprio 0
	s_add_i32 s55, s55, s15
	v_lshl_add_u64 v[198:199], s[8:9], 0, v[140:141]
	s_mov_b64 s[2:3], 0x100
	s_add_i32 s35, s55, 0x2000
	v_lshl_add_u64 v[134:135], v[198:199], 0, s[2:3]
	s_mov_b32 m0, s55
	v_lshl_add_u64 v[204:205], s[8:9], 0, v[128:129]
	s_add_u32 s74, s8, 0x10100
	ds_read_b128 v[60:63], v139 offset:16384
	ds_read_b128 v[100:103], v139 offset:17408
	ds_read_b128 v[104:107], v139 offset:18432
	ds_read_b128 v[108:111], v139 offset:19456
	ds_read_b128 v[112:115], v139 offset:20480
	ds_read_b128 v[116:119], v139 offset:21504
	ds_read_b128 v[120:123], v139 offset:22528
	ds_read_b128 v[124:127], v139 offset:23552
	global_load_lds_dwordx4 v[134:135], off
	v_lshl_add_u64 v[134:135], v[204:205], 0, s[2:3]
	s_mov_b32 m0, s35
	s_addc_u32 s75, s9, 0
	s_add_i32 s38, s38, s15
	global_load_lds_dwordx4 v[134:135], off
	v_lshl_add_u64 v[134:135], s[74:75], 0, v[140:141]
	s_mov_b32 m0, s38
	s_add_i32 s53, s38, 0x2000
	global_load_lds_dwordx4 v[134:135], off
	v_lshl_add_u64 v[134:135], s[74:75], 0, v[128:129]
	s_mov_b32 m0, s53
	v_lshl_add_u64 v[206:207], s[6:7], 0, v[132:133]
	global_load_lds_dwordx4 v[134:135], off
	v_lshl_add_u64 v[134:135], v[206:207], 0, s[2:3]
	s_mov_b32 m0, s26
	v_lshl_add_u64 v[208:209], s[6:7], 0, v[130:131]
	global_load_lds_dwordx4 v[134:135], off
	v_lshl_add_u64 v[134:135], v[208:209], 0, s[2:3]
	s_mov_b32 m0, s27
	s_nop 0
	global_load_lds_dwordx4 v[134:135], off
	s_waitcnt vmcnt(8)
	s_waitcnt lgkmcnt(0)
	s_setprio 1
	s_barrier
	v_mfma_f32_16x16x32_bf16 v[134:137], v[0:3], v[60:63], 0
	v_mfma_f32_16x16x32_bf16 v[146:149], v[0:3], v[104:107], 0
	v_mfma_f32_16x16x32_bf16 v[154:157], v[0:3], v[112:115], 0
	v_mfma_f32_16x16x32_bf16 v[0:3], v[0:3], v[120:123], 0
	v_mfma_f32_16x16x32_bf16 v[134:137], v[4:7], v[100:103], v[134:137]
	v_mfma_f32_16x16x32_bf16 v[146:149], v[4:7], v[108:111], v[146:149]
	v_mfma_f32_16x16x32_bf16 v[154:157], v[4:7], v[116:119], v[154:157]
	v_mfma_f32_16x16x32_bf16 v[0:3], v[4:7], v[124:127], v[0:3]
	v_mfma_f32_16x16x32_bf16 v[4:7], v[8:11], v[120:123], 0
	v_mfma_f32_16x16x32_bf16 v[142:145], v[8:11], v[60:63], 0
	v_mfma_f32_16x16x32_bf16 v[150:153], v[8:11], v[104:107], 0
	v_mfma_f32_16x16x32_bf16 v[158:161], v[8:11], v[112:115], 0
	v_mfma_f32_16x16x32_bf16 v[4:7], v[12:15], v[124:127], v[4:7]
	v_mfma_f32_16x16x32_bf16 v[142:145], v[12:15], v[100:103], v[142:145]
	v_mfma_f32_16x16x32_bf16 v[150:153], v[12:15], v[108:111], v[150:153]
	v_mfma_f32_16x16x32_bf16 v[158:161], v[12:15], v[116:119], v[158:161]
	v_mfma_f32_16x16x32_bf16 v[8:11], v[16:19], v[60:63], 0
	v_mfma_f32_16x16x32_bf16 v[12:15], v[24:27], v[60:63], 0
	v_mfma_f32_16x16x32_bf16 v[8:11], v[20:23], v[100:103], v[8:11]
	v_mfma_f32_16x16x32_bf16 v[12:15], v[28:31], v[100:103], v[12:15]
	v_mfma_f32_16x16x32_bf16 v[60:63], v[16:19], v[104:107], 0
	v_mfma_f32_16x16x32_bf16 v[100:103], v[24:27], v[104:107], 0
	v_mfma_f32_16x16x32_bf16 v[104:107], v[16:19], v[112:115], 0
	v_mfma_f32_16x16x32_bf16 v[16:19], v[16:19], v[120:123], 0
	v_mfma_f32_16x16x32_bf16 v[60:63], v[20:23], v[108:111], v[60:63]
	v_mfma_f32_16x16x32_bf16 v[100:103], v[28:31], v[108:111], v[100:103]
	v_mfma_f32_16x16x32_bf16 v[104:107], v[20:23], v[116:119], v[104:107]
	v_mfma_f32_16x16x32_bf16 v[108:111], v[24:27], v[112:115], 0
	v_mfma_f32_16x16x32_bf16 v[16:19], v[20:23], v[124:127], v[16:19]
	v_mfma_f32_16x16x32_bf16 v[20:23], v[24:27], v[120:123], 0
	v_mfma_f32_16x16x32_bf16 v[108:111], v[28:31], v[116:119], v[108:111]
	v_mfma_f32_16x16x32_bf16 v[20:23], v[28:31], v[124:127], v[20:23]
	s_barrier
	s_setprio 0
	s_add_i32 s60, 0, 0x18000
	s_add_i32 s76, 0, 0x1c000
	v_add_u32_e32 v218, s60, v138
	v_add_u32_e32 v219, s76, v138
	ds_read_b128 v[24:27], v218
	ds_read_b128 v[28:31], v218 offset:1024
	ds_read_b128 v[112:115], v218 offset:2048
	ds_read_b128 v[116:119], v218 offset:3072
	ds_read_b128 v[120:123], v219
	ds_read_b128 v[124:127], v219 offset:1024
	ds_read_b128 v[162:165], v219 offset:2048
	ds_read_b128 v[166:169], v219 offset:3072
	s_add_u32 s74, s6, 0x40100
	s_addc_u32 s75, s7, 0
	s_mov_b32 m0, s28
	v_lshl_add_u64 v[210:211], s[74:75], 0, v[132:133]
	ds_read_b128 v[170:173], v139 offset:32768
	ds_read_b128 v[174:177], v139 offset:33792
	ds_read_b128 v[178:181], v139 offset:34816
	ds_read_b128 v[182:185], v139 offset:35840
	ds_read_b128 v[186:189], v139 offset:36864
	ds_read_b128 v[190:193], v139 offset:37888
	ds_read_b128 v[194:197], v139 offset:38912
	ds_read_b128 v[200:203], v139 offset:39936
	global_load_lds_dwordx4 v[210:211], off
	v_lshl_add_u64 v[210:211], s[74:75], 0, v[130:131]
	s_mov_b32 m0, s29
	s_nop 0
	global_load_lds_dwordx4 v[210:211], off
	s_waitcnt vmcnt(8)
	s_waitcnt lgkmcnt(0)
	s_setprio 1
	s_barrier
	v_mfma_f32_16x16x32_bf16 v[64:67], v[24:27], v[170:173], v[64:67]
	v_mfma_f32_16x16x32_bf16 v[68:71], v[112:115], v[170:173], v[68:71]
	v_mfma_f32_16x16x32_bf16 v[72:75], v[24:27], v[178:181], v[72:75]
	v_mfma_f32_16x16x32_bf16 v[76:79], v[112:115], v[178:181], v[76:79]
	v_mfma_f32_16x16x32_bf16 v[80:83], v[24:27], v[186:189], v[80:83]
	v_mfma_f32_16x16x32_bf16 v[84:87], v[112:115], v[186:189], v[84:87]
	v_mfma_f32_16x16x32_bf16 v[88:91], v[24:27], v[194:197], v[88:91]
	v_mfma_f32_16x16x32_bf16 v[92:95], v[112:115], v[194:197], v[92:95]
	v_mfma_f32_16x16x32_bf16 v[64:67], v[28:31], v[174:177], v[64:67]
	v_mfma_f32_16x16x32_bf16 v[68:71], v[116:119], v[174:177], v[68:71]
	v_mfma_f32_16x16x32_bf16 v[72:75], v[28:31], v[182:185], v[72:75]
	v_mfma_f32_16x16x32_bf16 v[76:79], v[116:119], v[182:185], v[76:79]
	v_mfma_f32_16x16x32_bf16 v[80:83], v[28:31], v[190:193], v[80:83]
	v_mfma_f32_16x16x32_bf16 v[84:87], v[116:119], v[190:193], v[84:87]
	v_mfma_f32_16x16x32_bf16 v[88:91], v[28:31], v[200:203], v[88:91]
	v_mfma_f32_16x16x32_bf16 v[92:95], v[116:119], v[200:203], v[92:95]
	v_mfma_f32_16x16x32_bf16 v[96:99], v[120:123], v[170:173], v[96:99]
	v_mfma_f32_16x16x32_bf16 v[32:35], v[162:165], v[170:173], v[32:35]
	v_mfma_f32_16x16x32_bf16 v[36:39], v[120:123], v[178:181], v[36:39]
	v_mfma_f32_16x16x32_bf16 v[40:43], v[162:165], v[178:181], v[40:43]
	v_mfma_f32_16x16x32_bf16 v[44:47], v[120:123], v[186:189], v[44:47]
	v_mfma_f32_16x16x32_bf16 v[48:51], v[162:165], v[186:189], v[48:51]
	v_mfma_f32_16x16x32_bf16 v[52:55], v[120:123], v[194:197], v[52:55]
	v_mfma_f32_16x16x32_bf16 v[56:59], v[162:165], v[194:197], v[56:59]
	v_mfma_f32_16x16x32_bf16 v[96:99], v[124:127], v[174:177], v[96:99]
	v_mfma_f32_16x16x32_bf16 v[32:35], v[166:169], v[174:177], v[32:35]
	v_mfma_f32_16x16x32_bf16 v[36:39], v[124:127], v[182:185], v[36:39]
	v_mfma_f32_16x16x32_bf16 v[40:43], v[166:169], v[182:185], v[40:43]
	v_mfma_f32_16x16x32_bf16 v[44:47], v[124:127], v[190:193], v[44:47]
	v_mfma_f32_16x16x32_bf16 v[48:51], v[166:169], v[190:193], v[48:51]
	v_mfma_f32_16x16x32_bf16 v[52:55], v[124:127], v[200:203], v[52:55]
	v_mfma_f32_16x16x32_bf16 v[56:59], v[166:169], v[200:203], v[56:59]
	s_barrier
	s_setprio 0
	s_add_i32 s74, s60, s15
	s_mov_b64 s[2:3], 0x180
	s_add_i32 s60, s74, 0x2000
	v_lshl_add_u64 v[198:199], v[198:199], 0, s[2:3]
	s_mov_b32 m0, s74
	s_add_u32 s84, s8, 0x10180
	ds_read_b128 v[170:173], v139 offset:49152
	ds_read_b128 v[174:177], v139 offset:50176
	ds_read_b128 v[178:181], v139 offset:51200
	ds_read_b128 v[182:185], v139 offset:52224
	ds_read_b128 v[186:189], v139 offset:53248
	ds_read_b128 v[190:193], v139 offset:54272
	ds_read_b128 v[194:197], v139 offset:55296
	ds_read_b128 v[200:203], v139 offset:56320
	global_load_lds_dwordx4 v[198:199], off
	v_lshl_add_u64 v[198:199], v[204:205], 0, s[2:3]
	s_mov_b32 m0, s60
	s_addc_u32 s85, s9, 0
	s_add_i32 s8, s76, s15
	global_load_lds_dwordx4 v[198:199], off
	v_lshl_add_u64 v[198:199], s[84:85], 0, v[140:141]
	s_mov_b32 m0, s8
	s_add_i32 s9, s8, 0x2000
	global_load_lds_dwordx4 v[198:199], off
	v_lshl_add_u64 v[198:199], s[84:85], 0, v[128:129]
	s_mov_b32 m0, s9
	s_nop 0
	global_load_lds_dwordx4 v[198:199], off
	v_lshl_add_u64 v[198:199], v[206:207], 0, s[2:3]
	s_mov_b32 m0, s58
	s_nop 0
	global_load_lds_dwordx4 v[198:199], off
	v_lshl_add_u64 v[198:199], v[208:209], 0, s[2:3]
	s_mov_b32 m0, s59
	s_nop 0
	global_load_lds_dwordx4 v[198:199], off
	s_waitcnt vmcnt(8)
	s_waitcnt lgkmcnt(0)
	s_setprio 1
	s_barrier
	v_mfma_f32_16x16x32_bf16 v[0:3], v[24:27], v[194:197], v[0:3]
	v_mfma_f32_16x16x32_bf16 v[4:7], v[112:115], v[194:197], v[4:7]
	v_mfma_f32_16x16x32_bf16 v[134:137], v[24:27], v[170:173], v[134:137]
	v_mfma_f32_16x16x32_bf16 v[142:145], v[112:115], v[170:173], v[142:145]
	v_mfma_f32_16x16x32_bf16 v[146:149], v[24:27], v[178:181], v[146:149]
	v_mfma_f32_16x16x32_bf16 v[150:153], v[112:115], v[178:181], v[150:153]
	v_mfma_f32_16x16x32_bf16 v[154:157], v[24:27], v[186:189], v[154:157]
	v_mfma_f32_16x16x32_bf16 v[158:161], v[112:115], v[186:189], v[158:161]
	v_mfma_f32_16x16x32_bf16 v[0:3], v[28:31], v[200:203], v[0:3]
	v_mfma_f32_16x16x32_bf16 v[4:7], v[116:119], v[200:203], v[4:7]
	v_mfma_f32_16x16x32_bf16 v[134:137], v[28:31], v[174:177], v[134:137]
	v_mfma_f32_16x16x32_bf16 v[142:145], v[116:119], v[174:177], v[142:145]
	v_mfma_f32_16x16x32_bf16 v[146:149], v[28:31], v[182:185], v[146:149]
	v_mfma_f32_16x16x32_bf16 v[150:153], v[116:119], v[182:185], v[150:153]
	v_mfma_f32_16x16x32_bf16 v[154:157], v[28:31], v[190:193], v[154:157]
	v_mfma_f32_16x16x32_bf16 v[158:161], v[116:119], v[190:193], v[158:161]
	v_mfma_f32_16x16x32_bf16 v[8:11], v[120:123], v[170:173], v[8:11]
	v_mfma_f32_16x16x32_bf16 v[12:15], v[162:165], v[170:173], v[12:15]
	v_mfma_f32_16x16x32_bf16 v[24:27], v[120:123], v[178:181], v[60:63]
	v_mfma_f32_16x16x32_bf16 v[28:31], v[162:165], v[178:181], v[100:103]
	v_mfma_f32_16x16x32_bf16 v[60:63], v[120:123], v[186:189], v[104:107]
	v_mfma_f32_16x16x32_bf16 v[100:103], v[162:165], v[186:189], v[108:111]
	v_mfma_f32_16x16x32_bf16 v[16:19], v[120:123], v[194:197], v[16:19]
	v_mfma_f32_16x16x32_bf16 v[20:23], v[162:165], v[194:197], v[20:23]
	v_mfma_f32_16x16x32_bf16 v[8:11], v[124:127], v[174:177], v[8:11]
	v_mfma_f32_16x16x32_bf16 v[12:15], v[166:169], v[174:177], v[12:15]
	v_mfma_f32_16x16x32_bf16 v[24:27], v[124:127], v[182:185], v[24:27]
	v_mfma_f32_16x16x32_bf16 v[28:31], v[166:169], v[182:185], v[28:31]
	v_mfma_f32_16x16x32_bf16 v[60:63], v[124:127], v[190:193], v[60:63]
	v_mfma_f32_16x16x32_bf16 v[100:103], v[166:169], v[190:193], v[100:103]
	v_mfma_f32_16x16x32_bf16 v[16:19], v[124:127], v[200:203], v[16:19]
	v_mfma_f32_16x16x32_bf16 v[20:23], v[166:169], v[200:203], v[20:23]
	s_barrier
	s_setprio 0
	ds_read_b128 v[104:107], v212
	ds_read_b128 v[108:111], v212 offset:1024
	ds_read_b128 v[112:115], v212 offset:2048
	ds_read_b128 v[116:119], v212 offset:3072
	ds_read_b128 v[120:123], v213
	ds_read_b128 v[124:127], v213 offset:1024
	ds_read_b128 v[162:165], v213 offset:2048
	ds_read_b128 v[166:169], v213 offset:3072
	s_add_u32 s6, s6, 0x40180
	s_addc_u32 s7, s7, 0
	s_mov_b32 m0, s61
	v_lshl_add_u64 v[198:199], s[6:7], 0, v[132:133]
	ds_read_b128 v[170:173], v139
	ds_read_b128 v[174:177], v139 offset:1024
	ds_read_b128 v[178:181], v139 offset:2048
	ds_read_b128 v[182:185], v139 offset:3072
	ds_read_b128 v[186:189], v139 offset:4096
	ds_read_b128 v[190:193], v139 offset:5120
	ds_read_b128 v[194:197], v139 offset:6144
	ds_read_b128 v[200:203], v139 offset:7168
	global_load_lds_dwordx4 v[198:199], off
	v_lshl_add_u64 v[198:199], s[6:7], 0, v[130:131]
	s_mov_b32 m0, s24
	s_nop 0
	global_load_lds_dwordx4 v[198:199], off
	s_waitcnt vmcnt(8)
	s_waitcnt lgkmcnt(0)
	s_setprio 1
	s_barrier
	v_mfma_f32_16x16x32_bf16 v[64:67], v[104:107], v[170:173], v[64:67]
	v_mfma_f32_16x16x32_bf16 v[68:71], v[112:115], v[170:173], v[68:71]
	v_mfma_f32_16x16x32_bf16 v[72:75], v[104:107], v[178:181], v[72:75]
	v_mfma_f32_16x16x32_bf16 v[76:79], v[112:115], v[178:181], v[76:79]
	v_mfma_f32_16x16x32_bf16 v[80:83], v[104:107], v[186:189], v[80:83]
	v_mfma_f32_16x16x32_bf16 v[84:87], v[112:115], v[186:189], v[84:87]
	v_mfma_f32_16x16x32_bf16 v[88:91], v[104:107], v[194:197], v[88:91]
	v_mfma_f32_16x16x32_bf16 v[64:67], v[108:111], v[174:177], v[64:67]
	v_mfma_f32_16x16x32_bf16 v[68:71], v[116:119], v[174:177], v[68:71]
	v_mfma_f32_16x16x32_bf16 v[72:75], v[108:111], v[182:185], v[72:75]
	v_mfma_f32_16x16x32_bf16 v[76:79], v[116:119], v[182:185], v[76:79]
	v_mfma_f32_16x16x32_bf16 v[80:83], v[108:111], v[190:193], v[80:83]
	v_mfma_f32_16x16x32_bf16 v[84:87], v[116:119], v[190:193], v[84:87]
	v_mfma_f32_16x16x32_bf16 v[206:209], v[108:111], v[200:203], v[88:91]
	v_mfma_f32_16x16x32_bf16 v[88:91], v[112:115], v[194:197], v[92:95]
	v_mfma_f32_16x16x32_bf16 v[210:213], v[116:119], v[200:203], v[88:91]
	v_mfma_f32_16x16x32_bf16 v[88:91], v[120:123], v[170:173], v[96:99]
	v_mfma_f32_16x16x32_bf16 v[32:35], v[162:165], v[170:173], v[32:35]
	v_mfma_f32_16x16x32_bf16 v[36:39], v[120:123], v[178:181], v[36:39]
	v_mfma_f32_16x16x32_bf16 v[40:43], v[162:165], v[178:181], v[40:43]
	v_mfma_f32_16x16x32_bf16 v[44:47], v[120:123], v[186:189], v[44:47]
	v_mfma_f32_16x16x32_bf16 v[48:51], v[162:165], v[186:189], v[48:51]
	v_mfma_f32_16x16x32_bf16 v[52:55], v[120:123], v[194:197], v[52:55]
	v_mfma_f32_16x16x32_bf16 v[56:59], v[162:165], v[194:197], v[56:59]
	v_mfma_f32_16x16x32_bf16 v[96:99], v[124:127], v[174:177], v[88:91]
	v_mfma_f32_16x16x32_bf16 v[32:35], v[166:169], v[174:177], v[32:35]
	v_mfma_f32_16x16x32_bf16 v[36:39], v[124:127], v[182:185], v[36:39]
	v_mfma_f32_16x16x32_bf16 v[40:43], v[166:169], v[182:185], v[40:43]
	v_mfma_f32_16x16x32_bf16 v[44:47], v[124:127], v[190:193], v[44:47]
	v_mfma_f32_16x16x32_bf16 v[48:51], v[166:169], v[190:193], v[48:51]
	v_mfma_f32_16x16x32_bf16 v[52:55], v[124:127], v[200:203], v[52:55]
	v_mfma_f32_16x16x32_bf16 v[56:59], v[166:169], v[200:203], v[56:59]
	s_barrier
	s_setprio 0
	s_mov_b32 m0, s55
	v_lshl_add_u64 v[198:199], s[10:11], 0, v[140:141]
	s_add_u32 s6, s10, 0x10000
	ds_read_b128 v[88:91], v139 offset:16384
	ds_read_b128 v[92:95], v139 offset:17408
	ds_read_b128 v[170:173], v139 offset:18432
	ds_read_b128 v[174:177], v139 offset:19456
	ds_read_b128 v[178:181], v139 offset:20480
	ds_read_b128 v[182:185], v139 offset:21504
	ds_read_b128 v[186:189], v139 offset:22528
	ds_read_b128 v[190:193], v139 offset:23552
	global_load_lds_dwordx4 v[198:199], off
	v_lshl_add_u64 v[204:205], s[10:11], 0, v[128:129]
	s_mov_b32 m0, s35
	s_addc_u32 s7, s11, 0
	global_load_lds_dwordx4 v[204:205], off
	v_lshl_add_u64 v[194:195], s[6:7], 0, v[140:141]
	s_mov_b32 m0, s38
	v_lshl_add_u64 v[242:243], s[42:43], 0, v[132:133]
	global_load_lds_dwordx4 v[194:195], off
	v_lshl_add_u64 v[194:195], s[6:7], 0, v[128:129]
	s_mov_b32 m0, s53
	v_lshl_add_u64 v[244:245], s[42:43], 0, v[130:131]
	global_load_lds_dwordx4 v[194:195], off
	s_mov_b32 m0, s26
	s_nop 0
	global_load_lds_dwordx4 v[242:243], off
	s_mov_b32 m0, s27
	s_nop 0
	global_load_lds_dwordx4 v[244:245], off
	s_waitcnt vmcnt(8)
	s_waitcnt lgkmcnt(0)
	s_setprio 1
	s_barrier
	v_mfma_f32_16x16x32_bf16 v[0:3], v[104:107], v[186:189], v[0:3]
	v_mfma_f32_16x16x32_bf16 v[4:7], v[112:115], v[186:189], v[4:7]
	v_mfma_f32_16x16x32_bf16 v[134:137], v[104:107], v[88:91], v[134:137]
	v_mfma_f32_16x16x32_bf16 v[142:145], v[112:115], v[88:91], v[142:145]
	v_mfma_f32_16x16x32_bf16 v[146:149], v[104:107], v[170:173], v[146:149]
	v_mfma_f32_16x16x32_bf16 v[150:153], v[112:115], v[170:173], v[150:153]
	v_mfma_f32_16x16x32_bf16 v[154:157], v[104:107], v[178:181], v[154:157]
	v_mfma_f32_16x16x32_bf16 v[158:161], v[112:115], v[178:181], v[158:161]
	v_mfma_f32_16x16x32_bf16 v[0:3], v[108:111], v[190:193], v[0:3]
	v_mfma_f32_16x16x32_bf16 v[4:7], v[116:119], v[190:193], v[4:7]
	v_mfma_f32_16x16x32_bf16 v[134:137], v[108:111], v[92:95], v[134:137]
	v_mfma_f32_16x16x32_bf16 v[142:145], v[116:119], v[92:95], v[142:145]
	v_mfma_f32_16x16x32_bf16 v[146:149], v[108:111], v[174:177], v[146:149]
	v_mfma_f32_16x16x32_bf16 v[150:153], v[116:119], v[174:177], v[150:153]
	v_mfma_f32_16x16x32_bf16 v[154:157], v[108:111], v[182:185], v[154:157]
	v_mfma_f32_16x16x32_bf16 v[158:161], v[116:119], v[182:185], v[158:161]
	v_mfma_f32_16x16x32_bf16 v[8:11], v[120:123], v[88:91], v[8:11]
	v_mfma_f32_16x16x32_bf16 v[194:197], v[124:127], v[92:95], v[8:11]
	v_mfma_f32_16x16x32_bf16 v[8:11], v[162:165], v[88:91], v[12:15]
	v_mfma_f32_16x16x32_bf16 v[200:203], v[166:169], v[92:95], v[8:11]
	v_mfma_f32_16x16x32_bf16 v[8:11], v[120:123], v[170:173], v[24:27]
	v_mfma_f32_16x16x32_bf16 v[214:217], v[124:127], v[174:177], v[8:11]
	v_mfma_f32_16x16x32_bf16 v[8:11], v[162:165], v[170:173], v[28:31]
	v_mfma_f32_16x16x32_bf16 v[170:173], v[166:169], v[174:177], v[8:11]
	v_mfma_f32_16x16x32_bf16 v[8:11], v[120:123], v[178:181], v[60:63]
	v_mfma_f32_16x16x32_bf16 v[174:177], v[124:127], v[182:185], v[8:11]
	v_mfma_f32_16x16x32_bf16 v[8:11], v[162:165], v[178:181], v[100:103]
	v_mfma_f32_16x16x32_bf16 v[178:181], v[166:169], v[182:185], v[8:11]
	v_mfma_f32_16x16x32_bf16 v[8:11], v[120:123], v[186:189], v[16:19]
	v_mfma_f32_16x16x32_bf16 v[182:185], v[124:127], v[190:193], v[8:11]
	v_mfma_f32_16x16x32_bf16 v[8:11], v[162:165], v[186:189], v[20:23]
	v_mfma_f32_16x16x32_bf16 v[162:165], v[166:169], v[190:193], v[8:11]
	s_barrier
	s_setprio 0
	s_nop 4
	ds_read_b128 v[8:11], v218
	ds_read_b128 v[12:15], v218 offset:1024
	ds_read_b128 v[16:19], v218 offset:2048
	ds_read_b128 v[20:23], v218 offset:3072
	ds_read_b128 v[166:169], v219
	ds_read_b128 v[186:189], v219 offset:1024
	ds_read_b128 v[190:193], v219 offset:2048
	ds_read_b128 v[218:221], v219 offset:3072
	s_add_u32 s6, s42, 0x40000
	s_addc_u32 s7, s43, 0
	s_mov_b32 m0, s28
	v_lshl_add_u64 v[88:89], s[6:7], 0, v[132:133]
	ds_read_b128 v[24:27], v139 offset:32768
	ds_read_b128 v[28:31], v139 offset:33792
	ds_read_b128 v[60:63], v139 offset:34816
	ds_read_b128 v[222:225], v139 offset:35840
	ds_read_b128 v[226:229], v139 offset:36864
	ds_read_b128 v[230:233], v139 offset:37888
	ds_read_b128 v[234:237], v139 offset:38912
	ds_read_b128 v[238:241], v139 offset:39936
	global_load_lds_dwordx4 v[88:89], off
	v_lshl_add_u64 v[88:89], s[6:7], 0, v[130:131]
	s_mov_b32 m0, s29
	s_nop 0
	global_load_lds_dwordx4 v[88:89], off
	s_waitcnt vmcnt(8)
	s_waitcnt lgkmcnt(0)
	s_setprio 1
	s_barrier
	v_mfma_f32_16x16x32_bf16 v[64:67], v[8:11], v[24:27], v[64:67]
	v_mfma_f32_16x16x32_bf16 v[120:123], v[12:15], v[28:31], v[64:67]
	v_mfma_f32_16x16x32_bf16 v[64:67], v[16:19], v[24:27], v[68:71]
	v_mfma_f32_16x16x32_bf16 v[124:127], v[20:23], v[28:31], v[64:67]
	v_mfma_f32_16x16x32_bf16 v[64:67], v[8:11], v[60:63], v[72:75]
	v_mfma_f32_16x16x32_bf16 v[104:107], v[12:15], v[222:225], v[64:67]
	v_mfma_f32_16x16x32_bf16 v[64:67], v[16:19], v[60:63], v[76:79]
	v_mfma_f32_16x16x32_bf16 v[108:111], v[20:23], v[222:225], v[64:67]
	v_mfma_f32_16x16x32_bf16 v[64:67], v[8:11], v[226:229], v[80:83]
	v_mfma_f32_16x16x32_bf16 v[88:91], v[12:15], v[230:233], v[64:67]
	v_mfma_f32_16x16x32_bf16 v[64:67], v[16:19], v[226:229], v[84:87]
	v_mfma_f32_16x16x32_bf16 v[92:95], v[20:23], v[230:233], v[64:67]
	v_mfma_f32_16x16x32_bf16 v[64:67], v[8:11], v[234:237], v[206:209]
	v_mfma_f32_16x16x32_bf16 v[72:75], v[12:15], v[238:241], v[64:67]
	v_mfma_f32_16x16x32_bf16 v[64:67], v[16:19], v[234:237], v[210:213]
	v_mfma_f32_16x16x32_bf16 v[76:79], v[20:23], v[238:241], v[64:67]
	v_mfma_f32_16x16x32_bf16 v[64:67], v[166:169], v[24:27], v[96:99]
	v_mfma_f32_16x16x32_bf16 v[24:27], v[190:193], v[24:27], v[32:35]
	v_mfma_f32_16x16x32_bf16 v[112:115], v[218:221], v[28:31], v[24:27]
	v_mfma_f32_16x16x32_bf16 v[24:27], v[166:169], v[60:63], v[36:39]
	v_mfma_f32_16x16x32_bf16 v[100:103], v[186:189], v[222:225], v[24:27]
	v_mfma_f32_16x16x32_bf16 v[24:27], v[190:193], v[60:63], v[40:43]
	v_mfma_f32_16x16x32_bf16 v[96:99], v[218:221], v[222:225], v[24:27]
	v_mfma_f32_16x16x32_bf16 v[24:27], v[166:169], v[226:229], v[44:47]
	v_mfma_f32_16x16x32_bf16 v[84:87], v[186:189], v[230:233], v[24:27]
	v_mfma_f32_16x16x32_bf16 v[24:27], v[190:193], v[226:229], v[48:51]
	v_mfma_f32_16x16x32_bf16 v[80:83], v[218:221], v[230:233], v[24:27]
	v_mfma_f32_16x16x32_bf16 v[24:27], v[166:169], v[234:237], v[52:55]
	v_mfma_f32_16x16x32_bf16 v[68:71], v[186:189], v[238:241], v[24:27]
	v_mfma_f32_16x16x32_bf16 v[24:27], v[190:193], v[234:237], v[56:59]
	v_mfma_f32_16x16x32_bf16 v[116:119], v[186:189], v[28:31], v[64:67]
	v_mfma_f32_16x16x32_bf16 v[64:67], v[218:221], v[238:241], v[24:27]
	s_barrier
	s_setprio 0
	s_mov_b32 m0, s74
	s_nop 2
	v_lshl_add_u64 v[24:25], v[198:199], 0, s[36:37]
	s_add_u32 s6, s10, 0x10080
	ds_read_b128 v[32:35], v139 offset:49152
	ds_read_b128 v[36:39], v139 offset:50176
	ds_read_b128 v[206:209], v139 offset:51200
	ds_read_b128 v[210:213], v139 offset:52224
	ds_read_b128 v[222:225], v139 offset:53248
	ds_read_b128 v[226:229], v139 offset:54272
	ds_read_b128 v[230:233], v139 offset:55296
	ds_read_b128 v[234:237], v139 offset:56320
	global_load_lds_dwordx4 v[24:25], off
	v_lshl_add_u64 v[24:25], v[204:205], 0, s[36:37]
	s_mov_b32 m0, s60
	s_addc_u32 s7, s11, 0
	global_load_lds_dwordx4 v[24:25], off
	v_lshl_add_u64 v[24:25], s[6:7], 0, v[140:141]
	s_mov_b32 m0, s8
	s_nop 0
	global_load_lds_dwordx4 v[24:25], off
	v_lshl_add_u64 v[24:25], s[6:7], 0, v[128:129]
	s_mov_b32 m0, s9
	s_nop 0
	global_load_lds_dwordx4 v[24:25], off
	v_lshl_add_u64 v[24:25], v[242:243], 0, s[36:37]
	s_mov_b32 m0, s58
	s_nop 0
	global_load_lds_dwordx4 v[24:25], off
	v_lshl_add_u64 v[24:25], v[244:245], 0, s[36:37]
	s_mov_b32 m0, s59
	s_nop 0
	global_load_lds_dwordx4 v[24:25], off
	s_waitcnt vmcnt(8)
	s_waitcnt lgkmcnt(0)
	s_setprio 1
	s_barrier
	v_mfma_f32_16x16x32_bf16 v[24:27], v[8:11], v[32:35], v[134:137]
	v_mfma_f32_16x16x32_bf16 v[56:59], v[12:15], v[36:39], v[24:27]
	v_mfma_f32_16x16x32_bf16 v[24:27], v[16:19], v[32:35], v[142:145]
	v_mfma_f32_16x16x32_bf16 v[60:63], v[20:23], v[36:39], v[24:27]
	v_mfma_f32_16x16x32_bf16 v[24:27], v[8:11], v[206:209], v[146:149]
	v_mfma_f32_16x16x32_bf16 v[40:43], v[12:15], v[210:213], v[24:27]
	v_mfma_f32_16x16x32_bf16 v[24:27], v[16:19], v[206:209], v[150:153]
	v_mfma_f32_16x16x32_bf16 v[0:3], v[8:11], v[230:233], v[0:3]
	v_mfma_f32_16x16x32_bf16 v[44:47], v[20:23], v[210:213], v[24:27]
	v_mfma_f32_16x16x32_bf16 v[24:27], v[8:11], v[222:225], v[154:157]
	v_mfma_f32_16x16x32_bf16 v[28:31], v[16:19], v[222:225], v[158:161]
	v_mfma_f32_16x16x32_bf16 v[8:11], v[12:15], v[234:237], v[0:3]
	v_mfma_f32_16x16x32_bf16 v[0:3], v[16:19], v[230:233], v[4:7]
	v_mfma_f32_16x16x32_bf16 v[24:27], v[12:15], v[226:229], v[24:27]
	v_mfma_f32_16x16x32_bf16 v[28:31], v[20:23], v[226:229], v[28:31]
	v_mfma_f32_16x16x32_bf16 v[12:15], v[20:23], v[234:237], v[0:3]
	v_mfma_f32_16x16x32_bf16 v[0:3], v[166:169], v[32:35], v[194:197]
	v_mfma_f32_16x16x32_bf16 v[52:55], v[186:189], v[36:39], v[0:3]
	v_mfma_f32_16x16x32_bf16 v[0:3], v[190:193], v[32:35], v[200:203]
	v_mfma_f32_16x16x32_bf16 v[48:51], v[218:221], v[36:39], v[0:3]
	v_mfma_f32_16x16x32_bf16 v[0:3], v[166:169], v[206:209], v[214:217]
	v_mfma_f32_16x16x32_bf16 v[36:39], v[186:189], v[210:213], v[0:3]
	v_mfma_f32_16x16x32_bf16 v[0:3], v[190:193], v[206:209], v[170:173]
	v_mfma_f32_16x16x32_bf16 v[32:35], v[218:221], v[210:213], v[0:3]
	v_mfma_f32_16x16x32_bf16 v[0:3], v[166:169], v[222:225], v[174:177]
	v_mfma_f32_16x16x32_bf16 v[20:23], v[186:189], v[226:229], v[0:3]
	v_mfma_f32_16x16x32_bf16 v[0:3], v[190:193], v[222:225], v[178:181]
	v_mfma_f32_16x16x32_bf16 v[16:19], v[218:221], v[226:229], v[0:3]
	v_mfma_f32_16x16x32_bf16 v[0:3], v[166:169], v[230:233], v[182:185]
	v_mfma_f32_16x16x32_bf16 v[4:7], v[186:189], v[234:237], v[0:3]
	v_mfma_f32_16x16x32_bf16 v[0:3], v[190:193], v[230:233], v[162:165]
	v_mfma_f32_16x16x32_bf16 v[0:3], v[218:221], v[234:237], v[0:3]
	s_barrier
	s_setprio 0
	s_andn2_b64 vcc, exec, s[48:49]
	s_cbranch_vccnz .LBB0_459
	s_barrier

.LBB0_552:
	s_add_u32 s8, s6, 0xfffc0080
	s_addc_u32 s9, s7, -1
	s_add_i32 s35, 0, 0x10000
	s_cmp_eq_u32 s56, 12
	s_cselect_b32 s11, s4, s9
	s_cselect_b32 s10, s5, s8
	v_add_u32_e32 v140, s35, v165
	s_cselect_b32 s9, s24, s51
	s_cselect_b32 s8, s38, s47
	s_add_i32 s57, 0, 0x14000
	ds_read_b128 v[158:161], v140
	ds_read_b128 v[168:171], v140 offset:1024
	ds_read_b128 v[172:175], v140 offset:2048
	ds_read_b128 v[176:179], v140 offset:3072
	v_add_u32_e32 v140, s57, v165
	ds_read_b128 v[180:183], v140
	ds_read_b128 v[184:187], v140 offset:1024
	ds_read_b128 v[206:209], v140 offset:2048
	ds_read_b128 v[210:213], v140 offset:3072
	v_lshl_add_u64 v[142:143], s[6:7], 0, v[136:137]
	s_add_i32 m0, s66, 0xc000
	ds_read_b128 v[214:217], v166
	ds_read_b128 v[218:221], v166 offset:1024
	ds_read_b128 v[222:225], v166 offset:2048
	ds_read_b128 v[226:229], v166 offset:3072
	ds_read_b128 v[230:233], v166 offset:4096
	ds_read_b128 v[234:237], v166 offset:5120
	ds_read_b128 v[238:241], v166 offset:6144
	ds_read_b128 v[242:245], v166 offset:7168
	global_load_lds_dwordx4 v[142:143], off
	v_lshl_add_u64 v[142:143], s[6:7], 0, v[138:139]
	s_add_i32 m0, s66, 0xe000
	s_nop 0
	global_load_lds_dwordx4 v[142:143], off
	s_waitcnt vmcnt(8)
	s_waitcnt lgkmcnt(0)
	s_setprio 1
	s_barrier
	v_mfma_f32_16x16x32_bf16 v[124:127], v[158:161], v[214:217], v[124:127]
	v_mfma_f32_16x16x32_bf16 v[120:123], v[172:175], v[214:217], v[120:123]
	v_mfma_f32_16x16x32_bf16 v[108:111], v[158:161], v[222:225], v[108:111]
	v_mfma_f32_16x16x32_bf16 v[104:107], v[172:175], v[222:225], v[104:107]
	v_mfma_f32_16x16x32_bf16 v[92:95], v[158:161], v[230:233], v[92:95]
	v_mfma_f32_16x16x32_bf16 v[88:91], v[172:175], v[230:233], v[88:91]
	v_mfma_f32_16x16x32_bf16 v[76:79], v[158:161], v[238:241], v[76:79]
	v_mfma_f32_16x16x32_bf16 v[72:75], v[172:175], v[238:241], v[72:75]
	v_mfma_f32_16x16x32_bf16 v[124:127], v[168:171], v[218:221], v[124:127]
	v_mfma_f32_16x16x32_bf16 v[120:123], v[176:179], v[218:221], v[120:123]
	v_mfma_f32_16x16x32_bf16 v[108:111], v[168:171], v[226:229], v[108:111]
	v_mfma_f32_16x16x32_bf16 v[104:107], v[176:179], v[226:229], v[104:107]
	v_mfma_f32_16x16x32_bf16 v[92:95], v[168:171], v[234:237], v[92:95]
	v_mfma_f32_16x16x32_bf16 v[88:91], v[176:179], v[234:237], v[88:91]
	v_mfma_f32_16x16x32_bf16 v[76:79], v[168:171], v[242:245], v[76:79]
	v_mfma_f32_16x16x32_bf16 v[72:75], v[176:179], v[242:245], v[72:75]
	v_mfma_f32_16x16x32_bf16 v[116:119], v[180:183], v[214:217], v[116:119]
	v_mfma_f32_16x16x32_bf16 v[112:115], v[206:209], v[214:217], v[112:115]
	v_mfma_f32_16x16x32_bf16 v[100:103], v[180:183], v[222:225], v[100:103]
	v_mfma_f32_16x16x32_bf16 v[96:99], v[206:209], v[222:225], v[96:99]
	v_mfma_f32_16x16x32_bf16 v[84:87], v[180:183], v[230:233], v[84:87]
	v_mfma_f32_16x16x32_bf16 v[80:83], v[206:209], v[230:233], v[80:83]
	v_mfma_f32_16x16x32_bf16 v[68:71], v[180:183], v[238:241], v[68:71]
	v_mfma_f32_16x16x32_bf16 v[64:67], v[206:209], v[238:241], v[64:67]
	v_mfma_f32_16x16x32_bf16 v[116:119], v[184:187], v[218:221], v[116:119]
	v_mfma_f32_16x16x32_bf16 v[112:115], v[210:213], v[218:221], v[112:115]
	v_mfma_f32_16x16x32_bf16 v[100:103], v[184:187], v[226:229], v[100:103]
	v_mfma_f32_16x16x32_bf16 v[96:99], v[210:213], v[226:229], v[96:99]
	v_mfma_f32_16x16x32_bf16 v[84:87], v[184:187], v[234:237], v[84:87]
	v_mfma_f32_16x16x32_bf16 v[80:83], v[210:213], v[234:237], v[80:83]
	v_mfma_f32_16x16x32_bf16 v[68:71], v[184:187], v[242:245], v[68:71]
	v_mfma_f32_16x16x32_bf16 v[64:67], v[210:213], v[242:245], v[64:67]
	s_barrier
	s_setprio 0
	s_add_i32 s35, s35, s12
	v_lshl_add_u64 v[142:143], s[8:9], 0, v[132:133]
	s_mov_b32 m0, s35
	ds_read_b128 v[214:217], v166 offset:16384
	ds_read_b128 v[218:221], v166 offset:17408
	ds_read_b128 v[222:225], v166 offset:18432
	ds_read_b128 v[226:229], v166 offset:19456
	ds_read_b128 v[230:233], v166 offset:20480
	ds_read_b128 v[234:237], v166 offset:21504
	ds_read_b128 v[238:241], v166 offset:22528
	ds_read_b128 v[242:245], v166 offset:23552
	global_load_lds_dwordx4 v[142:143], off
	s_add_i32 m0, s35, 0x2000
	s_add_u32 s58, s8, 0x40000
	v_lshl_add_u64 v[144:145], s[8:9], 0, v[128:129]
	s_addc_u32 s59, s9, 0
	s_add_i32 s35, s57, s12
	global_load_lds_dwordx4 v[144:145], off
	v_lshl_add_u64 v[146:147], s[58:59], 0, v[132:133]
	s_mov_b32 m0, s35
	v_lshl_add_u64 v[148:149], s[10:11], 0, v[130:131]
	global_load_lds_dwordx4 v[146:147], off
	v_lshl_add_u64 v[146:147], s[58:59], 0, v[128:129]
	s_add_i32 m0, s35, 0x2000
	s_nop 0
	global_load_lds_dwordx4 v[146:147], off
	v_lshl_add_u64 v[146:147], s[10:11], 0, v[134:135]
	s_mov_b32 m0, s66
	s_nop 0
	global_load_lds_dwordx4 v[146:147], off
	s_mov_b32 m0, s67
	s_nop 0
	global_load_lds_dwordx4 v[148:149], off
	s_waitcnt vmcnt(8)
	s_waitcnt lgkmcnt(0)
	s_setprio 1
	s_barrier
	v_mfma_f32_16x16x32_bf16 v[60:63], v[158:161], v[214:217], v[60:63]
	v_mfma_f32_16x16x32_bf16 v[56:59], v[172:175], v[214:217], v[56:59]
	v_mfma_f32_16x16x32_bf16 v[44:47], v[158:161], v[222:225], v[44:47]
	v_mfma_f32_16x16x32_bf16 v[40:43], v[172:175], v[222:225], v[40:43]
	v_mfma_f32_16x16x32_bf16 v[28:31], v[158:161], v[230:233], v[28:31]
	v_mfma_f32_16x16x32_bf16 v[24:27], v[172:175], v[230:233], v[24:27]
	v_mfma_f32_16x16x32_bf16 v[12:15], v[158:161], v[238:241], v[12:15]
	v_mfma_f32_16x16x32_bf16 v[8:11], v[172:175], v[238:241], v[8:11]
	v_mfma_f32_16x16x32_bf16 v[60:63], v[168:171], v[218:221], v[60:63]
	v_mfma_f32_16x16x32_bf16 v[56:59], v[176:179], v[218:221], v[56:59]
	v_mfma_f32_16x16x32_bf16 v[44:47], v[168:171], v[226:229], v[44:47]
	v_mfma_f32_16x16x32_bf16 v[40:43], v[176:179], v[226:229], v[40:43]
	v_mfma_f32_16x16x32_bf16 v[28:31], v[168:171], v[234:237], v[28:31]
	v_mfma_f32_16x16x32_bf16 v[24:27], v[176:179], v[234:237], v[24:27]
	v_mfma_f32_16x16x32_bf16 v[12:15], v[168:171], v[242:245], v[12:15]
	v_mfma_f32_16x16x32_bf16 v[8:11], v[176:179], v[242:245], v[8:11]
	v_mfma_f32_16x16x32_bf16 v[52:55], v[180:183], v[214:217], v[52:55]
	v_mfma_f32_16x16x32_bf16 v[48:51], v[206:209], v[214:217], v[48:51]
	v_mfma_f32_16x16x32_bf16 v[36:39], v[180:183], v[222:225], v[36:39]
	v_mfma_f32_16x16x32_bf16 v[32:35], v[206:209], v[222:225], v[32:35]
	v_mfma_f32_16x16x32_bf16 v[20:23], v[180:183], v[230:233], v[20:23]
	v_mfma_f32_16x16x32_bf16 v[16:19], v[206:209], v[230:233], v[16:19]
	v_mfma_f32_16x16x32_bf16 v[4:7], v[180:183], v[238:241], v[4:7]
	v_mfma_f32_16x16x32_bf16 v[0:3], v[206:209], v[238:241], v[0:3]
	v_mfma_f32_16x16x32_bf16 v[52:55], v[184:187], v[218:221], v[52:55]
	v_mfma_f32_16x16x32_bf16 v[48:51], v[210:213], v[218:221], v[48:51]
	v_mfma_f32_16x16x32_bf16 v[36:39], v[184:187], v[226:229], v[36:39]
	v_mfma_f32_16x16x32_bf16 v[32:35], v[210:213], v[226:229], v[32:35]
	v_mfma_f32_16x16x32_bf16 v[20:23], v[184:187], v[234:237], v[20:23]
	v_mfma_f32_16x16x32_bf16 v[16:19], v[210:213], v[234:237], v[16:19]
	v_mfma_f32_16x16x32_bf16 v[4:7], v[184:187], v[242:245], v[4:7]
	v_mfma_f32_16x16x32_bf16 v[0:3], v[210:213], v[242:245], v[0:3]
	s_barrier
	s_setprio 0
	s_add_i32 s35, 0, 0x18000
	v_add_u32_e32 v140, s35, v165
	s_add_i32 s57, 0, 0x1c000
	ds_read_b128 v[158:161], v140
	ds_read_b128 v[168:171], v140 offset:1024
	ds_read_b128 v[172:175], v140 offset:2048
	ds_read_b128 v[176:179], v140 offset:3072
	v_add_u32_e32 v140, s57, v165
	ds_read_b128 v[180:183], v140
	ds_read_b128 v[184:187], v140 offset:1024
	ds_read_b128 v[206:209], v140 offset:2048
	ds_read_b128 v[210:213], v140 offset:3072
	s_add_u32 s10, s10, 0x40000
	s_addc_u32 s11, s11, 0
	s_mov_b32 m0, s74
	v_lshl_add_u64 v[150:151], s[10:11], 0, v[134:135]
	ds_read_b128 v[214:217], v166 offset:32768
	ds_read_b128 v[218:221], v166 offset:33792
	ds_read_b128 v[222:225], v166 offset:34816
	ds_read_b128 v[226:229], v166 offset:35840
	ds_read_b128 v[230:233], v166 offset:36864
	ds_read_b128 v[234:237], v166 offset:37888
	ds_read_b128 v[238:241], v166 offset:38912
	ds_read_b128 v[242:245], v166 offset:39936
	global_load_lds_dwordx4 v[150:151], off
	v_lshl_add_u64 v[150:151], s[10:11], 0, v[130:131]
	s_mov_b32 m0, s75
	s_nop 0
	global_load_lds_dwordx4 v[150:151], off
	s_waitcnt vmcnt(8)
	s_waitcnt lgkmcnt(0)
	s_setprio 1
	s_barrier
	v_mfma_f32_16x16x32_bf16 v[124:127], v[158:161], v[214:217], v[124:127]
	v_mfma_f32_16x16x32_bf16 v[120:123], v[172:175], v[214:217], v[120:123]
	v_mfma_f32_16x16x32_bf16 v[108:111], v[158:161], v[222:225], v[108:111]
	v_mfma_f32_16x16x32_bf16 v[104:107], v[172:175], v[222:225], v[104:107]
	v_mfma_f32_16x16x32_bf16 v[92:95], v[158:161], v[230:233], v[92:95]
	v_mfma_f32_16x16x32_bf16 v[88:91], v[172:175], v[230:233], v[88:91]
	v_mfma_f32_16x16x32_bf16 v[76:79], v[158:161], v[238:241], v[76:79]
	v_mfma_f32_16x16x32_bf16 v[72:75], v[172:175], v[238:241], v[72:75]
	v_mfma_f32_16x16x32_bf16 v[124:127], v[168:171], v[218:221], v[124:127]
	v_mfma_f32_16x16x32_bf16 v[120:123], v[176:179], v[218:221], v[120:123]
	v_mfma_f32_16x16x32_bf16 v[108:111], v[168:171], v[226:229], v[108:111]
	v_mfma_f32_16x16x32_bf16 v[104:107], v[176:179], v[226:229], v[104:107]
	v_mfma_f32_16x16x32_bf16 v[92:95], v[168:171], v[234:237], v[92:95]
	v_mfma_f32_16x16x32_bf16 v[88:91], v[176:179], v[234:237], v[88:91]
	v_mfma_f32_16x16x32_bf16 v[76:79], v[168:171], v[242:245], v[76:79]
	v_mfma_f32_16x16x32_bf16 v[72:75], v[176:179], v[242:245], v[72:75]
	v_mfma_f32_16x16x32_bf16 v[116:119], v[180:183], v[214:217], v[116:119]
	v_mfma_f32_16x16x32_bf16 v[112:115], v[206:209], v[214:217], v[112:115]
	v_mfma_f32_16x16x32_bf16 v[100:103], v[180:183], v[222:225], v[100:103]
	v_mfma_f32_16x16x32_bf16 v[96:99], v[206:209], v[222:225], v[96:99]
	v_mfma_f32_16x16x32_bf16 v[84:87], v[180:183], v[230:233], v[84:87]
	v_mfma_f32_16x16x32_bf16 v[80:83], v[206:209], v[230:233], v[80:83]
	v_mfma_f32_16x16x32_bf16 v[68:71], v[180:183], v[238:241], v[68:71]
	v_mfma_f32_16x16x32_bf16 v[64:67], v[206:209], v[238:241], v[64:67]
	v_mfma_f32_16x16x32_bf16 v[116:119], v[184:187], v[218:221], v[116:119]
	v_mfma_f32_16x16x32_bf16 v[112:115], v[210:213], v[218:221], v[112:115]
	v_mfma_f32_16x16x32_bf16 v[100:103], v[184:187], v[226:229], v[100:103]
	v_mfma_f32_16x16x32_bf16 v[96:99], v[210:213], v[226:229], v[96:99]
	v_mfma_f32_16x16x32_bf16 v[84:87], v[184:187], v[234:237], v[84:87]
	v_mfma_f32_16x16x32_bf16 v[80:83], v[210:213], v[234:237], v[80:83]
	v_mfma_f32_16x16x32_bf16 v[68:71], v[184:187], v[242:245], v[68:71]
	v_mfma_f32_16x16x32_bf16 v[64:67], v[210:213], v[242:245], v[64:67]
	s_barrier
	s_setprio 0
	s_add_i32 s10, s35, s12
	v_lshl_add_u64 v[142:143], v[142:143], 0, s[36:37]
	s_mov_b32 m0, s10
	ds_read_b128 v[214:217], v166 offset:49152
	ds_read_b128 v[218:221], v166 offset:50176
	ds_read_b128 v[222:225], v166 offset:51200
	ds_read_b128 v[226:229], v166 offset:52224
	ds_read_b128 v[230:233], v166 offset:53248
	ds_read_b128 v[234:237], v166 offset:54272
	ds_read_b128 v[238:241], v166 offset:55296
	ds_read_b128 v[242:245], v166 offset:56320
	global_load_lds_dwordx4 v[142:143], off
	s_add_i32 m0, s10, 0x2000
	s_add_u32 s8, s8, 0x40080
	v_lshl_add_u64 v[142:143], v[144:145], 0, s[36:37]
	s_addc_u32 s9, s9, 0
	s_add_i32 s10, s57, s12
	global_load_lds_dwordx4 v[142:143], off
	v_lshl_add_u64 v[142:143], s[8:9], 0, v[132:133]
	s_mov_b32 m0, s10
	s_nop 0
	global_load_lds_dwordx4 v[142:143], off
	v_lshl_add_u64 v[142:143], s[8:9], 0, v[128:129]
	s_add_i32 m0, s10, 0x2000
	s_nop 0
	global_load_lds_dwordx4 v[142:143], off
	v_lshl_add_u64 v[142:143], v[146:147], 0, s[36:37]
	s_mov_b32 m0, s26
	s_nop 0
	global_load_lds_dwordx4 v[142:143], off
	v_lshl_add_u64 v[142:143], v[148:149], 0, s[36:37]
	s_mov_b32 m0, s27
	s_nop 0
	global_load_lds_dwordx4 v[142:143], off
	s_waitcnt vmcnt(8)
	s_waitcnt lgkmcnt(0)
	s_setprio 1
	s_barrier
	v_mfma_f32_16x16x32_bf16 v[60:63], v[158:161], v[214:217], v[60:63]
	v_mfma_f32_16x16x32_bf16 v[56:59], v[172:175], v[214:217], v[56:59]
	v_mfma_f32_16x16x32_bf16 v[44:47], v[158:161], v[222:225], v[44:47]
	v_mfma_f32_16x16x32_bf16 v[40:43], v[172:175], v[222:225], v[40:43]
	v_mfma_f32_16x16x32_bf16 v[28:31], v[158:161], v[230:233], v[28:31]
	v_mfma_f32_16x16x32_bf16 v[24:27], v[172:175], v[230:233], v[24:27]
	v_mfma_f32_16x16x32_bf16 v[12:15], v[158:161], v[238:241], v[12:15]
	v_mfma_f32_16x16x32_bf16 v[8:11], v[172:175], v[238:241], v[8:11]
	v_mfma_f32_16x16x32_bf16 v[60:63], v[168:171], v[218:221], v[60:63]
	v_mfma_f32_16x16x32_bf16 v[56:59], v[176:179], v[218:221], v[56:59]
	v_mfma_f32_16x16x32_bf16 v[44:47], v[168:171], v[226:229], v[44:47]
	v_mfma_f32_16x16x32_bf16 v[40:43], v[176:179], v[226:229], v[40:43]
	v_mfma_f32_16x16x32_bf16 v[28:31], v[168:171], v[234:237], v[28:31]
	v_mfma_f32_16x16x32_bf16 v[24:27], v[176:179], v[234:237], v[24:27]
	v_mfma_f32_16x16x32_bf16 v[12:15], v[168:171], v[242:245], v[12:15]
	v_mfma_f32_16x16x32_bf16 v[8:11], v[176:179], v[242:245], v[8:11]
	v_mfma_f32_16x16x32_bf16 v[52:55], v[180:183], v[214:217], v[52:55]
	v_mfma_f32_16x16x32_bf16 v[48:51], v[206:209], v[214:217], v[48:51]
	v_mfma_f32_16x16x32_bf16 v[36:39], v[180:183], v[222:225], v[36:39]
	v_mfma_f32_16x16x32_bf16 v[32:35], v[206:209], v[222:225], v[32:35]
	v_mfma_f32_16x16x32_bf16 v[20:23], v[180:183], v[230:233], v[20:23]
	v_mfma_f32_16x16x32_bf16 v[16:19], v[206:209], v[230:233], v[16:19]
	v_mfma_f32_16x16x32_bf16 v[4:7], v[180:183], v[238:241], v[4:7]
	v_mfma_f32_16x16x32_bf16 v[0:3], v[206:209], v[238:241], v[0:3]
	v_mfma_f32_16x16x32_bf16 v[52:55], v[184:187], v[218:221], v[52:55]
	v_mfma_f32_16x16x32_bf16 v[48:51], v[210:213], v[218:221], v[48:51]
	v_mfma_f32_16x16x32_bf16 v[36:39], v[184:187], v[226:229], v[36:39]
	v_mfma_f32_16x16x32_bf16 v[32:35], v[210:213], v[226:229], v[32:35]
	v_mfma_f32_16x16x32_bf16 v[20:23], v[184:187], v[234:237], v[20:23]
	v_mfma_f32_16x16x32_bf16 v[16:19], v[210:213], v[234:237], v[16:19]
	v_mfma_f32_16x16x32_bf16 v[4:7], v[184:187], v[242:245], v[4:7]
	v_mfma_f32_16x16x32_bf16 v[0:3], v[210:213], v[242:245], v[0:3]
	s_barrier
	s_setprio 0
	s_add_i32 s56, s56, 2
	s_add_u32 s6, s6, 0x100
	s_addc_u32 s7, s7, 0
	s_add_u32 s47, s47, 0x100
	s_addc_u32 s51, s51, 0
	s_cmp_gt_u32 s56, 13
	s_cbranch_scc0 .LBB0_552
	s_and_b64 vcc, exec, s[44:45]
	s_cbranch_vccz .LBB0_555
	s_barrier

.LBB0_676:
	s_lshl_b32 s12, s61, 22
	s_and_b32 s35, s12, 0x3c00000
	s_ashr_i32 s12, s61, 4
	s_ashr_i32 s13, s12, 31
	s_lshl_b64 s[12:13], s[12:13], 9
	s_add_u32 s35, s14, s35
	s_addc_u32 s53, s15, 0
	s_add_u32 s54, s35, s12
	s_addc_u32 s55, s53, s13
	s_and_b64 s[56:57], s[42:43], exec
	s_cselect_b32 s59, s55, s9
	s_cselect_b32 s58, s54, s8
	s_ashr_i32 s53, s52, 31
	s_lshl_b64 s[56:57], s[52:53], 19
	s_add_u32 s35, s26, s56
	s_addc_u32 s53, s27, s57
	s_add_u32 s56, s35, s12
	s_addc_u32 s57, s53, s13
	s_and_b64 s[12:13], s[42:43], exec
	s_cselect_b32 s13, s57, s11
	s_cselect_b32 s12, s56, s10
	s_add_i32 s70, 0, 0x10000
	s_add_i32 s71, 0, 0x14000
	v_add_u32_e32 v152, s70, v138
	v_add_u32_e32 v153, s71, v138
	ds_read_b128 v[0:3], v152
	ds_read_b128 v[4:7], v152 offset:1024
	ds_read_b128 v[8:11], v152 offset:2048
	ds_read_b128 v[12:15], v152 offset:3072
	ds_read_b128 v[16:19], v153
	ds_read_b128 v[20:23], v153 offset:1024
	ds_read_b128 v[24:27], v153 offset:2048
	ds_read_b128 v[28:31], v153 offset:3072
	v_mov_b32_e32 v204, 0x358637bd
	v_mov_b32_e32 v250, 0x260
	v_mov_b32_e32 v251, 0x3e124925
	s_add_u32 s68, s8, 0x200080
	s_addc_u32 s69, s9, 0
	s_add_i32 s72, s4, 0xc000
	v_lshl_add_u64 v[64:65], s[68:69], 0, v[132:133]
	s_mov_b32 m0, s72
	s_add_i32 s35, s4, 0xe000
	ds_read_b128 v[32:35], v139
	ds_read_b128 v[36:39], v139 offset:1024
	ds_read_b128 v[40:43], v139 offset:2048
	ds_read_b128 v[44:47], v139 offset:3072
	ds_read_b128 v[48:51], v139 offset:4096
	ds_read_b128 v[52:55], v139 offset:5120
	ds_read_b128 v[56:59], v139 offset:6144
	ds_read_b128 v[60:63], v139 offset:7168
	global_load_lds_dwordx4 v[64:65], off
	v_lshl_add_u64 v[64:65], s[68:69], 0, v[130:131]
	s_mov_b32 m0, s35
	s_nop 0
	global_load_lds_dwordx4 v[64:65], off
	s_waitcnt vmcnt(8)
	s_waitcnt lgkmcnt(0)
	s_setprio 1
	s_barrier
	v_mfma_f32_16x16x32_bf16 v[64:67], v[0:3], v[32:35], 0
	v_mfma_f32_16x16x32_bf16 v[68:71], v[8:11], v[32:35], 0
	v_mfma_f32_16x16x32_bf16 v[72:75], v[0:3], v[40:43], 0
	v_mfma_f32_16x16x32_bf16 v[76:79], v[8:11], v[40:43], 0
	v_mfma_f32_16x16x32_bf16 v[80:83], v[0:3], v[48:51], 0
	v_mfma_f32_16x16x32_bf16 v[84:87], v[8:11], v[48:51], 0
	v_mfma_f32_16x16x32_bf16 v[88:91], v[0:3], v[56:59], 0
	v_mfma_f32_16x16x32_bf16 v[92:95], v[8:11], v[56:59], 0
	v_mfma_f32_16x16x32_bf16 v[64:67], v[4:7], v[36:39], v[64:67]
	v_mfma_f32_16x16x32_bf16 v[68:71], v[12:15], v[36:39], v[68:71]
	v_mfma_f32_16x16x32_bf16 v[72:75], v[4:7], v[44:47], v[72:75]
	v_mfma_f32_16x16x32_bf16 v[76:79], v[12:15], v[44:47], v[76:79]
	v_mfma_f32_16x16x32_bf16 v[80:83], v[4:7], v[52:55], v[80:83]
	v_mfma_f32_16x16x32_bf16 v[84:87], v[12:15], v[52:55], v[84:87]
	v_mfma_f32_16x16x32_bf16 v[88:91], v[4:7], v[60:63], v[88:91]
	v_mfma_f32_16x16x32_bf16 v[92:95], v[12:15], v[60:63], v[92:95]
	v_mfma_f32_16x16x32_bf16 v[96:99], v[16:19], v[32:35], 0
	v_mfma_f32_16x16x32_bf16 v[32:35], v[24:27], v[32:35], 0
	v_mfma_f32_16x16x32_bf16 v[96:99], v[20:23], v[36:39], v[96:99]
	v_mfma_f32_16x16x32_bf16 v[32:35], v[28:31], v[36:39], v[32:35]
	v_mfma_f32_16x16x32_bf16 v[36:39], v[16:19], v[40:43], 0
	v_mfma_f32_16x16x32_bf16 v[40:43], v[24:27], v[40:43], 0
	v_mfma_f32_16x16x32_bf16 v[36:39], v[20:23], v[44:47], v[36:39]
	v_mfma_f32_16x16x32_bf16 v[40:43], v[28:31], v[44:47], v[40:43]
	v_mfma_f32_16x16x32_bf16 v[44:47], v[16:19], v[48:51], 0
	v_mfma_f32_16x16x32_bf16 v[48:51], v[24:27], v[48:51], 0
	v_mfma_f32_16x16x32_bf16 v[44:47], v[20:23], v[52:55], v[44:47]
	v_mfma_f32_16x16x32_bf16 v[48:51], v[28:31], v[52:55], v[48:51]
	v_mfma_f32_16x16x32_bf16 v[52:55], v[16:19], v[56:59], 0
	v_mfma_f32_16x16x32_bf16 v[56:59], v[24:27], v[56:59], 0
	v_mfma_f32_16x16x32_bf16 v[52:55], v[20:23], v[60:63], v[52:55]
	v_mfma_f32_16x16x32_bf16 v[56:59], v[28:31], v[60:63], v[56:59]
	s_barrier
	s_setprio 0
	s_add_i32 s70, s70, s28
	v_lshl_add_u64 v[142:143], s[10:11], 0, v[140:141]
	s_mov_b64 s[2:3], 0x100
	s_add_i32 s53, s70, 0x2000
	v_lshl_add_u64 v[134:135], v[142:143], 0, s[2:3]
	s_mov_b32 m0, s70
	v_lshl_add_u64 v[144:145], s[10:11], 0, v[128:129]
	s_add_u32 s74, s10, 0x40100
	ds_read_b128 v[60:63], v139 offset:16384
	ds_read_b128 v[100:103], v139 offset:17408
	ds_read_b128 v[104:107], v139 offset:18432
	ds_read_b128 v[108:111], v139 offset:19456
	ds_read_b128 v[112:115], v139 offset:20480
	ds_read_b128 v[116:119], v139 offset:21504
	ds_read_b128 v[120:123], v139 offset:22528
	ds_read_b128 v[124:127], v139 offset:23552
	global_load_lds_dwordx4 v[134:135], off
	v_lshl_add_u64 v[134:135], v[144:145], 0, s[2:3]
	s_mov_b32 m0, s53
	s_addc_u32 s75, s11, 0
	s_add_i32 s68, s71, s28
	global_load_lds_dwordx4 v[134:135], off
	v_lshl_add_u64 v[134:135], s[74:75], 0, v[140:141]
	s_mov_b32 m0, s68
	s_add_i32 s69, s68, 0x2000
	global_load_lds_dwordx4 v[134:135], off
	v_lshl_add_u64 v[134:135], s[74:75], 0, v[128:129]
	s_mov_b32 m0, s69
	v_lshl_add_u64 v[146:147], s[8:9], 0, v[132:133]
	global_load_lds_dwordx4 v[134:135], off
	v_lshl_add_u64 v[134:135], v[146:147], 0, s[2:3]
	s_mov_b32 m0, s4
	v_lshl_add_u64 v[148:149], s[8:9], 0, v[130:131]
	global_load_lds_dwordx4 v[134:135], off
	v_lshl_add_u64 v[134:135], v[148:149], 0, s[2:3]
	s_mov_b32 m0, s5
	s_nop 0
	global_load_lds_dwordx4 v[134:135], off
	s_waitcnt vmcnt(8)
	s_waitcnt lgkmcnt(0)
	s_setprio 1
	s_barrier
	v_mfma_f32_16x16x32_bf16 v[134:137], v[0:3], v[60:63], 0
	v_mfma_f32_16x16x32_bf16 v[162:165], v[0:3], v[104:107], 0
	v_mfma_f32_16x16x32_bf16 v[170:173], v[0:3], v[112:115], 0
	v_mfma_f32_16x16x32_bf16 v[0:3], v[0:3], v[120:123], 0
	v_mfma_f32_16x16x32_bf16 v[134:137], v[4:7], v[100:103], v[134:137]
	v_mfma_f32_16x16x32_bf16 v[162:165], v[4:7], v[108:111], v[162:165]
	v_mfma_f32_16x16x32_bf16 v[170:173], v[4:7], v[116:119], v[170:173]
	v_mfma_f32_16x16x32_bf16 v[0:3], v[4:7], v[124:127], v[0:3]
	v_mfma_f32_16x16x32_bf16 v[4:7], v[8:11], v[120:123], 0
	v_mfma_f32_16x16x32_bf16 v[158:161], v[8:11], v[60:63], 0
	v_mfma_f32_16x16x32_bf16 v[166:169], v[8:11], v[104:107], 0
	v_mfma_f32_16x16x32_bf16 v[174:177], v[8:11], v[112:115], 0
	v_mfma_f32_16x16x32_bf16 v[4:7], v[12:15], v[124:127], v[4:7]
	v_mfma_f32_16x16x32_bf16 v[158:161], v[12:15], v[100:103], v[158:161]
	v_mfma_f32_16x16x32_bf16 v[166:169], v[12:15], v[108:111], v[166:169]
	v_mfma_f32_16x16x32_bf16 v[174:177], v[12:15], v[116:119], v[174:177]
	v_mfma_f32_16x16x32_bf16 v[8:11], v[16:19], v[60:63], 0
	v_mfma_f32_16x16x32_bf16 v[12:15], v[24:27], v[60:63], 0
	v_mfma_f32_16x16x32_bf16 v[8:11], v[20:23], v[100:103], v[8:11]
	v_mfma_f32_16x16x32_bf16 v[12:15], v[28:31], v[100:103], v[12:15]
	v_mfma_f32_16x16x32_bf16 v[60:63], v[16:19], v[104:107], 0
	v_mfma_f32_16x16x32_bf16 v[100:103], v[24:27], v[104:107], 0
	v_mfma_f32_16x16x32_bf16 v[104:107], v[16:19], v[112:115], 0
	v_mfma_f32_16x16x32_bf16 v[16:19], v[16:19], v[120:123], 0
	v_mfma_f32_16x16x32_bf16 v[60:63], v[20:23], v[108:111], v[60:63]
	v_mfma_f32_16x16x32_bf16 v[100:103], v[28:31], v[108:111], v[100:103]
	v_mfma_f32_16x16x32_bf16 v[104:107], v[20:23], v[116:119], v[104:107]
	v_mfma_f32_16x16x32_bf16 v[108:111], v[24:27], v[112:115], 0
	v_mfma_f32_16x16x32_bf16 v[16:19], v[20:23], v[124:127], v[16:19]
	v_mfma_f32_16x16x32_bf16 v[20:23], v[24:27], v[120:123], 0
	v_mfma_f32_16x16x32_bf16 v[108:111], v[28:31], v[116:119], v[108:111]
	v_mfma_f32_16x16x32_bf16 v[20:23], v[28:31], v[124:127], v[20:23]
	s_barrier
	s_setprio 0
	s_add_i32 s73, 0, 0x18000
	s_add_i32 s76, 0, 0x1c000
	v_add_u32_e32 v154, s73, v138
	v_add_u32_e32 v155, s76, v138
	ds_read_b128 v[24:27], v154
	ds_read_b128 v[28:31], v154 offset:1024
	ds_read_b128 v[112:115], v154 offset:2048
	ds_read_b128 v[116:119], v154 offset:3072
	ds_read_b128 v[120:123], v155
	ds_read_b128 v[124:127], v155 offset:1024
	ds_read_b128 v[178:181], v155 offset:2048
	ds_read_b128 v[182:185], v155 offset:3072
	s_add_u32 s74, s8, 0x200100
	s_addc_u32 s75, s9, 0
	s_mov_b32 m0, s24
	v_lshl_add_u64 v[150:151], s[74:75], 0, v[132:133]
	ds_read_b128 v[206:209], v139 offset:32768
	ds_read_b128 v[210:213], v139 offset:33792
	ds_read_b128 v[214:217], v139 offset:34816
	ds_read_b128 v[218:221], v139 offset:35840
	ds_read_b128 v[222:225], v139 offset:36864
	ds_read_b128 v[226:229], v139 offset:37888
	ds_read_b128 v[230:233], v139 offset:38912
	ds_read_b128 v[234:237], v139 offset:39936
	global_load_lds_dwordx4 v[150:151], off
	v_lshl_add_u64 v[150:151], s[74:75], 0, v[130:131]
	s_mov_b32 m0, s29
	s_nop 0
	global_load_lds_dwordx4 v[150:151], off
	s_waitcnt vmcnt(8)
	s_waitcnt lgkmcnt(0)
	s_setprio 1
	s_barrier
	v_mfma_f32_16x16x32_bf16 v[64:67], v[24:27], v[206:209], v[64:67]
	v_mfma_f32_16x16x32_bf16 v[68:71], v[112:115], v[206:209], v[68:71]
	v_mfma_f32_16x16x32_bf16 v[72:75], v[24:27], v[214:217], v[72:75]
	v_mfma_f32_16x16x32_bf16 v[76:79], v[112:115], v[214:217], v[76:79]
	v_mfma_f32_16x16x32_bf16 v[80:83], v[24:27], v[222:225], v[80:83]
	v_mfma_f32_16x16x32_bf16 v[84:87], v[112:115], v[222:225], v[84:87]
	v_mfma_f32_16x16x32_bf16 v[88:91], v[24:27], v[230:233], v[88:91]
	v_mfma_f32_16x16x32_bf16 v[92:95], v[112:115], v[230:233], v[92:95]
	v_mfma_f32_16x16x32_bf16 v[64:67], v[28:31], v[210:213], v[64:67]
	v_mfma_f32_16x16x32_bf16 v[68:71], v[116:119], v[210:213], v[68:71]
	v_mfma_f32_16x16x32_bf16 v[72:75], v[28:31], v[218:221], v[72:75]
	v_mfma_f32_16x16x32_bf16 v[76:79], v[116:119], v[218:221], v[76:79]
	v_mfma_f32_16x16x32_bf16 v[80:83], v[28:31], v[226:229], v[80:83]
	v_mfma_f32_16x16x32_bf16 v[84:87], v[116:119], v[226:229], v[84:87]
	v_mfma_f32_16x16x32_bf16 v[88:91], v[28:31], v[234:237], v[88:91]
	v_mfma_f32_16x16x32_bf16 v[92:95], v[116:119], v[234:237], v[92:95]
	v_mfma_f32_16x16x32_bf16 v[96:99], v[120:123], v[206:209], v[96:99]
	v_mfma_f32_16x16x32_bf16 v[32:35], v[178:181], v[206:209], v[32:35]
	v_mfma_f32_16x16x32_bf16 v[36:39], v[120:123], v[214:217], v[36:39]
	v_mfma_f32_16x16x32_bf16 v[40:43], v[178:181], v[214:217], v[40:43]
	v_mfma_f32_16x16x32_bf16 v[44:47], v[120:123], v[222:225], v[44:47]
	v_mfma_f32_16x16x32_bf16 v[48:51], v[178:181], v[222:225], v[48:51]
	v_mfma_f32_16x16x32_bf16 v[52:55], v[120:123], v[230:233], v[52:55]
	v_mfma_f32_16x16x32_bf16 v[56:59], v[178:181], v[230:233], v[56:59]
	v_mfma_f32_16x16x32_bf16 v[96:99], v[124:127], v[210:213], v[96:99]
	v_mfma_f32_16x16x32_bf16 v[32:35], v[182:185], v[210:213], v[32:35]
	v_mfma_f32_16x16x32_bf16 v[36:39], v[124:127], v[218:221], v[36:39]
	v_mfma_f32_16x16x32_bf16 v[40:43], v[182:185], v[218:221], v[40:43]
	v_mfma_f32_16x16x32_bf16 v[44:47], v[124:127], v[226:229], v[44:47]
	v_mfma_f32_16x16x32_bf16 v[48:51], v[182:185], v[226:229], v[48:51]
	v_mfma_f32_16x16x32_bf16 v[52:55], v[124:127], v[234:237], v[52:55]
	v_mfma_f32_16x16x32_bf16 v[56:59], v[182:185], v[234:237], v[56:59]
	s_barrier
	s_setprio 0
	s_add_i32 s73, s73, s28
	s_mov_b64 s[2:3], 0x180
	s_add_i32 s71, s73, 0x2000
	v_lshl_add_u64 v[142:143], v[142:143], 0, s[2:3]
	s_mov_b32 m0, s73
	s_add_u32 s74, s10, 0x40180
	ds_read_b128 v[206:209], v139 offset:49152
	ds_read_b128 v[210:213], v139 offset:50176
	ds_read_b128 v[214:217], v139 offset:51200
	ds_read_b128 v[218:221], v139 offset:52224
	ds_read_b128 v[222:225], v139 offset:53248
	ds_read_b128 v[226:229], v139 offset:54272
	ds_read_b128 v[230:233], v139 offset:55296
	ds_read_b128 v[234:237], v139 offset:56320
	global_load_lds_dwordx4 v[142:143], off
	v_lshl_add_u64 v[142:143], v[144:145], 0, s[2:3]
	s_mov_b32 m0, s71
	s_addc_u32 s75, s11, 0
	s_add_i32 s10, s76, s28
	global_load_lds_dwordx4 v[142:143], off
	v_lshl_add_u64 v[142:143], s[74:75], 0, v[140:141]
	s_mov_b32 m0, s10
	s_add_i32 s11, s10, 0x2000
	global_load_lds_dwordx4 v[142:143], off
	v_lshl_add_u64 v[142:143], s[74:75], 0, v[128:129]
	s_mov_b32 m0, s11
	s_nop 0
	global_load_lds_dwordx4 v[142:143], off
	v_lshl_add_u64 v[142:143], v[146:147], 0, s[2:3]
	s_mov_b32 m0, s38
	s_nop 0
	global_load_lds_dwordx4 v[142:143], off
	v_lshl_add_u64 v[142:143], v[148:149], 0, s[2:3]
	s_mov_b32 m0, s60
	s_nop 0
	global_load_lds_dwordx4 v[142:143], off
	s_waitcnt vmcnt(8)
	s_waitcnt lgkmcnt(0)
	s_setprio 1
	s_barrier
	v_mfma_f32_16x16x32_bf16 v[0:3], v[24:27], v[230:233], v[0:3]
	v_mfma_f32_16x16x32_bf16 v[4:7], v[112:115], v[230:233], v[4:7]
	v_mfma_f32_16x16x32_bf16 v[134:137], v[24:27], v[206:209], v[134:137]
	v_mfma_f32_16x16x32_bf16 v[158:161], v[112:115], v[206:209], v[158:161]
	v_mfma_f32_16x16x32_bf16 v[162:165], v[24:27], v[214:217], v[162:165]
	v_mfma_f32_16x16x32_bf16 v[166:169], v[112:115], v[214:217], v[166:169]
	v_mfma_f32_16x16x32_bf16 v[170:173], v[24:27], v[222:225], v[170:173]
	v_mfma_f32_16x16x32_bf16 v[174:177], v[112:115], v[222:225], v[174:177]
	v_mfma_f32_16x16x32_bf16 v[0:3], v[28:31], v[234:237], v[0:3]
	v_mfma_f32_16x16x32_bf16 v[4:7], v[116:119], v[234:237], v[4:7]
	v_mfma_f32_16x16x32_bf16 v[134:137], v[28:31], v[210:213], v[134:137]
	v_mfma_f32_16x16x32_bf16 v[158:161], v[116:119], v[210:213], v[158:161]
	v_mfma_f32_16x16x32_bf16 v[162:165], v[28:31], v[218:221], v[162:165]
	v_mfma_f32_16x16x32_bf16 v[166:169], v[116:119], v[218:221], v[166:169]
	v_mfma_f32_16x16x32_bf16 v[170:173], v[28:31], v[226:229], v[170:173]
	v_mfma_f32_16x16x32_bf16 v[174:177], v[116:119], v[226:229], v[174:177]
	v_mfma_f32_16x16x32_bf16 v[8:11], v[120:123], v[206:209], v[8:11]
	v_mfma_f32_16x16x32_bf16 v[12:15], v[178:181], v[206:209], v[12:15]
	v_mfma_f32_16x16x32_bf16 v[24:27], v[120:123], v[214:217], v[60:63]
	v_mfma_f32_16x16x32_bf16 v[28:31], v[178:181], v[214:217], v[100:103]
	v_mfma_f32_16x16x32_bf16 v[60:63], v[120:123], v[222:225], v[104:107]
	v_mfma_f32_16x16x32_bf16 v[100:103], v[178:181], v[222:225], v[108:111]
	v_mfma_f32_16x16x32_bf16 v[16:19], v[120:123], v[230:233], v[16:19]
	v_mfma_f32_16x16x32_bf16 v[20:23], v[178:181], v[230:233], v[20:23]
	v_mfma_f32_16x16x32_bf16 v[8:11], v[124:127], v[210:213], v[8:11]
	v_mfma_f32_16x16x32_bf16 v[12:15], v[182:185], v[210:213], v[12:15]
	v_mfma_f32_16x16x32_bf16 v[24:27], v[124:127], v[218:221], v[24:27]
	v_mfma_f32_16x16x32_bf16 v[28:31], v[182:185], v[218:221], v[28:31]
	v_mfma_f32_16x16x32_bf16 v[60:63], v[124:127], v[226:229], v[60:63]
	v_mfma_f32_16x16x32_bf16 v[100:103], v[182:185], v[226:229], v[100:103]
	v_mfma_f32_16x16x32_bf16 v[16:19], v[124:127], v[234:237], v[16:19]
	v_mfma_f32_16x16x32_bf16 v[20:23], v[182:185], v[234:237], v[20:23]
	s_barrier
	s_setprio 0
	ds_read_b128 v[104:107], v152
	ds_read_b128 v[108:111], v152 offset:1024
	ds_read_b128 v[112:115], v152 offset:2048
	ds_read_b128 v[116:119], v152 offset:3072
	ds_read_b128 v[120:123], v153
	ds_read_b128 v[124:127], v153 offset:1024
	ds_read_b128 v[178:181], v153 offset:2048
	ds_read_b128 v[182:185], v153 offset:3072
	s_add_u32 s8, s8, 0x200180
	s_addc_u32 s9, s9, 0
	s_mov_b32 m0, s72
	v_lshl_add_u64 v[142:143], s[8:9], 0, v[132:133]
	ds_read_b128 v[206:209], v139
	ds_read_b128 v[210:213], v139 offset:1024
	ds_read_b128 v[214:217], v139 offset:2048
	ds_read_b128 v[218:221], v139 offset:3072
	ds_read_b128 v[222:225], v139 offset:4096
	ds_read_b128 v[226:229], v139 offset:5120
	ds_read_b128 v[230:233], v139 offset:6144
	ds_read_b128 v[234:237], v139 offset:7168
	global_load_lds_dwordx4 v[142:143], off
	v_lshl_add_u64 v[142:143], s[8:9], 0, v[130:131]
	s_mov_b32 m0, s35
	s_nop 0
	global_load_lds_dwordx4 v[142:143], off
	s_waitcnt vmcnt(8)
	s_waitcnt lgkmcnt(0)
	s_setprio 1
	s_barrier
	v_mfma_f32_16x16x32_bf16 v[64:67], v[104:107], v[206:209], v[64:67]
	v_mfma_f32_16x16x32_bf16 v[68:71], v[112:115], v[206:209], v[68:71]
	v_mfma_f32_16x16x32_bf16 v[72:75], v[104:107], v[214:217], v[72:75]
	v_mfma_f32_16x16x32_bf16 v[76:79], v[112:115], v[214:217], v[76:79]
	v_mfma_f32_16x16x32_bf16 v[80:83], v[104:107], v[222:225], v[80:83]
	v_mfma_f32_16x16x32_bf16 v[84:87], v[112:115], v[222:225], v[84:87]
	v_mfma_f32_16x16x32_bf16 v[88:91], v[104:107], v[230:233], v[88:91]
	v_mfma_f32_16x16x32_bf16 v[64:67], v[108:111], v[210:213], v[64:67]
	v_mfma_f32_16x16x32_bf16 v[68:71], v[116:119], v[210:213], v[68:71]
	v_mfma_f32_16x16x32_bf16 v[72:75], v[108:111], v[218:221], v[72:75]
	v_mfma_f32_16x16x32_bf16 v[76:79], v[116:119], v[218:221], v[76:79]
	v_mfma_f32_16x16x32_bf16 v[80:83], v[108:111], v[226:229], v[80:83]
	v_mfma_f32_16x16x32_bf16 v[84:87], v[116:119], v[226:229], v[84:87]
	v_mfma_f32_16x16x32_bf16 v[238:241], v[108:111], v[234:237], v[88:91]
	v_mfma_f32_16x16x32_bf16 v[88:91], v[112:115], v[230:233], v[92:95]
	v_mfma_f32_16x16x32_bf16 v[242:245], v[116:119], v[234:237], v[88:91]
	v_mfma_f32_16x16x32_bf16 v[88:91], v[120:123], v[206:209], v[96:99]
	v_mfma_f32_16x16x32_bf16 v[32:35], v[178:181], v[206:209], v[32:35]
	v_mfma_f32_16x16x32_bf16 v[36:39], v[120:123], v[214:217], v[36:39]
	v_mfma_f32_16x16x32_bf16 v[40:43], v[178:181], v[214:217], v[40:43]
	v_mfma_f32_16x16x32_bf16 v[44:47], v[120:123], v[222:225], v[44:47]
	v_mfma_f32_16x16x32_bf16 v[48:51], v[178:181], v[222:225], v[48:51]
	v_mfma_f32_16x16x32_bf16 v[52:55], v[120:123], v[230:233], v[52:55]
	v_mfma_f32_16x16x32_bf16 v[56:59], v[178:181], v[230:233], v[56:59]
	v_mfma_f32_16x16x32_bf16 v[96:99], v[124:127], v[210:213], v[88:91]
	v_mfma_f32_16x16x32_bf16 v[32:35], v[182:185], v[210:213], v[32:35]
	v_mfma_f32_16x16x32_bf16 v[36:39], v[124:127], v[218:221], v[36:39]
	v_mfma_f32_16x16x32_bf16 v[40:43], v[182:185], v[218:221], v[40:43]
	v_mfma_f32_16x16x32_bf16 v[44:47], v[124:127], v[226:229], v[44:47]
	v_mfma_f32_16x16x32_bf16 v[48:51], v[182:185], v[226:229], v[48:51]
	v_mfma_f32_16x16x32_bf16 v[52:55], v[124:127], v[234:237], v[52:55]
	v_mfma_f32_16x16x32_bf16 v[56:59], v[182:185], v[234:237], v[56:59]
	s_barrier
	s_setprio 0
	s_mov_b32 m0, s70
	v_lshl_add_u64 v[190:191], s[12:13], 0, v[140:141]
	s_add_u32 s8, s12, 0x40000
	ds_read_b128 v[88:91], v139 offset:16384
	ds_read_b128 v[92:95], v139 offset:17408
	ds_read_b128 v[206:209], v139 offset:18432
	ds_read_b128 v[210:213], v139 offset:19456
	ds_read_b128 v[214:217], v139 offset:20480
	ds_read_b128 v[218:221], v139 offset:21504
	ds_read_b128 v[222:225], v139 offset:22528
	ds_read_b128 v[226:229], v139 offset:23552
	global_load_lds_dwordx4 v[190:191], off
	v_lshl_add_u64 v[192:193], s[12:13], 0, v[128:129]
	s_mov_b32 m0, s53
	s_addc_u32 s9, s13, 0
	global_load_lds_dwordx4 v[192:193], off
	v_lshl_add_u64 v[142:143], s[8:9], 0, v[140:141]
	s_mov_b32 m0, s68
	v_lshl_add_u64 v[194:195], s[58:59], 0, v[132:133]
	global_load_lds_dwordx4 v[142:143], off
	v_lshl_add_u64 v[142:143], s[8:9], 0, v[128:129]
	s_mov_b32 m0, s69
	v_lshl_add_u64 v[196:197], s[58:59], 0, v[130:131]
	global_load_lds_dwordx4 v[142:143], off
	s_mov_b32 m0, s4
	s_nop 0
	global_load_lds_dwordx4 v[194:195], off
	s_mov_b32 m0, s5
	s_nop 0
	global_load_lds_dwordx4 v[196:197], off
	s_waitcnt vmcnt(8)
	s_waitcnt lgkmcnt(0)
	s_setprio 1
	s_barrier
	v_mfma_f32_16x16x32_bf16 v[0:3], v[104:107], v[222:225], v[0:3]
	v_mfma_f32_16x16x32_bf16 v[4:7], v[112:115], v[222:225], v[4:7]
	v_mfma_f32_16x16x32_bf16 v[134:137], v[104:107], v[88:91], v[134:137]
	v_mfma_f32_16x16x32_bf16 v[158:161], v[112:115], v[88:91], v[158:161]
	v_mfma_f32_16x16x32_bf16 v[162:165], v[104:107], v[206:209], v[162:165]
	v_mfma_f32_16x16x32_bf16 v[166:169], v[112:115], v[206:209], v[166:169]
	v_mfma_f32_16x16x32_bf16 v[170:173], v[104:107], v[214:217], v[170:173]
	v_mfma_f32_16x16x32_bf16 v[174:177], v[112:115], v[214:217], v[174:177]
	v_mfma_f32_16x16x32_bf16 v[0:3], v[108:111], v[226:229], v[0:3]
	v_mfma_f32_16x16x32_bf16 v[4:7], v[116:119], v[226:229], v[4:7]
	v_mfma_f32_16x16x32_bf16 v[134:137], v[108:111], v[92:95], v[134:137]
	v_mfma_f32_16x16x32_bf16 v[158:161], v[116:119], v[92:95], v[158:161]
	v_mfma_f32_16x16x32_bf16 v[162:165], v[108:111], v[210:213], v[162:165]
	v_mfma_f32_16x16x32_bf16 v[166:169], v[116:119], v[210:213], v[166:169]
	v_mfma_f32_16x16x32_bf16 v[170:173], v[108:111], v[218:221], v[170:173]
	v_mfma_f32_16x16x32_bf16 v[174:177], v[116:119], v[218:221], v[174:177]
	v_mfma_f32_16x16x32_bf16 v[8:11], v[120:123], v[88:91], v[8:11]
	v_mfma_f32_16x16x32_bf16 v[230:233], v[124:127], v[92:95], v[8:11]
	v_mfma_f32_16x16x32_bf16 v[8:11], v[178:181], v[88:91], v[12:15]
	v_mfma_f32_16x16x32_bf16 v[234:237], v[182:185], v[92:95], v[8:11]
	v_mfma_f32_16x16x32_bf16 v[8:11], v[120:123], v[206:209], v[24:27]
	v_mfma_f32_16x16x32_bf16 v[246:249], v[124:127], v[210:213], v[8:11]
	v_mfma_f32_16x16x32_bf16 v[8:11], v[178:181], v[206:209], v[28:31]
	v_mfma_f32_16x16x32_bf16 v[206:209], v[182:185], v[210:213], v[8:11]
	v_mfma_f32_16x16x32_bf16 v[8:11], v[120:123], v[214:217], v[60:63]
	v_mfma_f32_16x16x32_bf16 v[210:213], v[124:127], v[218:221], v[8:11]
	v_mfma_f32_16x16x32_bf16 v[8:11], v[178:181], v[214:217], v[100:103]
	v_mfma_f32_16x16x32_bf16 v[214:217], v[182:185], v[218:221], v[8:11]
	v_mfma_f32_16x16x32_bf16 v[8:11], v[120:123], v[222:225], v[16:19]
	v_mfma_f32_16x16x32_bf16 v[218:221], v[124:127], v[226:229], v[8:11]
	v_mfma_f32_16x16x32_bf16 v[8:11], v[178:181], v[222:225], v[20:23]
	v_mfma_f32_16x16x32_bf16 v[178:181], v[182:185], v[226:229], v[8:11]
	s_barrier
	s_setprio 0
	s_nop 4
	ds_read_b128 v[8:11], v154
	ds_read_b128 v[12:15], v154 offset:1024
	ds_read_b128 v[16:19], v154 offset:2048
	ds_read_b128 v[20:23], v154 offset:3072
	ds_read_b128 v[182:185], v155
	ds_read_b128 v[222:225], v155 offset:1024
	ds_read_b128 v[226:229], v155 offset:2048
	ds_read_b128 v[142:145], v155 offset:3072
	s_add_u32 s8, s58, 0x200000
	s_addc_u32 s9, s59, 0
	s_mov_b32 m0, s24
	v_lshl_add_u64 v[88:89], s[8:9], 0, v[132:133]
	ds_read_b128 v[24:27], v139 offset:32768
	ds_read_b128 v[28:31], v139 offset:33792
	ds_read_b128 v[60:63], v139 offset:34816
	ds_read_b128 v[146:149], v139 offset:35840
	ds_read_b128 v[150:153], v139 offset:36864
	ds_read_b128 v[154:157], v139 offset:37888
	ds_read_b128 v[200:203], v139 offset:38912
	ds_read_b128 v[186:189], v139 offset:39936
	global_load_lds_dwordx4 v[88:89], off
	v_lshl_add_u64 v[88:89], s[8:9], 0, v[130:131]
	s_mov_b32 m0, s29
	s_nop 0
	global_load_lds_dwordx4 v[88:89], off
	s_waitcnt vmcnt(8)
	s_waitcnt lgkmcnt(0)
	s_setprio 1
	s_barrier
	v_mfma_f32_16x16x32_bf16 v[64:67], v[8:11], v[24:27], v[64:67]
	v_mfma_f32_16x16x32_bf16 v[124:127], v[12:15], v[28:31], v[64:67]
	v_mfma_f32_16x16x32_bf16 v[64:67], v[16:19], v[24:27], v[68:71]
	v_mfma_f32_16x16x32_bf16 v[120:123], v[20:23], v[28:31], v[64:67]
	v_mfma_f32_16x16x32_bf16 v[64:67], v[8:11], v[60:63], v[72:75]
	v_mfma_f32_16x16x32_bf16 v[108:111], v[12:15], v[146:149], v[64:67]
	v_mfma_f32_16x16x32_bf16 v[64:67], v[16:19], v[60:63], v[76:79]
	v_mfma_f32_16x16x32_bf16 v[104:107], v[20:23], v[146:149], v[64:67]
	v_mfma_f32_16x16x32_bf16 v[64:67], v[8:11], v[150:153], v[80:83]
	v_mfma_f32_16x16x32_bf16 v[92:95], v[12:15], v[154:157], v[64:67]
	v_mfma_f32_16x16x32_bf16 v[64:67], v[16:19], v[150:153], v[84:87]
	v_mfma_f32_16x16x32_bf16 v[88:91], v[20:23], v[154:157], v[64:67]
	v_mfma_f32_16x16x32_bf16 v[64:67], v[8:11], v[200:203], v[238:241]
	v_mfma_f32_16x16x32_bf16 v[68:71], v[12:15], v[186:189], v[64:67]
	v_mfma_f32_16x16x32_bf16 v[64:67], v[16:19], v[200:203], v[242:245]
	v_mfma_f32_16x16x32_bf16 v[64:67], v[20:23], v[186:189], v[64:67]
	v_mfma_f32_16x16x32_bf16 v[72:75], v[182:185], v[24:27], v[96:99]
	v_mfma_f32_16x16x32_bf16 v[24:27], v[226:229], v[24:27], v[32:35]
	v_mfma_f32_16x16x32_bf16 v[112:115], v[142:145], v[28:31], v[24:27]
	v_mfma_f32_16x16x32_bf16 v[24:27], v[182:185], v[60:63], v[36:39]
	v_mfma_f32_16x16x32_bf16 v[100:103], v[222:225], v[146:149], v[24:27]
	v_mfma_f32_16x16x32_bf16 v[24:27], v[226:229], v[60:63], v[40:43]
	v_mfma_f32_16x16x32_bf16 v[96:99], v[142:145], v[146:149], v[24:27]
	v_mfma_f32_16x16x32_bf16 v[24:27], v[182:185], v[150:153], v[44:47]
	v_mfma_f32_16x16x32_bf16 v[84:87], v[222:225], v[154:157], v[24:27]
	v_mfma_f32_16x16x32_bf16 v[24:27], v[226:229], v[150:153], v[48:51]
	v_mfma_f32_16x16x32_bf16 v[80:83], v[142:145], v[154:157], v[24:27]
	v_mfma_f32_16x16x32_bf16 v[24:27], v[182:185], v[200:203], v[52:55]
	v_mfma_f32_16x16x32_bf16 v[52:55], v[222:225], v[186:189], v[24:27]
	v_mfma_f32_16x16x32_bf16 v[24:27], v[226:229], v[200:203], v[56:59]
	v_mfma_f32_16x16x32_bf16 v[116:119], v[222:225], v[28:31], v[72:75]
	v_mfma_f32_16x16x32_bf16 v[48:51], v[142:145], v[186:189], v[24:27]
	s_barrier
	s_setprio 0
	s_mov_b32 m0, s73
	s_nop 2
	v_lshl_add_u64 v[24:25], v[190:191], 0, s[36:37]
	s_add_u32 s8, s12, 0x40080
	ds_read_b128 v[32:35], v139 offset:49152
	ds_read_b128 v[36:39], v139 offset:50176
	ds_read_b128 v[146:149], v139 offset:51200
	ds_read_b128 v[150:153], v139 offset:52224
	ds_read_b128 v[154:157], v139 offset:53248
	ds_read_b128 v[186:189], v139 offset:54272
	ds_read_b128 v[200:203], v139 offset:55296
	ds_read_b128 v[238:241], v139 offset:56320
	global_load_lds_dwordx4 v[24:25], off
	v_lshl_add_u64 v[24:25], v[192:193], 0, s[36:37]
	s_mov_b32 m0, s71
	s_addc_u32 s9, s13, 0
	global_load_lds_dwordx4 v[24:25], off
	v_lshl_add_u64 v[24:25], s[8:9], 0, v[140:141]
	s_mov_b32 m0, s10
	s_nop 0
	global_load_lds_dwordx4 v[24:25], off
	v_lshl_add_u64 v[24:25], s[8:9], 0, v[128:129]
	s_mov_b32 m0, s11
	s_nop 0
	global_load_lds_dwordx4 v[24:25], off
	v_lshl_add_u64 v[24:25], v[194:195], 0, s[36:37]
	s_mov_b32 m0, s38
	s_nop 0
	global_load_lds_dwordx4 v[24:25], off
	v_lshl_add_u64 v[24:25], v[196:197], 0, s[36:37]
	s_mov_b32 m0, s60
	s_nop 0
	global_load_lds_dwordx4 v[24:25], off
	s_waitcnt vmcnt(8)
	s_waitcnt lgkmcnt(0)
	s_setprio 1
	s_barrier
	v_mfma_f32_16x16x32_bf16 v[24:27], v[8:11], v[32:35], v[134:137]
	v_mfma_f32_16x16x32_bf16 v[76:79], v[12:15], v[36:39], v[24:27]
	v_mfma_f32_16x16x32_bf16 v[24:27], v[16:19], v[32:35], v[158:161]
	v_mfma_f32_16x16x32_bf16 v[72:75], v[20:23], v[36:39], v[24:27]
	v_mfma_f32_16x16x32_bf16 v[24:27], v[8:11], v[146:149], v[162:165]
	v_mfma_f32_16x16x32_bf16 v[44:47], v[12:15], v[150:153], v[24:27]
	v_mfma_f32_16x16x32_bf16 v[24:27], v[16:19], v[146:149], v[166:169]
	v_mfma_f32_16x16x32_bf16 v[40:43], v[20:23], v[150:153], v[24:27]
	v_mfma_f32_16x16x32_bf16 v[24:27], v[8:11], v[154:157], v[170:173]
	v_mfma_f32_16x16x32_bf16 v[0:3], v[8:11], v[200:203], v[0:3]
	v_mfma_f32_16x16x32_bf16 v[28:31], v[12:15], v[186:189], v[24:27]
	v_mfma_f32_16x16x32_bf16 v[24:27], v[16:19], v[154:157], v[174:177]
	v_mfma_f32_16x16x32_bf16 v[12:15], v[12:15], v[238:241], v[0:3]
	v_mfma_f32_16x16x32_bf16 v[0:3], v[16:19], v[200:203], v[4:7]
	v_mfma_f32_16x16x32_bf16 v[24:27], v[20:23], v[186:189], v[24:27]
	v_mfma_f32_16x16x32_bf16 v[8:11], v[20:23], v[238:241], v[0:3]
	v_mfma_f32_16x16x32_bf16 v[0:3], v[182:185], v[32:35], v[230:233]
	v_mfma_f32_16x16x32_bf16 v[60:63], v[222:225], v[36:39], v[0:3]
	v_mfma_f32_16x16x32_bf16 v[0:3], v[226:229], v[32:35], v[234:237]
	v_mfma_f32_16x16x32_bf16 v[56:59], v[142:145], v[36:39], v[0:3]
	v_mfma_f32_16x16x32_bf16 v[0:3], v[182:185], v[146:149], v[246:249]
	v_mfma_f32_16x16x32_bf16 v[36:39], v[222:225], v[150:153], v[0:3]
	v_mfma_f32_16x16x32_bf16 v[0:3], v[226:229], v[146:149], v[206:209]
	v_mfma_f32_16x16x32_bf16 v[32:35], v[142:145], v[150:153], v[0:3]
	v_mfma_f32_16x16x32_bf16 v[0:3], v[182:185], v[154:157], v[210:213]
	v_mfma_f32_16x16x32_bf16 v[20:23], v[222:225], v[186:189], v[0:3]
	v_mfma_f32_16x16x32_bf16 v[0:3], v[226:229], v[154:157], v[214:217]
	v_mfma_f32_16x16x32_bf16 v[16:19], v[142:145], v[186:189], v[0:3]
	v_mfma_f32_16x16x32_bf16 v[0:3], v[182:185], v[200:203], v[218:221]
	v_mfma_f32_16x16x32_bf16 v[4:7], v[222:225], v[238:241], v[0:3]
	v_mfma_f32_16x16x32_bf16 v[0:3], v[226:229], v[200:203], v[178:181]
	v_mfma_f32_16x16x32_bf16 v[0:3], v[142:145], v[238:241], v[0:3]
	s_barrier
	s_setprio 0
	s_andn2_b64 vcc, exec, s[48:49]
	s_cbranch_vccnz .LBB0_678
	s_barrier

.LBB0_694:
	s_ashr_i32 s48, s54, 4
	s_ashr_i32 s47, s46, 31
	s_ashr_i32 s49, s48, 31
	s_lshl_b64 s[12:13], s[46:47], 19
	s_lshl_b64 s[50:51], s[48:49], 9
	s_add_u32 s12, s4, s12
	s_addc_u32 s13, s5, s13
	s_add_u32 s48, s12, s50
	s_addc_u32 s49, s13, s51
	s_and_b64 s[12:13], s[40:41], exec
	s_cselect_b32 s53, s49, s9
	s_cselect_b32 s52, s48, s8
	s_lshl_b32 s12, s54, 22
	s_and_b32 s12, s12, 0x3c00000
	s_add_u32 s12, s14, s12
	s_addc_u32 s13, s15, 0
	s_add_u32 s50, s12, s50
	s_addc_u32 s51, s13, s51
	s_and_b64 s[12:13], s[40:41], exec
	s_cselect_b32 s13, s51, s11
	s_cselect_b32 s12, s50, s10
	s_add_i32 s47, 0, 0x10000
	s_add_i32 s57, 0, 0x14000
	v_add_u32_e32 v140, s47, v138
	v_add_u32_e32 v198, s57, v138
	ds_read_b128 v[0:3], v140
	ds_read_b128 v[4:7], v140 offset:1024
	ds_read_b128 v[8:11], v140 offset:2048
	ds_read_b128 v[12:15], v140 offset:3072
	ds_read_b128 v[16:19], v198
	ds_read_b128 v[20:23], v198 offset:1024
	ds_read_b128 v[24:27], v198 offset:2048
	ds_read_b128 v[28:31], v198 offset:3072
	v_mov_b32_e32 v252, 0x358637bd
	s_add_u32 s58, s8, 0x40080
	s_addc_u32 s59, s9, 0
	s_add_i32 s61, s25, 0xc000
	v_lshl_add_u64 v[64:65], s[58:59], 0, v[134:135]
	s_mov_b32 m0, s61
	s_add_i32 s35, s25, 0xe000
	ds_read_b128 v[32:35], v139
	ds_read_b128 v[36:39], v139 offset:1024
	ds_read_b128 v[40:43], v139 offset:2048
	ds_read_b128 v[44:47], v139 offset:3072
	ds_read_b128 v[48:51], v139 offset:4096
	ds_read_b128 v[52:55], v139 offset:5120
	ds_read_b128 v[56:59], v139 offset:6144
	ds_read_b128 v[60:63], v139 offset:7168
	global_load_lds_dwordx4 v[64:65], off
	v_lshl_add_u64 v[64:65], s[58:59], 0, v[130:131]
	s_mov_b32 m0, s35
	s_nop 0
	global_load_lds_dwordx4 v[64:65], off
	s_waitcnt vmcnt(8)
	s_waitcnt lgkmcnt(0)
	s_setprio 1
	s_barrier
	v_mfma_f32_16x16x32_bf16 v[64:67], v[0:3], v[32:35], 0
	v_mfma_f32_16x16x32_bf16 v[68:71], v[8:11], v[32:35], 0
	v_mfma_f32_16x16x32_bf16 v[72:75], v[0:3], v[40:43], 0
	v_mfma_f32_16x16x32_bf16 v[76:79], v[8:11], v[40:43], 0
	v_mfma_f32_16x16x32_bf16 v[80:83], v[0:3], v[48:51], 0
	v_mfma_f32_16x16x32_bf16 v[84:87], v[8:11], v[48:51], 0
	v_mfma_f32_16x16x32_bf16 v[88:91], v[0:3], v[56:59], 0
	v_mfma_f32_16x16x32_bf16 v[92:95], v[8:11], v[56:59], 0
	v_mfma_f32_16x16x32_bf16 v[64:67], v[4:7], v[36:39], v[64:67]
	v_mfma_f32_16x16x32_bf16 v[68:71], v[12:15], v[36:39], v[68:71]
	v_mfma_f32_16x16x32_bf16 v[72:75], v[4:7], v[44:47], v[72:75]
	v_mfma_f32_16x16x32_bf16 v[76:79], v[12:15], v[44:47], v[76:79]
	v_mfma_f32_16x16x32_bf16 v[80:83], v[4:7], v[52:55], v[80:83]
	v_mfma_f32_16x16x32_bf16 v[84:87], v[12:15], v[52:55], v[84:87]
	v_mfma_f32_16x16x32_bf16 v[88:91], v[4:7], v[60:63], v[88:91]
	v_mfma_f32_16x16x32_bf16 v[92:95], v[12:15], v[60:63], v[92:95]
	v_mfma_f32_16x16x32_bf16 v[96:99], v[16:19], v[32:35], 0
	v_mfma_f32_16x16x32_bf16 v[32:35], v[24:27], v[32:35], 0
	v_mfma_f32_16x16x32_bf16 v[96:99], v[20:23], v[36:39], v[96:99]
	v_mfma_f32_16x16x32_bf16 v[32:35], v[28:31], v[36:39], v[32:35]
	v_mfma_f32_16x16x32_bf16 v[36:39], v[16:19], v[40:43], 0
	v_mfma_f32_16x16x32_bf16 v[40:43], v[24:27], v[40:43], 0
	v_mfma_f32_16x16x32_bf16 v[36:39], v[20:23], v[44:47], v[36:39]
	v_mfma_f32_16x16x32_bf16 v[40:43], v[28:31], v[44:47], v[40:43]
	v_mfma_f32_16x16x32_bf16 v[44:47], v[16:19], v[48:51], 0
	v_mfma_f32_16x16x32_bf16 v[48:51], v[24:27], v[48:51], 0
	v_mfma_f32_16x16x32_bf16 v[44:47], v[20:23], v[52:55], v[44:47]
	v_mfma_f32_16x16x32_bf16 v[48:51], v[28:31], v[52:55], v[48:51]
	v_mfma_f32_16x16x32_bf16 v[52:55], v[16:19], v[56:59], 0
	v_mfma_f32_16x16x32_bf16 v[56:59], v[24:27], v[56:59], 0
	v_mfma_f32_16x16x32_bf16 v[52:55], v[20:23], v[60:63], v[52:55]
	v_mfma_f32_16x16x32_bf16 v[56:59], v[28:31], v[60:63], v[56:59]
	s_barrier
	s_setprio 0
	s_add_i32 s59, s47, s24
	v_lshl_add_u64 v[136:137], s[10:11], 0, v[132:133]
	s_mov_b64 s[68:69], 0x100
	s_add_i32 s47, s59, 0x2000
	v_lshl_add_u64 v[142:143], v[136:137], 0, s[68:69]
	s_mov_b32 m0, s59
	v_lshl_add_u64 v[190:191], s[10:11], 0, v[128:129]
	s_add_u32 s66, s10, 0x200100
	ds_read_b128 v[60:63], v139 offset:16384
	ds_read_b128 v[100:103], v139 offset:17408
	ds_read_b128 v[104:107], v139 offset:18432
	ds_read_b128 v[108:111], v139 offset:19456
	ds_read_b128 v[112:115], v139 offset:20480
	ds_read_b128 v[116:119], v139 offset:21504
	ds_read_b128 v[120:123], v139 offset:22528
	ds_read_b128 v[124:127], v139 offset:23552
	global_load_lds_dwordx4 v[142:143], off
	v_lshl_add_u64 v[142:143], v[190:191], 0, s[68:69]
	s_mov_b32 m0, s47
	s_addc_u32 s67, s11, 0
	s_add_i32 s57, s57, s24
	global_load_lds_dwordx4 v[142:143], off
	v_lshl_add_u64 v[142:143], s[66:67], 0, v[132:133]
	s_mov_b32 m0, s57
	s_add_i32 s58, s57, 0x2000
	global_load_lds_dwordx4 v[142:143], off
	v_lshl_add_u64 v[142:143], s[66:67], 0, v[128:129]
	s_mov_b32 m0, s58
	v_lshl_add_u64 v[192:193], s[8:9], 0, v[134:135]
	global_load_lds_dwordx4 v[142:143], off
	v_lshl_add_u64 v[142:143], v[192:193], 0, s[68:69]
	s_mov_b32 m0, s25
	v_lshl_add_u64 v[194:195], s[8:9], 0, v[130:131]
	global_load_lds_dwordx4 v[142:143], off
	v_lshl_add_u64 v[142:143], v[194:195], 0, s[68:69]
	s_mov_b32 m0, s26
	s_nop 0
	global_load_lds_dwordx4 v[142:143], off
	s_waitcnt vmcnt(8)
	s_waitcnt lgkmcnt(0)
	s_setprio 1
	s_barrier
	v_mfma_f32_16x16x32_bf16 v[142:145], v[0:3], v[60:63], 0
	v_mfma_f32_16x16x32_bf16 v[150:153], v[0:3], v[104:107], 0
	v_mfma_f32_16x16x32_bf16 v[158:161], v[0:3], v[112:115], 0
	v_mfma_f32_16x16x32_bf16 v[0:3], v[0:3], v[120:123], 0
	v_mfma_f32_16x16x32_bf16 v[142:145], v[4:7], v[100:103], v[142:145]
	v_mfma_f32_16x16x32_bf16 v[150:153], v[4:7], v[108:111], v[150:153]
	v_mfma_f32_16x16x32_bf16 v[158:161], v[4:7], v[116:119], v[158:161]
	v_mfma_f32_16x16x32_bf16 v[0:3], v[4:7], v[124:127], v[0:3]
	v_mfma_f32_16x16x32_bf16 v[4:7], v[8:11], v[120:123], 0
	v_mfma_f32_16x16x32_bf16 v[146:149], v[8:11], v[60:63], 0
	v_mfma_f32_16x16x32_bf16 v[154:157], v[8:11], v[104:107], 0
	v_mfma_f32_16x16x32_bf16 v[162:165], v[8:11], v[112:115], 0
	v_mfma_f32_16x16x32_bf16 v[4:7], v[12:15], v[124:127], v[4:7]
	v_mfma_f32_16x16x32_bf16 v[146:149], v[12:15], v[100:103], v[146:149]
	v_mfma_f32_16x16x32_bf16 v[154:157], v[12:15], v[108:111], v[154:157]
	v_mfma_f32_16x16x32_bf16 v[162:165], v[12:15], v[116:119], v[162:165]
	v_mfma_f32_16x16x32_bf16 v[8:11], v[16:19], v[60:63], 0
	v_mfma_f32_16x16x32_bf16 v[12:15], v[24:27], v[60:63], 0
	v_mfma_f32_16x16x32_bf16 v[8:11], v[20:23], v[100:103], v[8:11]
	v_mfma_f32_16x16x32_bf16 v[12:15], v[28:31], v[100:103], v[12:15]
	v_mfma_f32_16x16x32_bf16 v[60:63], v[16:19], v[104:107], 0
	v_mfma_f32_16x16x32_bf16 v[100:103], v[24:27], v[104:107], 0
	v_mfma_f32_16x16x32_bf16 v[104:107], v[16:19], v[112:115], 0
	v_mfma_f32_16x16x32_bf16 v[16:19], v[16:19], v[120:123], 0
	v_mfma_f32_16x16x32_bf16 v[60:63], v[20:23], v[108:111], v[60:63]
	v_mfma_f32_16x16x32_bf16 v[100:103], v[28:31], v[108:111], v[100:103]
	v_mfma_f32_16x16x32_bf16 v[104:107], v[20:23], v[116:119], v[104:107]
	v_mfma_f32_16x16x32_bf16 v[108:111], v[24:27], v[112:115], 0
	v_mfma_f32_16x16x32_bf16 v[16:19], v[20:23], v[124:127], v[16:19]
	v_mfma_f32_16x16x32_bf16 v[20:23], v[24:27], v[120:123], 0
	v_mfma_f32_16x16x32_bf16 v[108:111], v[28:31], v[116:119], v[108:111]
	v_mfma_f32_16x16x32_bf16 v[20:23], v[28:31], v[124:127], v[20:23]
	s_barrier
	s_setprio 0
	s_add_i32 s60, 0, 0x18000
	s_add_i32 s70, 0, 0x1c000
	v_add_u32_e32 v230, s60, v138
	v_add_u32_e32 v238, s70, v138
	ds_read_b128 v[24:27], v230
	ds_read_b128 v[28:31], v230 offset:1024
	ds_read_b128 v[112:115], v230 offset:2048
	ds_read_b128 v[116:119], v230 offset:3072
	ds_read_b128 v[120:123], v238
	ds_read_b128 v[124:127], v238 offset:1024
	ds_read_b128 v[166:169], v238 offset:2048
	ds_read_b128 v[170:173], v238 offset:3072
	s_add_u32 s66, s8, 0x40100
	s_addc_u32 s67, s9, 0
	s_mov_b32 m0, s27
	v_lshl_add_u64 v[196:197], s[66:67], 0, v[134:135]
	ds_read_b128 v[174:177], v139 offset:32768
	ds_read_b128 v[178:181], v139 offset:33792
	ds_read_b128 v[182:185], v139 offset:34816
	ds_read_b128 v[186:189], v139 offset:35840
	ds_read_b128 v[200:203], v139 offset:36864
	ds_read_b128 v[206:209], v139 offset:37888
	ds_read_b128 v[210:213], v139 offset:38912
	ds_read_b128 v[214:217], v139 offset:39936
	global_load_lds_dwordx4 v[196:197], off
	v_lshl_add_u64 v[196:197], s[66:67], 0, v[130:131]
	s_mov_b32 m0, s28
	s_nop 0
	global_load_lds_dwordx4 v[196:197], off
	s_waitcnt vmcnt(8)
	s_waitcnt lgkmcnt(0)
	s_setprio 1
	s_barrier
	v_mfma_f32_16x16x32_bf16 v[64:67], v[24:27], v[174:177], v[64:67]
	v_mfma_f32_16x16x32_bf16 v[68:71], v[112:115], v[174:177], v[68:71]
	v_mfma_f32_16x16x32_bf16 v[72:75], v[24:27], v[182:185], v[72:75]
	v_mfma_f32_16x16x32_bf16 v[76:79], v[112:115], v[182:185], v[76:79]
	v_mfma_f32_16x16x32_bf16 v[80:83], v[24:27], v[200:203], v[80:83]
	v_mfma_f32_16x16x32_bf16 v[84:87], v[112:115], v[200:203], v[84:87]
	v_mfma_f32_16x16x32_bf16 v[88:91], v[24:27], v[210:213], v[88:91]
	v_mfma_f32_16x16x32_bf16 v[92:95], v[112:115], v[210:213], v[92:95]
	v_mfma_f32_16x16x32_bf16 v[64:67], v[28:31], v[178:181], v[64:67]
	v_mfma_f32_16x16x32_bf16 v[68:71], v[116:119], v[178:181], v[68:71]
	v_mfma_f32_16x16x32_bf16 v[72:75], v[28:31], v[186:189], v[72:75]
	v_mfma_f32_16x16x32_bf16 v[76:79], v[116:119], v[186:189], v[76:79]
	v_mfma_f32_16x16x32_bf16 v[80:83], v[28:31], v[206:209], v[80:83]
	v_mfma_f32_16x16x32_bf16 v[84:87], v[116:119], v[206:209], v[84:87]
	v_mfma_f32_16x16x32_bf16 v[88:91], v[28:31], v[214:217], v[88:91]
	v_mfma_f32_16x16x32_bf16 v[92:95], v[116:119], v[214:217], v[92:95]
	v_mfma_f32_16x16x32_bf16 v[96:99], v[120:123], v[174:177], v[96:99]
	v_mfma_f32_16x16x32_bf16 v[32:35], v[166:169], v[174:177], v[32:35]
	v_mfma_f32_16x16x32_bf16 v[36:39], v[120:123], v[182:185], v[36:39]
	v_mfma_f32_16x16x32_bf16 v[40:43], v[166:169], v[182:185], v[40:43]
	v_mfma_f32_16x16x32_bf16 v[44:47], v[120:123], v[200:203], v[44:47]
	v_mfma_f32_16x16x32_bf16 v[48:51], v[166:169], v[200:203], v[48:51]
	v_mfma_f32_16x16x32_bf16 v[52:55], v[120:123], v[210:213], v[52:55]
	v_mfma_f32_16x16x32_bf16 v[56:59], v[166:169], v[210:213], v[56:59]
	v_mfma_f32_16x16x32_bf16 v[96:99], v[124:127], v[178:181], v[96:99]
	v_mfma_f32_16x16x32_bf16 v[32:35], v[170:173], v[178:181], v[32:35]
	v_mfma_f32_16x16x32_bf16 v[36:39], v[124:127], v[186:189], v[36:39]
	v_mfma_f32_16x16x32_bf16 v[40:43], v[170:173], v[186:189], v[40:43]
	v_mfma_f32_16x16x32_bf16 v[44:47], v[124:127], v[206:209], v[44:47]
	v_mfma_f32_16x16x32_bf16 v[48:51], v[170:173], v[206:209], v[48:51]
	v_mfma_f32_16x16x32_bf16 v[52:55], v[124:127], v[214:217], v[52:55]
	v_mfma_f32_16x16x32_bf16 v[56:59], v[170:173], v[214:217], v[56:59]
	s_barrier
	s_setprio 0
	s_add_i32 s66, s60, s24
	s_mov_b64 s[74:75], 0x180
	s_add_i32 s60, s66, 0x2000
	v_lshl_add_u64 v[136:137], v[136:137], 0, s[74:75]
	s_mov_b32 m0, s66
	s_add_u32 s68, s10, 0x200180
	ds_read_b128 v[174:177], v139 offset:49152
	ds_read_b128 v[178:181], v139 offset:50176
	ds_read_b128 v[182:185], v139 offset:51200
	ds_read_b128 v[186:189], v139 offset:52224
	ds_read_b128 v[200:203], v139 offset:53248
	ds_read_b128 v[206:209], v139 offset:54272
	ds_read_b128 v[210:213], v139 offset:55296
	ds_read_b128 v[214:217], v139 offset:56320
	global_load_lds_dwordx4 v[136:137], off
	v_lshl_add_u64 v[136:137], v[190:191], 0, s[74:75]
	s_mov_b32 m0, s60
	s_addc_u32 s69, s11, 0
	s_add_i32 s10, s70, s24
	global_load_lds_dwordx4 v[136:137], off
	v_lshl_add_u64 v[136:137], s[68:69], 0, v[132:133]
	s_mov_b32 m0, s10
	s_add_i32 s11, s10, 0x2000
	global_load_lds_dwordx4 v[136:137], off
	v_lshl_add_u64 v[136:137], s[68:69], 0, v[128:129]
	s_mov_b32 m0, s11
	s_nop 0
	global_load_lds_dwordx4 v[136:137], off
	v_lshl_add_u64 v[136:137], v[192:193], 0, s[74:75]
	s_mov_b32 m0, s29
	s_nop 0
	global_load_lds_dwordx4 v[136:137], off
	v_lshl_add_u64 v[136:137], v[194:195], 0, s[74:75]
	s_mov_b32 m0, s38
	s_nop 0
	global_load_lds_dwordx4 v[136:137], off
	s_waitcnt vmcnt(8)
	s_waitcnt lgkmcnt(0)
	s_setprio 1
	s_barrier
	v_mfma_f32_16x16x32_bf16 v[0:3], v[24:27], v[210:213], v[0:3]
	v_mfma_f32_16x16x32_bf16 v[4:7], v[112:115], v[210:213], v[4:7]
	v_mfma_f32_16x16x32_bf16 v[142:145], v[24:27], v[174:177], v[142:145]
	v_mfma_f32_16x16x32_bf16 v[146:149], v[112:115], v[174:177], v[146:149]
	v_mfma_f32_16x16x32_bf16 v[150:153], v[24:27], v[182:185], v[150:153]
	v_mfma_f32_16x16x32_bf16 v[154:157], v[112:115], v[182:185], v[154:157]
	v_mfma_f32_16x16x32_bf16 v[158:161], v[24:27], v[200:203], v[158:161]
	v_mfma_f32_16x16x32_bf16 v[162:165], v[112:115], v[200:203], v[162:165]
	v_mfma_f32_16x16x32_bf16 v[0:3], v[28:31], v[214:217], v[0:3]
	v_mfma_f32_16x16x32_bf16 v[4:7], v[116:119], v[214:217], v[4:7]
	v_mfma_f32_16x16x32_bf16 v[142:145], v[28:31], v[178:181], v[142:145]
	v_mfma_f32_16x16x32_bf16 v[146:149], v[116:119], v[178:181], v[146:149]
	v_mfma_f32_16x16x32_bf16 v[150:153], v[28:31], v[186:189], v[150:153]
	v_mfma_f32_16x16x32_bf16 v[154:157], v[116:119], v[186:189], v[154:157]
	v_mfma_f32_16x16x32_bf16 v[158:161], v[28:31], v[206:209], v[158:161]
	v_mfma_f32_16x16x32_bf16 v[162:165], v[116:119], v[206:209], v[162:165]
	v_mfma_f32_16x16x32_bf16 v[8:11], v[120:123], v[174:177], v[8:11]
	v_mfma_f32_16x16x32_bf16 v[12:15], v[166:169], v[174:177], v[12:15]
	v_mfma_f32_16x16x32_bf16 v[24:27], v[120:123], v[182:185], v[60:63]
	v_mfma_f32_16x16x32_bf16 v[28:31], v[166:169], v[182:185], v[100:103]
	v_mfma_f32_16x16x32_bf16 v[60:63], v[120:123], v[200:203], v[104:107]
	v_mfma_f32_16x16x32_bf16 v[100:103], v[166:169], v[200:203], v[108:111]
	v_mfma_f32_16x16x32_bf16 v[16:19], v[120:123], v[210:213], v[16:19]
	v_mfma_f32_16x16x32_bf16 v[20:23], v[166:169], v[210:213], v[20:23]
	v_mfma_f32_16x16x32_bf16 v[8:11], v[124:127], v[178:181], v[8:11]
	v_mfma_f32_16x16x32_bf16 v[12:15], v[170:173], v[178:181], v[12:15]
	v_mfma_f32_16x16x32_bf16 v[24:27], v[124:127], v[186:189], v[24:27]
	v_mfma_f32_16x16x32_bf16 v[28:31], v[170:173], v[186:189], v[28:31]
	v_mfma_f32_16x16x32_bf16 v[60:63], v[124:127], v[206:209], v[60:63]
	v_mfma_f32_16x16x32_bf16 v[100:103], v[170:173], v[206:209], v[100:103]
	v_mfma_f32_16x16x32_bf16 v[16:19], v[124:127], v[214:217], v[16:19]
	v_mfma_f32_16x16x32_bf16 v[20:23], v[170:173], v[214:217], v[20:23]
	s_barrier
	s_setprio 0
	ds_read_b128 v[104:107], v140
	ds_read_b128 v[108:111], v140 offset:1024
	ds_read_b128 v[112:115], v140 offset:2048
	ds_read_b128 v[116:119], v140 offset:3072
	ds_read_b128 v[120:123], v198
	ds_read_b128 v[124:127], v198 offset:1024
	ds_read_b128 v[166:169], v198 offset:2048
	ds_read_b128 v[170:173], v198 offset:3072
	s_add_u32 s8, s8, 0x40180
	s_addc_u32 s9, s9, 0
	s_mov_b32 m0, s61
	v_lshl_add_u64 v[136:137], s[8:9], 0, v[134:135]
	ds_read_b128 v[174:177], v139
	ds_read_b128 v[178:181], v139 offset:1024
	ds_read_b128 v[182:185], v139 offset:2048
	ds_read_b128 v[186:189], v139 offset:3072
	ds_read_b128 v[200:203], v139 offset:4096
	ds_read_b128 v[206:209], v139 offset:5120
	ds_read_b128 v[210:213], v139 offset:6144
	ds_read_b128 v[214:217], v139 offset:7168
	global_load_lds_dwordx4 v[136:137], off
	v_lshl_add_u64 v[136:137], s[8:9], 0, v[130:131]
	s_mov_b32 m0, s35
	s_nop 0
	global_load_lds_dwordx4 v[136:137], off
	s_waitcnt vmcnt(8)
	s_waitcnt lgkmcnt(0)
	s_setprio 1
	s_barrier
	v_mfma_f32_16x16x32_bf16 v[88:91], v[104:107], v[210:213], v[88:91]
	v_mfma_f32_16x16x32_bf16 v[64:67], v[104:107], v[174:177], v[64:67]
	v_mfma_f32_16x16x32_bf16 v[68:71], v[112:115], v[174:177], v[68:71]
	v_mfma_f32_16x16x32_bf16 v[72:75], v[104:107], v[182:185], v[72:75]
	v_mfma_f32_16x16x32_bf16 v[76:79], v[112:115], v[182:185], v[76:79]
	v_mfma_f32_16x16x32_bf16 v[80:83], v[104:107], v[200:203], v[80:83]
	v_mfma_f32_16x16x32_bf16 v[84:87], v[112:115], v[200:203], v[84:87]
	v_mfma_f32_16x16x32_bf16 v[218:221], v[108:111], v[214:217], v[88:91]
	v_mfma_f32_16x16x32_bf16 v[88:91], v[112:115], v[210:213], v[92:95]
	v_mfma_f32_16x16x32_bf16 v[64:67], v[108:111], v[178:181], v[64:67]
	v_mfma_f32_16x16x32_bf16 v[68:71], v[116:119], v[178:181], v[68:71]
	v_mfma_f32_16x16x32_bf16 v[72:75], v[108:111], v[186:189], v[72:75]
	v_mfma_f32_16x16x32_bf16 v[76:79], v[116:119], v[186:189], v[76:79]
	v_mfma_f32_16x16x32_bf16 v[80:83], v[108:111], v[206:209], v[80:83]
	v_mfma_f32_16x16x32_bf16 v[84:87], v[116:119], v[206:209], v[84:87]
	v_mfma_f32_16x16x32_bf16 v[92:95], v[116:119], v[214:217], v[88:91]
	v_mfma_f32_16x16x32_bf16 v[48:51], v[166:169], v[200:203], v[48:51]
	v_mfma_f32_16x16x32_bf16 v[88:91], v[120:123], v[174:177], v[96:99]
	v_mfma_f32_16x16x32_bf16 v[32:35], v[166:169], v[174:177], v[32:35]
	v_mfma_f32_16x16x32_bf16 v[36:39], v[120:123], v[182:185], v[36:39]
	v_mfma_f32_16x16x32_bf16 v[40:43], v[166:169], v[182:185], v[40:43]
	v_mfma_f32_16x16x32_bf16 v[44:47], v[120:123], v[200:203], v[44:47]
	v_mfma_f32_16x16x32_bf16 v[174:177], v[170:173], v[206:209], v[48:51]
	v_mfma_f32_16x16x32_bf16 v[48:51], v[120:123], v[210:213], v[52:55]
	v_mfma_f32_16x16x32_bf16 v[32:35], v[170:173], v[178:181], v[32:35]
	v_mfma_f32_16x16x32_bf16 v[36:39], v[124:127], v[186:189], v[36:39]
	v_mfma_f32_16x16x32_bf16 v[40:43], v[170:173], v[186:189], v[40:43]
	v_mfma_f32_16x16x32_bf16 v[44:47], v[124:127], v[206:209], v[44:47]
	v_mfma_f32_16x16x32_bf16 v[52:55], v[124:127], v[214:217], v[48:51]
	v_mfma_f32_16x16x32_bf16 v[48:51], v[166:169], v[210:213], v[56:59]
	v_mfma_f32_16x16x32_bf16 v[222:225], v[124:127], v[178:181], v[88:91]
	v_mfma_f32_16x16x32_bf16 v[178:181], v[170:173], v[214:217], v[48:51]
	s_barrier
	s_setprio 0
	s_mov_b32 m0, s59
	v_lshl_add_u64 v[136:137], s[12:13], 0, v[132:133]
	s_add_u32 s8, s12, 0x200000
	s_nop 0
	ds_read_b128 v[48:51], v139 offset:16384
	ds_read_b128 v[56:59], v139 offset:17408
	ds_read_b128 v[88:91], v139 offset:18432
	ds_read_b128 v[96:99], v139 offset:19456
	ds_read_b128 v[182:185], v139 offset:20480
	ds_read_b128 v[186:189], v139 offset:21504
	ds_read_b128 v[200:203], v139 offset:22528
	ds_read_b128 v[206:209], v139 offset:23552
	global_load_lds_dwordx4 v[136:137], off
	v_lshl_add_u64 v[204:205], s[12:13], 0, v[128:129]
	s_mov_b32 m0, s47
	s_addc_u32 s9, s13, 0
	global_load_lds_dwordx4 v[204:205], off
	v_lshl_add_u64 v[190:191], s[8:9], 0, v[132:133]
	s_mov_b32 m0, s57
	v_lshl_add_u64 v[250:251], s[52:53], 0, v[134:135]
	global_load_lds_dwordx4 v[190:191], off
	v_lshl_add_u64 v[190:191], s[8:9], 0, v[128:129]
	s_mov_b32 m0, s58
	v_lshl_add_u64 v[198:199], s[52:53], 0, v[130:131]
	global_load_lds_dwordx4 v[190:191], off
	s_mov_b32 m0, s25
	s_nop 0
	global_load_lds_dwordx4 v[250:251], off
	s_mov_b32 m0, s26
	s_nop 0
	global_load_lds_dwordx4 v[198:199], off
	s_waitcnt vmcnt(8)
	s_waitcnt lgkmcnt(0)
	s_setprio 1
	s_barrier
	v_mfma_f32_16x16x32_bf16 v[0:3], v[104:107], v[200:203], v[0:3]
	v_mfma_f32_16x16x32_bf16 v[4:7], v[112:115], v[200:203], v[4:7]
	v_mfma_f32_16x16x32_bf16 v[142:145], v[104:107], v[48:51], v[142:145]
	v_mfma_f32_16x16x32_bf16 v[146:149], v[112:115], v[48:51], v[146:149]
	v_mfma_f32_16x16x32_bf16 v[150:153], v[104:107], v[88:91], v[150:153]
	v_mfma_f32_16x16x32_bf16 v[154:157], v[112:115], v[88:91], v[154:157]
	v_mfma_f32_16x16x32_bf16 v[158:161], v[104:107], v[182:185], v[158:161]
	v_mfma_f32_16x16x32_bf16 v[162:165], v[112:115], v[182:185], v[162:165]
	v_mfma_f32_16x16x32_bf16 v[0:3], v[108:111], v[206:209], v[0:3]
	v_mfma_f32_16x16x32_bf16 v[4:7], v[116:119], v[206:209], v[4:7]
	v_mfma_f32_16x16x32_bf16 v[142:145], v[108:111], v[56:59], v[142:145]
	v_mfma_f32_16x16x32_bf16 v[146:149], v[116:119], v[56:59], v[146:149]
	v_mfma_f32_16x16x32_bf16 v[150:153], v[108:111], v[96:99], v[150:153]
	v_mfma_f32_16x16x32_bf16 v[154:157], v[116:119], v[96:99], v[154:157]
	v_mfma_f32_16x16x32_bf16 v[158:161], v[108:111], v[186:189], v[158:161]
	v_mfma_f32_16x16x32_bf16 v[162:165], v[116:119], v[186:189], v[162:165]
	v_mfma_f32_16x16x32_bf16 v[12:15], v[166:169], v[48:51], v[12:15]
	v_mfma_f32_16x16x32_bf16 v[210:213], v[170:173], v[56:59], v[12:15]
	v_mfma_f32_16x16x32_bf16 v[12:15], v[120:123], v[88:91], v[24:27]
	v_mfma_f32_16x16x32_bf16 v[24:27], v[124:127], v[96:99], v[12:15]
	v_mfma_f32_16x16x32_bf16 v[12:15], v[166:169], v[88:91], v[28:31]
	v_mfma_f32_16x16x32_bf16 v[214:217], v[170:173], v[96:99], v[12:15]
	v_mfma_f32_16x16x32_bf16 v[12:15], v[120:123], v[182:185], v[60:63]
	v_mfma_f32_16x16x32_bf16 v[226:229], v[124:127], v[186:189], v[12:15]
	v_mfma_f32_16x16x32_bf16 v[12:15], v[166:169], v[182:185], v[100:103]
	v_mfma_f32_16x16x32_bf16 v[8:11], v[120:123], v[48:51], v[8:11]
	v_mfma_f32_16x16x32_bf16 v[182:185], v[170:173], v[186:189], v[12:15]
	v_mfma_f32_16x16x32_bf16 v[12:15], v[120:123], v[200:203], v[16:19]
	v_mfma_f32_16x16x32_bf16 v[8:11], v[124:127], v[56:59], v[8:11]
	v_mfma_f32_16x16x32_bf16 v[186:189], v[124:127], v[206:209], v[12:15]
	v_mfma_f32_16x16x32_bf16 v[12:15], v[166:169], v[200:203], v[20:23]
	v_mfma_f32_16x16x32_bf16 v[166:169], v[170:173], v[206:209], v[12:15]
	s_barrier
	s_setprio 0
	s_nop 4
	ds_read_b128 v[12:15], v230
	ds_read_b128 v[16:19], v230 offset:1024
	ds_read_b128 v[170:173], v230 offset:2048
	ds_read_b128 v[200:203], v230 offset:3072
	ds_read_b128 v[206:209], v238
	ds_read_b128 v[230:233], v238 offset:1024
	ds_read_b128 v[234:237], v238 offset:2048
	ds_read_b128 v[238:241], v238 offset:3072
	s_add_u32 s8, s52, 0x40000
	s_addc_u32 s9, s53, 0
	s_mov_b32 m0, s27
	v_lshl_add_u64 v[48:49], s[8:9], 0, v[134:135]
	ds_read_b128 v[20:23], v139 offset:32768
	ds_read_b128 v[28:31], v139 offset:33792
	ds_read_b128 v[60:63], v139 offset:34816
	ds_read_b128 v[100:103], v139 offset:35840
	ds_read_b128 v[242:245], v139 offset:36864
	ds_read_b128 v[246:249], v139 offset:37888
	ds_read_b128 v[190:193], v139 offset:38912
	ds_read_b128 v[194:197], v139 offset:39936
	global_load_lds_dwordx4 v[48:49], off
	v_lshl_add_u64 v[48:49], s[8:9], 0, v[130:131]
	s_mov_b32 m0, s28
	s_nop 0
	global_load_lds_dwordx4 v[48:49], off
	s_waitcnt vmcnt(8)
	s_waitcnt lgkmcnt(0)
	s_setprio 1
	s_barrier
	v_mfma_f32_16x16x32_bf16 v[48:51], v[12:15], v[20:23], v[64:67]
	v_mfma_f32_16x16x32_bf16 v[120:123], v[16:19], v[28:31], v[48:51]
	v_mfma_f32_16x16x32_bf16 v[48:51], v[170:173], v[20:23], v[68:71]
	v_mfma_f32_16x16x32_bf16 v[112:115], v[200:203], v[28:31], v[48:51]
	v_mfma_f32_16x16x32_bf16 v[48:51], v[12:15], v[60:63], v[72:75]
	v_mfma_f32_16x16x32_bf16 v[104:107], v[16:19], v[100:103], v[48:51]
	v_mfma_f32_16x16x32_bf16 v[48:51], v[170:173], v[60:63], v[76:79]
	v_mfma_f32_16x16x32_bf16 v[96:99], v[200:203], v[100:103], v[48:51]
	v_mfma_f32_16x16x32_bf16 v[48:51], v[12:15], v[242:245], v[80:83]
	v_mfma_f32_16x16x32_bf16 v[88:91], v[16:19], v[246:249], v[48:51]
	v_mfma_f32_16x16x32_bf16 v[48:51], v[170:173], v[242:245], v[84:87]
	v_mfma_f32_16x16x32_bf16 v[80:83], v[200:203], v[246:249], v[48:51]
	v_mfma_f32_16x16x32_bf16 v[48:51], v[12:15], v[190:193], v[218:221]
	v_mfma_f32_16x16x32_bf16 v[56:59], v[16:19], v[194:197], v[48:51]
	v_mfma_f32_16x16x32_bf16 v[48:51], v[170:173], v[190:193], v[92:95]
	v_mfma_f32_16x16x32_bf16 v[48:51], v[200:203], v[194:197], v[48:51]
	v_mfma_f32_16x16x32_bf16 v[64:67], v[206:209], v[20:23], v[222:225]
	v_mfma_f32_16x16x32_bf16 v[20:23], v[234:237], v[20:23], v[32:35]
	v_mfma_f32_16x16x32_bf16 v[116:119], v[238:241], v[28:31], v[20:23]
	v_mfma_f32_16x16x32_bf16 v[20:23], v[206:209], v[60:63], v[36:39]
	v_mfma_f32_16x16x32_bf16 v[108:111], v[230:233], v[100:103], v[20:23]
	v_mfma_f32_16x16x32_bf16 v[20:23], v[234:237], v[60:63], v[40:43]
	v_mfma_f32_16x16x32_bf16 v[100:103], v[238:241], v[100:103], v[20:23]
	v_mfma_f32_16x16x32_bf16 v[20:23], v[206:209], v[242:245], v[44:47]
	v_mfma_f32_16x16x32_bf16 v[92:95], v[230:233], v[246:249], v[20:23]
	v_mfma_f32_16x16x32_bf16 v[20:23], v[234:237], v[242:245], v[174:177]
	v_mfma_f32_16x16x32_bf16 v[84:87], v[238:241], v[246:249], v[20:23]
	v_mfma_f32_16x16x32_bf16 v[20:23], v[206:209], v[190:193], v[52:55]
	v_mfma_f32_16x16x32_bf16 v[60:63], v[230:233], v[194:197], v[20:23]
	v_mfma_f32_16x16x32_bf16 v[20:23], v[234:237], v[190:193], v[178:181]
	v_mfma_f32_16x16x32_bf16 v[124:127], v[230:233], v[28:31], v[64:67]
	v_mfma_f32_16x16x32_bf16 v[52:55], v[238:241], v[194:197], v[20:23]
	s_barrier
	s_setprio 0
	s_mov_b32 m0, s66
	s_nop 2
	v_lshl_add_u64 v[20:21], v[136:137], 0, s[36:37]
	s_add_u32 s8, s12, 0x200080
	ds_read_b128 v[32:35], v139 offset:49152
	ds_read_b128 v[40:43], v139 offset:50176
	ds_read_b128 v[174:177], v139 offset:51200
	ds_read_b128 v[178:181], v139 offset:52224
	ds_read_b128 v[190:193], v139 offset:53248
	ds_read_b128 v[194:197], v139 offset:54272
	ds_read_b128 v[218:221], v139 offset:55296
	ds_read_b128 v[222:225], v139 offset:56320
	global_load_lds_dwordx4 v[20:21], off
	v_lshl_add_u64 v[20:21], v[204:205], 0, s[36:37]
	s_mov_b32 m0, s60
	s_addc_u32 s9, s13, 0
	global_load_lds_dwordx4 v[20:21], off
	v_lshl_add_u64 v[20:21], s[8:9], 0, v[132:133]
	s_mov_b32 m0, s10
	s_nop 0
	global_load_lds_dwordx4 v[20:21], off
	v_lshl_add_u64 v[20:21], s[8:9], 0, v[128:129]
	s_mov_b32 m0, s11
	s_nop 0
	global_load_lds_dwordx4 v[20:21], off
	v_lshl_add_u64 v[20:21], v[250:251], 0, s[36:37]
	s_mov_b32 m0, s29
	s_nop 0
	global_load_lds_dwordx4 v[20:21], off
	v_lshl_add_u64 v[20:21], v[198:199], 0, s[36:37]
	s_mov_b32 m0, s38
	s_nop 0
	global_load_lds_dwordx4 v[20:21], off
	s_waitcnt vmcnt(8)
	s_waitcnt lgkmcnt(0)
	s_setprio 1
	s_barrier
	v_mfma_f32_16x16x32_bf16 v[20:23], v[12:15], v[32:35], v[142:145]
	v_mfma_f32_16x16x32_bf16 v[76:79], v[16:19], v[40:43], v[20:23]
	v_mfma_f32_16x16x32_bf16 v[20:23], v[170:173], v[32:35], v[146:149]
	v_mfma_f32_16x16x32_bf16 v[68:71], v[200:203], v[40:43], v[20:23]
	v_mfma_f32_16x16x32_bf16 v[20:23], v[12:15], v[174:177], v[150:153]
	v_mfma_f32_16x16x32_bf16 v[44:47], v[16:19], v[178:181], v[20:23]
	v_mfma_f32_16x16x32_bf16 v[20:23], v[170:173], v[174:177], v[154:157]
	v_mfma_f32_16x16x32_bf16 v[36:39], v[200:203], v[178:181], v[20:23]
	v_mfma_f32_16x16x32_bf16 v[20:23], v[12:15], v[190:193], v[158:161]
	v_mfma_f32_16x16x32_bf16 v[0:3], v[12:15], v[218:221], v[0:3]
	v_mfma_f32_16x16x32_bf16 v[28:31], v[16:19], v[194:197], v[20:23]
	v_mfma_f32_16x16x32_bf16 v[20:23], v[170:173], v[190:193], v[162:165]
	v_mfma_f32_16x16x32_bf16 v[12:15], v[16:19], v[222:225], v[0:3]
	v_mfma_f32_16x16x32_bf16 v[0:3], v[170:173], v[218:221], v[4:7]
	v_mfma_f32_16x16x32_bf16 v[20:23], v[200:203], v[194:197], v[20:23]
	v_mfma_f32_16x16x32_bf16 v[4:7], v[200:203], v[222:225], v[0:3]
	v_mfma_f32_16x16x32_bf16 v[0:3], v[206:209], v[32:35], v[8:11]
	v_mfma_f32_16x16x32_bf16 v[72:75], v[230:233], v[40:43], v[0:3]
	v_mfma_f32_16x16x32_bf16 v[0:3], v[234:237], v[32:35], v[210:213]
	v_mfma_f32_16x16x32_bf16 v[64:67], v[238:241], v[40:43], v[0:3]
	v_mfma_f32_16x16x32_bf16 v[0:3], v[206:209], v[174:177], v[24:27]
	v_mfma_f32_16x16x32_bf16 v[40:43], v[230:233], v[178:181], v[0:3]
	v_mfma_f32_16x16x32_bf16 v[0:3], v[234:237], v[174:177], v[214:217]
	v_mfma_f32_16x16x32_bf16 v[32:35], v[238:241], v[178:181], v[0:3]
	v_mfma_f32_16x16x32_bf16 v[0:3], v[206:209], v[190:193], v[226:229]
	v_mfma_f32_16x16x32_bf16 v[24:27], v[230:233], v[194:197], v[0:3]
	v_mfma_f32_16x16x32_bf16 v[0:3], v[234:237], v[190:193], v[182:185]
	v_mfma_f32_16x16x32_bf16 v[16:19], v[238:241], v[194:197], v[0:3]
	v_mfma_f32_16x16x32_bf16 v[0:3], v[206:209], v[218:221], v[186:189]
	v_mfma_f32_16x16x32_bf16 v[8:11], v[230:233], v[222:225], v[0:3]
	v_mfma_f32_16x16x32_bf16 v[0:3], v[234:237], v[218:221], v[166:169]
	v_mfma_f32_16x16x32_bf16 v[0:3], v[238:241], v[222:225], v[0:3]
	s_barrier
	s_setprio 0
	s_andn2_b64 vcc, exec, s[42:43]
	s_cbranch_vccnz .LBB0_696
	s_barrier

.LBB0_714:
	s_add_u32 s8, s6, 0xfffc0080
	s_addc_u32 s9, s7, -1
	s_add_i32 s35, 0, 0x10000
	s_cmp_eq_u32 s59, 12
	s_cselect_b32 s11, s24, s9
	s_cselect_b32 s10, s51, s8
	v_add_u32_e32 v138, s35, v164
	s_cselect_b32 s9, s49, s58
	s_cselect_b32 s8, s56, s57
	s_add_i32 s66, 0, 0x14000
	ds_read_b128 v[158:161], v138
	ds_read_b128 v[166:169], v138 offset:1024
	ds_read_b128 v[170:173], v138 offset:2048
	ds_read_b128 v[174:177], v138 offset:3072
	v_add_u32_e32 v138, s66, v164
	ds_read_b128 v[178:181], v138
	ds_read_b128 v[182:185], v138 offset:1024
	ds_read_b128 v[206:209], v138 offset:2048
	ds_read_b128 v[210:213], v138 offset:3072
	v_lshl_add_u64 v[138:139], s[6:7], 0, v[134:135]
	s_add_i32 m0, s17, 0xc000
	ds_read_b128 v[214:217], v165
	ds_read_b128 v[218:221], v165 offset:1024
	ds_read_b128 v[222:225], v165 offset:2048
	ds_read_b128 v[226:229], v165 offset:3072
	ds_read_b128 v[230:233], v165 offset:4096
	ds_read_b128 v[234:237], v165 offset:5120
	ds_read_b128 v[238:241], v165 offset:6144
	ds_read_b128 v[242:245], v165 offset:7168
	global_load_lds_dwordx4 v[138:139], off
	v_lshl_add_u64 v[138:139], s[6:7], 0, v[136:137]
	s_add_i32 m0, s17, 0xe000
	s_nop 0
	global_load_lds_dwordx4 v[138:139], off
	s_waitcnt vmcnt(8)
	s_waitcnt lgkmcnt(0)
	s_setprio 1
	s_barrier
	v_mfma_f32_16x16x32_bf16 v[124:127], v[158:161], v[214:217], v[124:127]
	v_mfma_f32_16x16x32_bf16 v[120:123], v[170:173], v[214:217], v[120:123]
	v_mfma_f32_16x16x32_bf16 v[108:111], v[158:161], v[222:225], v[108:111]
	v_mfma_f32_16x16x32_bf16 v[104:107], v[170:173], v[222:225], v[104:107]
	v_mfma_f32_16x16x32_bf16 v[92:95], v[158:161], v[230:233], v[92:95]
	v_mfma_f32_16x16x32_bf16 v[88:91], v[170:173], v[230:233], v[88:91]
	v_mfma_f32_16x16x32_bf16 v[76:79], v[158:161], v[238:241], v[76:79]
	v_mfma_f32_16x16x32_bf16 v[72:75], v[170:173], v[238:241], v[72:75]
	v_mfma_f32_16x16x32_bf16 v[124:127], v[166:169], v[218:221], v[124:127]
	v_mfma_f32_16x16x32_bf16 v[120:123], v[174:177], v[218:221], v[120:123]
	v_mfma_f32_16x16x32_bf16 v[108:111], v[166:169], v[226:229], v[108:111]
	v_mfma_f32_16x16x32_bf16 v[104:107], v[174:177], v[226:229], v[104:107]
	v_mfma_f32_16x16x32_bf16 v[92:95], v[166:169], v[234:237], v[92:95]
	v_mfma_f32_16x16x32_bf16 v[88:91], v[174:177], v[234:237], v[88:91]
	v_mfma_f32_16x16x32_bf16 v[76:79], v[166:169], v[242:245], v[76:79]
	v_mfma_f32_16x16x32_bf16 v[72:75], v[174:177], v[242:245], v[72:75]
	v_mfma_f32_16x16x32_bf16 v[116:119], v[178:181], v[214:217], v[116:119]
	v_mfma_f32_16x16x32_bf16 v[112:115], v[206:209], v[214:217], v[112:115]
	v_mfma_f32_16x16x32_bf16 v[100:103], v[178:181], v[222:225], v[100:103]
	v_mfma_f32_16x16x32_bf16 v[96:99], v[206:209], v[222:225], v[96:99]
	v_mfma_f32_16x16x32_bf16 v[84:87], v[178:181], v[230:233], v[84:87]
	v_mfma_f32_16x16x32_bf16 v[80:83], v[206:209], v[230:233], v[80:83]
	v_mfma_f32_16x16x32_bf16 v[68:71], v[178:181], v[238:241], v[68:71]
	v_mfma_f32_16x16x32_bf16 v[64:67], v[206:209], v[238:241], v[64:67]
	v_mfma_f32_16x16x32_bf16 v[116:119], v[182:185], v[218:221], v[116:119]
	v_mfma_f32_16x16x32_bf16 v[112:115], v[210:213], v[218:221], v[112:115]
	v_mfma_f32_16x16x32_bf16 v[100:103], v[182:185], v[226:229], v[100:103]
	v_mfma_f32_16x16x32_bf16 v[96:99], v[210:213], v[226:229], v[96:99]
	v_mfma_f32_16x16x32_bf16 v[84:87], v[182:185], v[234:237], v[84:87]
	v_mfma_f32_16x16x32_bf16 v[80:83], v[210:213], v[234:237], v[80:83]
	v_mfma_f32_16x16x32_bf16 v[68:71], v[182:185], v[242:245], v[68:71]
	v_mfma_f32_16x16x32_bf16 v[64:67], v[210:213], v[242:245], v[64:67]
	s_barrier
	s_setprio 0
	s_add_i32 s35, s35, s14
	v_lshl_add_u64 v[138:139], s[8:9], 0, v[140:141]
	s_mov_b32 m0, s35
	ds_read_b128 v[214:217], v165 offset:16384
	ds_read_b128 v[218:221], v165 offset:17408
	ds_read_b128 v[222:225], v165 offset:18432
	ds_read_b128 v[226:229], v165 offset:19456
	ds_read_b128 v[230:233], v165 offset:20480
	ds_read_b128 v[234:237], v165 offset:21504
	ds_read_b128 v[238:241], v165 offset:22528
	ds_read_b128 v[242:245], v165 offset:23552
	global_load_lds_dwordx4 v[138:139], off
	s_add_i32 m0, s35, 0x2000
	s_add_u32 s60, s8, 0x40000
	v_lshl_add_u64 v[142:143], s[8:9], 0, v[128:129]
	s_addc_u32 s61, s9, 0
	s_add_i32 s35, s66, s14
	global_load_lds_dwordx4 v[142:143], off
	v_lshl_add_u64 v[144:145], s[60:61], 0, v[140:141]
	s_mov_b32 m0, s35
	v_lshl_add_u64 v[146:147], s[10:11], 0, v[130:131]
	global_load_lds_dwordx4 v[144:145], off
	v_lshl_add_u64 v[144:145], s[60:61], 0, v[128:129]
	s_add_i32 m0, s35, 0x2000
	s_nop 0
	global_load_lds_dwordx4 v[144:145], off
	v_lshl_add_u64 v[144:145], s[10:11], 0, v[132:133]
	s_mov_b32 m0, s17
	s_nop 0
	global_load_lds_dwordx4 v[144:145], off
	s_mov_b32 m0, s25
	s_nop 0
	global_load_lds_dwordx4 v[146:147], off
	s_waitcnt vmcnt(8)
	s_waitcnt lgkmcnt(0)
	s_setprio 1
	s_barrier
	v_mfma_f32_16x16x32_bf16 v[60:63], v[158:161], v[214:217], v[60:63]
	v_mfma_f32_16x16x32_bf16 v[56:59], v[170:173], v[214:217], v[56:59]
	v_mfma_f32_16x16x32_bf16 v[44:47], v[158:161], v[222:225], v[44:47]
	v_mfma_f32_16x16x32_bf16 v[40:43], v[170:173], v[222:225], v[40:43]
	v_mfma_f32_16x16x32_bf16 v[28:31], v[158:161], v[230:233], v[28:31]
	v_mfma_f32_16x16x32_bf16 v[24:27], v[170:173], v[230:233], v[24:27]
	v_mfma_f32_16x16x32_bf16 v[12:15], v[158:161], v[238:241], v[12:15]
	v_mfma_f32_16x16x32_bf16 v[8:11], v[170:173], v[238:241], v[8:11]
	v_mfma_f32_16x16x32_bf16 v[60:63], v[166:169], v[218:221], v[60:63]
	v_mfma_f32_16x16x32_bf16 v[56:59], v[174:177], v[218:221], v[56:59]
	v_mfma_f32_16x16x32_bf16 v[44:47], v[166:169], v[226:229], v[44:47]
	v_mfma_f32_16x16x32_bf16 v[40:43], v[174:177], v[226:229], v[40:43]
	v_mfma_f32_16x16x32_bf16 v[28:31], v[166:169], v[234:237], v[28:31]
	v_mfma_f32_16x16x32_bf16 v[24:27], v[174:177], v[234:237], v[24:27]
	v_mfma_f32_16x16x32_bf16 v[12:15], v[166:169], v[242:245], v[12:15]
	v_mfma_f32_16x16x32_bf16 v[8:11], v[174:177], v[242:245], v[8:11]
	v_mfma_f32_16x16x32_bf16 v[52:55], v[178:181], v[214:217], v[52:55]
	v_mfma_f32_16x16x32_bf16 v[48:51], v[206:209], v[214:217], v[48:51]
	v_mfma_f32_16x16x32_bf16 v[36:39], v[178:181], v[222:225], v[36:39]
	v_mfma_f32_16x16x32_bf16 v[32:35], v[206:209], v[222:225], v[32:35]
	v_mfma_f32_16x16x32_bf16 v[20:23], v[178:181], v[230:233], v[20:23]
	v_mfma_f32_16x16x32_bf16 v[16:19], v[206:209], v[230:233], v[16:19]
	v_mfma_f32_16x16x32_bf16 v[4:7], v[178:181], v[238:241], v[4:7]
	v_mfma_f32_16x16x32_bf16 v[0:3], v[206:209], v[238:241], v[0:3]
	v_mfma_f32_16x16x32_bf16 v[52:55], v[182:185], v[218:221], v[52:55]
	v_mfma_f32_16x16x32_bf16 v[48:51], v[210:213], v[218:221], v[48:51]
	v_mfma_f32_16x16x32_bf16 v[36:39], v[182:185], v[226:229], v[36:39]
	v_mfma_f32_16x16x32_bf16 v[32:35], v[210:213], v[226:229], v[32:35]
	v_mfma_f32_16x16x32_bf16 v[20:23], v[182:185], v[234:237], v[20:23]
	v_mfma_f32_16x16x32_bf16 v[16:19], v[210:213], v[234:237], v[16:19]
	v_mfma_f32_16x16x32_bf16 v[4:7], v[182:185], v[242:245], v[4:7]
	v_mfma_f32_16x16x32_bf16 v[0:3], v[210:213], v[242:245], v[0:3]
	s_barrier
	s_setprio 0
	s_add_i32 s35, 0, 0x18000
	v_add_u32_e32 v148, s35, v164
	s_add_i32 s60, 0, 0x1c000
	ds_read_b128 v[158:161], v148
	ds_read_b128 v[166:169], v148 offset:1024
	ds_read_b128 v[170:173], v148 offset:2048
	ds_read_b128 v[174:177], v148 offset:3072
	v_add_u32_e32 v148, s60, v164
	ds_read_b128 v[178:181], v148
	ds_read_b128 v[182:185], v148 offset:1024
	ds_read_b128 v[206:209], v148 offset:2048
	ds_read_b128 v[210:213], v148 offset:3072
	s_add_u32 s10, s10, 0x40000
	s_addc_u32 s11, s11, 0
	s_mov_b32 m0, s26
	v_lshl_add_u64 v[148:149], s[10:11], 0, v[132:133]
	ds_read_b128 v[214:217], v165 offset:32768
	ds_read_b128 v[218:221], v165 offset:33792
	ds_read_b128 v[222:225], v165 offset:34816
	ds_read_b128 v[226:229], v165 offset:35840
	ds_read_b128 v[230:233], v165 offset:36864
	ds_read_b128 v[234:237], v165 offset:37888
	ds_read_b128 v[238:241], v165 offset:38912
	ds_read_b128 v[242:245], v165 offset:39936
	global_load_lds_dwordx4 v[148:149], off
	v_lshl_add_u64 v[148:149], s[10:11], 0, v[130:131]
	s_mov_b32 m0, s27
	s_nop 0
	global_load_lds_dwordx4 v[148:149], off
	s_waitcnt vmcnt(8)
	s_waitcnt lgkmcnt(0)
	s_setprio 1
	s_barrier
	v_mfma_f32_16x16x32_bf16 v[124:127], v[158:161], v[214:217], v[124:127]
	v_mfma_f32_16x16x32_bf16 v[120:123], v[170:173], v[214:217], v[120:123]
	v_mfma_f32_16x16x32_bf16 v[108:111], v[158:161], v[222:225], v[108:111]
	v_mfma_f32_16x16x32_bf16 v[104:107], v[170:173], v[222:225], v[104:107]
	v_mfma_f32_16x16x32_bf16 v[92:95], v[158:161], v[230:233], v[92:95]
	v_mfma_f32_16x16x32_bf16 v[88:91], v[170:173], v[230:233], v[88:91]
	v_mfma_f32_16x16x32_bf16 v[76:79], v[158:161], v[238:241], v[76:79]
	v_mfma_f32_16x16x32_bf16 v[72:75], v[170:173], v[238:241], v[72:75]
	v_mfma_f32_16x16x32_bf16 v[124:127], v[166:169], v[218:221], v[124:127]
	v_mfma_f32_16x16x32_bf16 v[120:123], v[174:177], v[218:221], v[120:123]
	v_mfma_f32_16x16x32_bf16 v[108:111], v[166:169], v[226:229], v[108:111]
	v_mfma_f32_16x16x32_bf16 v[104:107], v[174:177], v[226:229], v[104:107]
	v_mfma_f32_16x16x32_bf16 v[92:95], v[166:169], v[234:237], v[92:95]
	v_mfma_f32_16x16x32_bf16 v[88:91], v[174:177], v[234:237], v[88:91]
	v_mfma_f32_16x16x32_bf16 v[76:79], v[166:169], v[242:245], v[76:79]
	v_mfma_f32_16x16x32_bf16 v[72:75], v[174:177], v[242:245], v[72:75]
	v_mfma_f32_16x16x32_bf16 v[116:119], v[178:181], v[214:217], v[116:119]
	v_mfma_f32_16x16x32_bf16 v[112:115], v[206:209], v[214:217], v[112:115]
	v_mfma_f32_16x16x32_bf16 v[100:103], v[178:181], v[222:225], v[100:103]
	v_mfma_f32_16x16x32_bf16 v[96:99], v[206:209], v[222:225], v[96:99]
	v_mfma_f32_16x16x32_bf16 v[84:87], v[178:181], v[230:233], v[84:87]
	v_mfma_f32_16x16x32_bf16 v[80:83], v[206:209], v[230:233], v[80:83]
	v_mfma_f32_16x16x32_bf16 v[68:71], v[178:181], v[238:241], v[68:71]
	v_mfma_f32_16x16x32_bf16 v[64:67], v[206:209], v[238:241], v[64:67]
	v_mfma_f32_16x16x32_bf16 v[116:119], v[182:185], v[218:221], v[116:119]
	v_mfma_f32_16x16x32_bf16 v[112:115], v[210:213], v[218:221], v[112:115]
	v_mfma_f32_16x16x32_bf16 v[100:103], v[182:185], v[226:229], v[100:103]
	v_mfma_f32_16x16x32_bf16 v[96:99], v[210:213], v[226:229], v[96:99]
	v_mfma_f32_16x16x32_bf16 v[84:87], v[182:185], v[234:237], v[84:87]
	v_mfma_f32_16x16x32_bf16 v[80:83], v[210:213], v[234:237], v[80:83]
	v_mfma_f32_16x16x32_bf16 v[68:71], v[182:185], v[242:245], v[68:71]
	v_mfma_f32_16x16x32_bf16 v[64:67], v[210:213], v[242:245], v[64:67]
	s_barrier
	s_setprio 0
	s_add_i32 s10, s35, s14
	v_lshl_add_u64 v[138:139], v[138:139], 0, s[36:37]
	s_mov_b32 m0, s10
	ds_read_b128 v[214:217], v165 offset:49152
	ds_read_b128 v[218:221], v165 offset:50176
	ds_read_b128 v[222:225], v165 offset:51200
	ds_read_b128 v[226:229], v165 offset:52224
	ds_read_b128 v[230:233], v165 offset:53248
	ds_read_b128 v[234:237], v165 offset:54272
	ds_read_b128 v[238:241], v165 offset:55296
	ds_read_b128 v[242:245], v165 offset:56320
	global_load_lds_dwordx4 v[138:139], off
	s_add_i32 m0, s10, 0x2000
	s_add_u32 s8, s8, 0x40080
	v_lshl_add_u64 v[138:139], v[142:143], 0, s[36:37]
	s_addc_u32 s9, s9, 0
	s_add_i32 s10, s60, s14
	global_load_lds_dwordx4 v[138:139], off
	v_lshl_add_u64 v[138:139], s[8:9], 0, v[140:141]
	s_mov_b32 m0, s10
	s_nop 0
	global_load_lds_dwordx4 v[138:139], off
	v_lshl_add_u64 v[138:139], s[8:9], 0, v[128:129]
	s_add_i32 m0, s10, 0x2000
	s_nop 0
	global_load_lds_dwordx4 v[138:139], off
	v_lshl_add_u64 v[138:139], v[144:145], 0, s[36:37]
	s_mov_b32 m0, s28
	s_nop 0
	global_load_lds_dwordx4 v[138:139], off
	v_lshl_add_u64 v[138:139], v[146:147], 0, s[36:37]
	s_mov_b32 m0, s29
	s_nop 0
	global_load_lds_dwordx4 v[138:139], off
	s_waitcnt vmcnt(8)
	s_waitcnt lgkmcnt(0)
	s_setprio 1
	s_barrier
	v_mfma_f32_16x16x32_bf16 v[60:63], v[158:161], v[214:217], v[60:63]
	v_mfma_f32_16x16x32_bf16 v[56:59], v[170:173], v[214:217], v[56:59]
	v_mfma_f32_16x16x32_bf16 v[44:47], v[158:161], v[222:225], v[44:47]
	v_mfma_f32_16x16x32_bf16 v[40:43], v[170:173], v[222:225], v[40:43]
	v_mfma_f32_16x16x32_bf16 v[28:31], v[158:161], v[230:233], v[28:31]
	v_mfma_f32_16x16x32_bf16 v[24:27], v[170:173], v[230:233], v[24:27]
	v_mfma_f32_16x16x32_bf16 v[12:15], v[158:161], v[238:241], v[12:15]
	v_mfma_f32_16x16x32_bf16 v[8:11], v[170:173], v[238:241], v[8:11]
	v_mfma_f32_16x16x32_bf16 v[60:63], v[166:169], v[218:221], v[60:63]
	v_mfma_f32_16x16x32_bf16 v[56:59], v[174:177], v[218:221], v[56:59]
	v_mfma_f32_16x16x32_bf16 v[44:47], v[166:169], v[226:229], v[44:47]
	v_mfma_f32_16x16x32_bf16 v[40:43], v[174:177], v[226:229], v[40:43]
	v_mfma_f32_16x16x32_bf16 v[28:31], v[166:169], v[234:237], v[28:31]
	v_mfma_f32_16x16x32_bf16 v[24:27], v[174:177], v[234:237], v[24:27]
	v_mfma_f32_16x16x32_bf16 v[12:15], v[166:169], v[242:245], v[12:15]
	v_mfma_f32_16x16x32_bf16 v[8:11], v[174:177], v[242:245], v[8:11]
	v_mfma_f32_16x16x32_bf16 v[52:55], v[178:181], v[214:217], v[52:55]
	v_mfma_f32_16x16x32_bf16 v[48:51], v[206:209], v[214:217], v[48:51]
	v_mfma_f32_16x16x32_bf16 v[36:39], v[178:181], v[222:225], v[36:39]
	v_mfma_f32_16x16x32_bf16 v[32:35], v[206:209], v[222:225], v[32:35]
	v_mfma_f32_16x16x32_bf16 v[20:23], v[178:181], v[230:233], v[20:23]
	v_mfma_f32_16x16x32_bf16 v[16:19], v[206:209], v[230:233], v[16:19]
	v_mfma_f32_16x16x32_bf16 v[4:7], v[178:181], v[238:241], v[4:7]
	v_mfma_f32_16x16x32_bf16 v[0:3], v[206:209], v[238:241], v[0:3]
	v_mfma_f32_16x16x32_bf16 v[52:55], v[182:185], v[218:221], v[52:55]
	v_mfma_f32_16x16x32_bf16 v[48:51], v[210:213], v[218:221], v[48:51]
	v_mfma_f32_16x16x32_bf16 v[36:39], v[182:185], v[226:229], v[36:39]
	v_mfma_f32_16x16x32_bf16 v[32:35], v[210:213], v[226:229], v[32:35]
	v_mfma_f32_16x16x32_bf16 v[20:23], v[182:185], v[234:237], v[20:23]
	v_mfma_f32_16x16x32_bf16 v[16:19], v[210:213], v[234:237], v[16:19]
	v_mfma_f32_16x16x32_bf16 v[4:7], v[182:185], v[242:245], v[4:7]
	v_mfma_f32_16x16x32_bf16 v[0:3], v[210:213], v[242:245], v[0:3]
	s_barrier
	s_setprio 0
	s_add_i32 s59, s59, 2
	s_add_u32 s6, s6, 0x100
	s_addc_u32 s7, s7, 0
	s_add_u32 s57, s57, 0x100
	s_addc_u32 s58, s58, 0
	s_cmp_gt_u32 s59, 13
	s_cbranch_scc0 .LBB0_714
	s_and_b64 vcc, exec, s[46:47]
	s_cbranch_vccz .LBB0_717
	s_barrier
